# ml_local normalizer-state dot product: double-buffered LDS reads with counted waits and 4 partial accumulators instead of 32 exposed LDS round trips; three wait-state pads added
# speedup vs baseline: 1.0053x; 1.0053x over previous
; __device__ void filters_phase(unsigned char* lds, const Params& p) {
;     ...
;   for (int tile = blockIdx.x; tile < 576; tile += gridDim.x) {
;     const int l = tile / 288, pt = tile % 288;
;     const int posidx0 = pt * 8;
;     const int L = (posidx0 < 2048) ? 2048 : 256;
;     const int pos0 = (posidx0 < 2048) ? posidx0 : posidx0 - 2048;
;     const float* w1 = p.in[10] + l * 33 * 64;
;     const float* b1 = p.in[11] + l * 64;
;     const float* w2 = p.in[12] + l * 64 * 64;
;     const float* b2 = p.in[13] + l * 64;
;     const float* w3 = p.in[14] + l * 64 * 512;
;     const float* b3 = p.in[15] + l * 512;
;     const float* fq = p.in[16] + l * 128;
;     ...
;       for (int i = 0; i < 64; ++i) {
;         const float wv = w3[i * 512 + col];
; #pragma unroll
.LBB0_161:
	s_mul_hi_i32 s6, s26, 0x38e38e39
	s_lshr_b32 s7, s6, 31
	s_ashr_i32 s28, s6, 6
	s_add_i32 s28, s28, s7
	s_mul_i32 s6, s28, 0x120
	s_sub_i32 s6, s26, s6
	s_lshl_b32 s14, s6, 3
	s_add_i32 s7, s14, 0xfffff800
	s_cmpk_lt_i32 s6, 0x100
	s_movk_i32 s6, 0x800
	s_cselect_b32 s15, s6, 0x100
	s_cselect_b32 s27, s14, s7
	v_readlane_b32 s56, v252, 54
	v_readlane_b32 s57, v252, 55
	s_lshl_b32 s58, s28, 17
	s_add_u32 s56, s56, s58
	s_addc_u32 s57, s57, 0
	s_nop 0
	v_lshlrev_b32_e32 v246, 2, v195
	global_load_dword v154, v246, s[56:57]
	v_add_u32_e32 v246, 0x800, v246
	global_load_dword v155, v246, s[56:57]
	v_add_u32_e32 v246, 0x800, v246
	global_load_dword v156, v246, s[56:57]
	v_add_u32_e32 v246, 0x800, v246
	global_load_dword v157, v246, s[56:57]
	v_add_u32_e32 v246, 0x800, v246
	global_load_dword v158, v246, s[56:57]
	v_add_u32_e32 v246, 0x800, v246
	global_load_dword v159, v246, s[56:57]
	v_add_u32_e32 v246, 0x800, v246
	global_load_dword v160, v246, s[56:57]
	v_add_u32_e32 v246, 0x800, v246
	global_load_dword v161, v246, s[56:57]
	v_add_u32_e32 v246, 0x800, v246
	global_load_dword v162, v246, s[56:57]
	v_add_u32_e32 v246, 0x800, v246
	global_load_dword v163, v246, s[56:57]
	v_add_u32_e32 v246, 0x800, v246
	global_load_dword v164, v246, s[56:57]
	v_add_u32_e32 v246, 0x800, v246
	global_load_dword v165, v246, s[56:57]
	v_add_u32_e32 v246, 0x800, v246
	global_load_dword v166, v246, s[56:57]
	v_add_u32_e32 v246, 0x800, v246
	global_load_dword v167, v246, s[56:57]
	v_add_u32_e32 v246, 0x800, v246
	global_load_dword v168, v246, s[56:57]
	v_add_u32_e32 v246, 0x800, v246
	global_load_dword v169, v246, s[56:57]
	v_add_u32_e32 v246, 0x800, v246
	global_load_dword v170, v246, s[56:57]
	v_add_u32_e32 v246, 0x800, v246
	global_load_dword v171, v246, s[56:57]
	v_add_u32_e32 v246, 0x800, v246
	global_load_dword v172, v246, s[56:57]
	v_add_u32_e32 v246, 0x800, v246
	global_load_dword v173, v246, s[56:57]
	v_add_u32_e32 v246, 0x800, v246
	global_load_dword v174, v246, s[56:57]
	v_add_u32_e32 v246, 0x800, v246
	global_load_dword v175, v246, s[56:57]
	v_add_u32_e32 v246, 0x800, v246
	global_load_dword v176, v246, s[56:57]
	v_add_u32_e32 v246, 0x800, v246
	global_load_dword v177, v246, s[56:57]
	v_add_u32_e32 v246, 0x800, v246
	global_load_dword v178, v246, s[56:57]
	v_add_u32_e32 v246, 0x800, v246
	global_load_dword v179, v246, s[56:57]
	v_add_u32_e32 v246, 0x800, v246
	global_load_dword v180, v246, s[56:57]
	v_add_u32_e32 v246, 0x800, v246
	global_load_dword v181, v246, s[56:57]
	v_add_u32_e32 v246, 0x800, v246
	global_load_dword v182, v246, s[56:57]
	v_add_u32_e32 v246, 0x800, v246
	global_load_dword v183, v246, s[56:57]
	v_add_u32_e32 v246, 0x800, v246
	global_load_dword v184, v246, s[56:57]
	v_add_u32_e32 v246, 0x800, v246
	global_load_dword v185, v246, s[56:57]
	v_add_u32_e32 v246, 0x800, v246
	global_load_dword v200, v246, s[56:57]
	v_add_u32_e32 v246, 0x800, v246
	global_load_dword v201, v246, s[56:57]
	v_add_u32_e32 v246, 0x800, v246
	global_load_dword v202, v246, s[56:57]
	v_add_u32_e32 v246, 0x800, v246
	global_load_dword v203, v246, s[56:57]
	v_add_u32_e32 v246, 0x800, v246
	global_load_dword v204, v246, s[56:57]
	v_add_u32_e32 v246, 0x800, v246
	global_load_dword v205, v246, s[56:57]
	v_add_u32_e32 v246, 0x800, v246
	global_load_dword v206, v246, s[56:57]
	v_add_u32_e32 v246, 0x800, v246
	global_load_dword v207, v246, s[56:57]
	v_add_u32_e32 v246, 0x800, v246
	global_load_dword v208, v246, s[56:57]
	v_add_u32_e32 v246, 0x800, v246
	global_load_dword v209, v246, s[56:57]
	v_add_u32_e32 v246, 0x800, v246
	global_load_dword v210, v246, s[56:57]
	v_add_u32_e32 v246, 0x800, v246
	global_load_dword v211, v246, s[56:57]
	v_add_u32_e32 v246, 0x800, v246
	global_load_dword v212, v246, s[56:57]
	v_add_u32_e32 v246, 0x800, v246
	global_load_dword v213, v246, s[56:57]
	v_add_u32_e32 v246, 0x800, v246
	global_load_dword v214, v246, s[56:57]
	v_add_u32_e32 v246, 0x800, v246
	global_load_dword v215, v246, s[56:57]
	v_add_u32_e32 v246, 0x800, v246
	global_load_dword v216, v246, s[56:57]
	v_add_u32_e32 v246, 0x800, v246
	global_load_dword v217, v246, s[56:57]
	v_add_u32_e32 v246, 0x800, v246
	global_load_dword v218, v246, s[56:57]
	v_add_u32_e32 v246, 0x800, v246
	global_load_dword v219, v246, s[56:57]
	v_add_u32_e32 v246, 0x800, v246
	global_load_dword v230, v246, s[56:57]
	v_add_u32_e32 v246, 0x800, v246
	global_load_dword v231, v246, s[56:57]
	v_add_u32_e32 v246, 0x800, v246
	global_load_dword v232, v246, s[56:57]
	v_add_u32_e32 v246, 0x800, v246
	global_load_dword v233, v246, s[56:57]
	s_and_saveexec_b64 s[16:17], s[0:1]
	s_cbranch_execz .LBB0_178
; __device__ void filters_phase(unsigned char* lds, const Params& p) {
;     ...
;     if (tid < 8 * 33) {
;       const int pp = tid / 33, f = tid % 33;
;       const float pos = (float)(pos0 + pp);
;       float v;
;       if (f == 0) v = pos / (float)(L - 1);
;       else {
;         const int bi = (f - 1) & 15;
;         const float fr = 1e-4f + (float)bi * ((15.0f - 1e-4f) / 15.0f);
;         const float kk = (float)(2.0 * 3.14159265358979323846 / (double)L);
;         const float ang = (kk * fr) * pos;
;         v = (f <= 16) ? cosf(ang) : -sinf(ang);
;       }
;       feats[pp * 33 + f] = v;
	v_add_u32_e32 v19, s27, v1
	v_cvt_f32_i32_e32 v19, v19
	s_and_saveexec_b64 s[6:7], s[2:3]
	s_xor_b64 s[18:19], exec, s[6:7]
	s_cbranch_execz .LBB0_175
	s_mov_b32 s8, 0x54442d18
	v_cvt_f64_u32_e32 v[48:49], s15
	s_mov_b32 s9, 0x401921fb
	v_div_scale_f64 v[50:51], s[6:7], v[48:49], v[48:49], s[8:9]
	v_rcp_f64_e32 v[52:53], v[50:51]
	v_div_scale_f64 v[54:55], vcc, s[8:9], v[48:49], s[8:9]
	s_brev_b32 s6, 18
	v_fma_f64 v[56:57], -v[50:51], v[52:53], 1.0
	v_fmac_f64_e32 v[52:53], v[52:53], v[56:57]
	v_fma_f64 v[56:57], -v[50:51], v[52:53], 1.0
	v_fmac_f64_e32 v[52:53], v[52:53], v[56:57]
	v_mul_f64 v[56:57], v[54:55], v[52:53]
	v_fma_f64 v[50:51], -v[50:51], v[56:57], v[54:55]
	v_div_fmas_f64 v[50:51], v[50:51], v[52:53], v[56:57]
	v_div_fixup_f64 v[48:49], v[50:51], v[48:49], s[8:9]
	v_cvt_f32_f64_e32 v21, v[48:49]
	v_mul_f32_e32 v21, v5, v21
	v_mul_f32_e32 v19, v21, v19
	v_and_b32_e32 v21, 0x7fffffff, v19
	v_cmp_nlt_f32_e64 s[20:21], |v19|, s6
	s_and_saveexec_b64 s[6:7], s[4:5]
	s_xor_b64 s[22:23], exec, s[6:7]
	s_cbranch_execz .LBB0_169
	s_and_saveexec_b64 s[6:7], s[20:21]
	s_xor_b64 s[24:25], exec, s[6:7]
	s_cbranch_execz .LBB0_166
	v_lshrrev_b32_e32 v23, 23, v21
	v_add_u32_e32 v23, 0xffffff88, v23
	v_cmp_lt_u32_e32 vcc, 63, v23
	v_not_b32_e32 v25, 63
	v_not_b32_e32 v27, 31
	v_cndmask_b32_e32 v25, 0, v25, vcc
	v_add_u32_e32 v23, v25, v23
	v_cmp_lt_u32_e64 s[6:7], 31, v23
	s_mov_b32 s10, 0xfe5163ab
	s_nop 0
	v_cndmask_b32_e64 v25, 0, v27, s[6:7]
	v_add_u32_e32 v23, v25, v23
	v_cmp_lt_u32_e64 s[8:9], 31, v23
	s_nop 1
	v_cndmask_b32_e64 v25, 0, v27, s[8:9]
	v_add_u32_e32 v23, v25, v23
	v_and_b32_e32 v25, 0x7fffff, v21
	v_or_b32_e32 v25, 0x800000, v25
	v_mad_u64_u32 v[48:49], s[10:11], v25, s10, 0
	v_mov_b32_e32 v192, v49
	s_mov_b32 s10, 0x3c439041
	v_mad_u64_u32 v[50:51], s[10:11], v25, s10, v[192:193]
	v_mov_b32_e32 v192, v51
	s_mov_b32 s10, 0xdb629599
	v_mad_u64_u32 v[52:53], s[10:11], v25, s10, v[192:193]
	v_mov_b32_e32 v192, v53
	s_mov_b32 s10, 0xf534ddc0
	v_mad_u64_u32 v[54:55], s[10:11], v25, s10, v[192:193]
	v_mov_b32_e32 v192, v55
	s_mov_b32 s10, 0xfc2757d1
	v_mad_u64_u32 v[56:57], s[10:11], v25, s10, v[192:193]
	v_mov_b32_e32 v192, v57
	s_mov_b32 s10, 0x4e441529
	v_mad_u64_u32 v[58:59], s[10:11], v25, s10, v[192:193]
	v_mov_b32_e32 v192, v59
	s_mov_b32 s10, 0xa2f9836e
	v_mad_u64_u32 v[60:61], s[10:11], v25, s10, v[192:193]
	v_cndmask_b32_e32 v27, v58, v54, vcc
	v_cndmask_b32_e32 v25, v60, v56, vcc
	v_cndmask_b32_e32 v31, v61, v58, vcc
	v_cndmask_b32_e64 v29, v25, v27, s[6:7]
	v_cndmask_b32_e64 v25, v31, v25, s[6:7]
	v_cndmask_b32_e32 v31, v56, v52, vcc
	v_cndmask_b32_e64 v27, v27, v31, s[6:7]
	v_cndmask_b32_e64 v25, v25, v29, s[8:9]
	v_cndmask_b32_e64 v29, v29, v27, s[8:9]
	v_sub_u32_e32 v33, 32, v23
	v_alignbit_b32 v35, v25, v29, v33
	v_cmp_eq_u32_e64 s[10:11], 0, v23
	v_cndmask_b32_e32 v48, v52, v48, vcc
	s_nop 0
	v_cndmask_b32_e64 v23, v35, v25, s[10:11]
	v_cndmask_b32_e32 v25, v54, v50, vcc
	v_cndmask_b32_e64 v31, v31, v25, s[6:7]
	v_cndmask_b32_e64 v27, v27, v31, s[8:9]
	v_alignbit_b32 v35, v29, v27, v33
	v_cndmask_b32_e64 v29, v35, v29, s[10:11]
	v_bfe_u32 v49, v23, 29, 1
	v_cndmask_b32_e64 v25, v25, v48, s[6:7]
	v_alignbit_b32 v35, v23, v29, 30
	v_sub_u32_e32 v50, 0, v49
	v_cndmask_b32_e64 v25, v31, v25, s[8:9]
	v_xor_b32_e32 v35, v35, v50
	v_alignbit_b32 v31, v27, v25, v33
	v_cndmask_b32_e64 v27, v31, v27, s[10:11]
	v_ffbh_u32_e32 v31, v35
	v_alignbit_b32 v29, v29, v27, 30
	v_min_u32_e32 v31, 32, v31
	v_alignbit_b32 v25, v27, v25, 30
	v_xor_b32_e32 v29, v29, v50
	v_sub_u32_e32 v33, 31, v31
	v_xor_b32_e32 v25, v25, v50
	v_alignbit_b32 v35, v35, v29, v33
	v_alignbit_b32 v25, v29, v25, v33
	v_alignbit_b32 v27, v35, v25, 9
	v_ffbh_u32_e32 v29, v27
	v_min_u32_e32 v29, 32, v29
	v_lshrrev_b32_e32 v37, 29, v23
	v_not_b32_e32 v33, v29
	v_alignbit_b32 v25, v27, v25, v33
	v_lshlrev_b32_e32 v27, 31, v37
	v_or_b32_e32 v33, 0x33000000, v27
	v_add_lshl_u32 v29, v29, v31, 23
	v_lshrrev_b32_e32 v25, 9, v25
	v_sub_u32_e32 v29, v33, v29
	v_or_b32_e32 v27, 0.5, v27
	v_lshlrev_b32_e32 v31, 23, v31
	v_or_b32_e32 v25, v29, v25
	v_lshrrev_b32_e32 v29, 9, v35
	v_sub_u32_e32 v27, v27, v31
	v_or_b32_e32 v27, v29, v27
	v_mul_f32_e32 v29, 0x3fc90fda, v27
	s_mov_b32 s6, 0x3fc90fda
	v_fma_f32 v31, v27, s6, -v29
	v_fmac_f32_e32 v31, 0x33a22168, v27
	v_fmac_f32_e32 v31, 0x3fc90fda, v25
	v_lshrrev_b32_e32 v23, 30, v23
	v_add_f32_e32 v25, v29, v31
	v_add_u32_e32 v23, v49, v23

; __device__ __forceinline__ bf16_t f2bf(float f) { return (bf16_t)(pack2(f, 0.f) & 0xffffu); }
; __device__ __forceinline__ float siluf(float x) { return x * frcp(1.f + fexp(-x)); }
; __device__ __forceinline__ void ml_conv8_comp(const uint4* u, const float* wc, int ccol, int L, int pos, float* o) {
; #pragma unroll
;   for (int e = 0; e < 8; ++e) o[e] = 0.f;
; #pragma unroll
;   for (int j = 0; j < 4; ++j) {
;     const int pp = pos + j - 1;
;     const float mk = (pp >= 0 && pp < L) ? 1.f : 0.f;
;     float f[8];
;     unpack8(u[j], f);
;     const float4 w0 = *(const float4*)(wc + j * 1024 + ccol);
;     const float4 w1 = *(const float4*)(wc + j * 1024 + ccol + 4);
;     o[0] += f[0] * (w0.x * mk); o[1] += f[1] * (w0.y * mk); o[2] += f[2] * (w0.z * mk); o[3] += f[3] * (w0.w * mk);
;     o[4] += f[4] * (w1.x * mk); o[5] += f[5] * (w1.y * mk); o[6] += f[6] * (w1.z * mk); o[7] += f[7] * (w1.w * mk);
;   }
; #pragma unroll
;   for (int e = 0; e < 8; ++e) o[e] = siluf(o[e]);
; __device__ void ml_local_tile(unsigned char* lds, const Params& p, int l, int b, int h, int n) {
;     ...
;   {
;     const int s = tid & 127, ec0 = tid >> 7;
;     const float wf = vec[6 * 128 + s], wb = vec[7 * 128 + s];
;     const float* wc = p.in[18] + (size_t)l * 4 * 1024;
; #pragma unroll
;     for (int i = 0; i < 4; ++i) {
;       const int ec = ec0 + 4 * i;
;       float k8[8];
;       ml_conv8_comp(ku[i], wc, 512 + h * 128 + ec * 8, L, p0 + s, k8);
;       float v8[8];
;       unpack8(vu[i], v8);
; #pragma unroll
;       for (int e = 0; e < 8; ++e) {
;         KT[(ec * 8 + e) * 136 + s] = f2bf(k8[e] * 0.08838834764831845f);
;         VF[(ec * 8 + e) * 136 + s] = f2bf(v8[e] * wf);
;         VB[(ec * 8 + e) * 136 + s] = f2bf(v8[e] * wb);
;       }
;     }
;   }
.LBB0_345:
	s_or_b64 exec, exec, s[8:9]
	s_movk_i32 s6, 0x88
	v_cmp_ge_i32_e32 vcc, s26, v92
	v_mul_lo_u32 v96, v82, s6
	s_add_i32 s6, 0, 0x19800
	s_and_b64 s[0:1], s[0:1], vcc
	v_cmp_gt_u32_e32 vcc, s26, v92
	s_waitcnt vmcnt(21)
	v_lshl_add_u32 v80, v86, 2, s6
	v_lshl_add_u64 v[84:85], v[84:85], 2, s[18:19]
	v_cndmask_b32_e64 v94, 0, 1.0, vcc
	v_cmp_ge_i32_e32 vcc, s26, v93
	s_waitcnt lgkmcnt(0)
	s_barrier
	ds_read2st64_b32 v[80:81], v80 offset0:12 offset1:14
	s_bitset1_b32 s96, 9
	v_ashrrev_i32_e32 v89, 6, v88
	v_and_b32_e32 v90, 15, v88
	v_bfe_u32 v91, v88, 4, 2
	v_lshlrev_b32_e32 v192, 3, v91
	v_readlane_b32 s0, v253, 38
	s_mov_b64 s[2:3], 0x1000
	v_lshl_add_u64 v[178:179], v[84:85], 0, s[2:3]
	s_mov_b64 s[2:3], 0x2000
	v_lshl_add_u64 v[180:181], v[84:85], 0, s[2:3]
	s_mov_b64 s[2:3], 0x3000
	v_lshl_add_u64 v[182:183], v[84:85], 0, s[2:3]
	global_load_dwordx4 v[114:117], v[84:85], off offset:2048
	global_load_dwordx4 v[118:121], v[84:85], off offset:2064
	global_load_dwordx4 v[122:125], v[178:179], off offset:2048
	global_load_dwordx4 v[126:129], v[178:179], off offset:2064
	global_load_dwordx4 v[130:133], v[180:181], off offset:2048
	global_load_dwordx4 v[134:137], v[180:181], off offset:2064
	global_load_dwordx4 v[138:141], v[182:183], off offset:2048
	global_load_dwordx4 v[142:145], v[182:183], off offset:2064
	global_load_dwordx4 v[146:149], v[84:85], off offset:2176
	global_load_dwordx4 v[150:153], v[84:85], off offset:2192
	global_load_dwordx4 v[154:157], v[178:179], off offset:2176
	global_load_dwordx4 v[158:161], v[178:179], off offset:2192
	global_load_dwordx4 v[162:165], v[180:181], off offset:2176
	global_load_dwordx4 v[166:169], v[180:181], off offset:2192
	global_load_dwordx4 v[170:173], v[182:183], off offset:2176
	global_load_dwordx4 v[174:177], v[182:183], off offset:2192
	v_add_u32_e32 v93, 1, v92
	v_add_u32_e32 v97, 2, v92
	v_cmp_lt_i32_e64 s[4:5], 0, v92
	v_cmp_gt_i32_e64 s[6:7], s26, v93
	v_cmp_gt_i32_e32 vcc, s26, v97
	s_movk_i32 s1, 0x440
	v_mul_lo_u32 v106, v87, s1
	v_mov_b32_e32 v94, 1.0
	v_cndmask_b32_e64 v95, 0, 1.0, s[4:5]
	v_cndmask_b32_e64 v93, 0, 1.0, s[6:7]
	v_cndmask_b32_e64 v92, 0, 1.0, vcc
	v_add_lshl_u32 v106, v106, v86, 1
	v_add_u32_e32 v107, s0, v106
	s_waitcnt vmcnt(8) lgkmcnt(0)
	v_mul_f32_e32 v104, v95, v114
	v_lshlrev_b32_e32 v105, 16, v76
	v_fma_f32 v96, v104, v105, 0
	v_mul_f32_e32 v104, v95, v115
	v_and_b32_e32 v105, 0xffff0000, v76
	v_fma_f32 v97, v104, v105, 0
	v_mul_f32_e32 v104, v95, v116
	v_lshlrev_b32_e32 v105, 16, v77
	v_fma_f32 v98, v104, v105, 0
	v_mul_f32_e32 v104, v95, v117
	v_and_b32_e32 v105, 0xffff0000, v77
	v_fma_f32 v99, v104, v105, 0
	v_mul_f32_e32 v104, v95, v118
	v_lshlrev_b32_e32 v105, 16, v78
	v_fma_f32 v100, v104, v105, 0
	v_mul_f32_e32 v104, v95, v119
	v_and_b32_e32 v105, 0xffff0000, v78
	v_fma_f32 v101, v104, v105, 0
	v_mul_f32_e32 v104, v95, v120
	v_lshlrev_b32_e32 v105, 16, v79
	v_fma_f32 v102, v104, v105, 0
	v_mul_f32_e32 v104, v95, v121
	v_and_b32_e32 v105, 0xffff0000, v79
	v_fma_f32 v103, v104, v105, 0
	v_mul_f32_e32 v104, v94, v122
	v_lshlrev_b32_e32 v105, 16, v72
	v_fmac_f32_e32 v96, v104, v105
	v_mul_f32_e32 v104, v94, v123
	v_and_b32_e32 v105, 0xffff0000, v72
	v_fmac_f32_e32 v97, v104, v105
	v_mul_f32_e32 v104, v94, v124
	v_lshlrev_b32_e32 v105, 16, v73
	v_fmac_f32_e32 v98, v104, v105
	v_mul_f32_e32 v104, v94, v125
	v_and_b32_e32 v105, 0xffff0000, v73
	v_fmac_f32_e32 v99, v104, v105
	v_mul_f32_e32 v104, v94, v126
	v_lshlrev_b32_e32 v105, 16, v74
	v_fmac_f32_e32 v100, v104, v105
	v_mul_f32_e32 v104, v94, v127
	v_and_b32_e32 v105, 0xffff0000, v74
	v_fmac_f32_e32 v101, v104, v105
	v_mul_f32_e32 v104, v94, v128
	v_lshlrev_b32_e32 v105, 16, v75
	v_fmac_f32_e32 v102, v104, v105
	v_mul_f32_e32 v104, v94, v129
	v_and_b32_e32 v105, 0xffff0000, v75
	v_fmac_f32_e32 v103, v104, v105
	v_mul_f32_e32 v104, v93, v130
	v_lshlrev_b32_e32 v105, 16, v68
	v_fmac_f32_e32 v96, v104, v105
	v_mul_f32_e32 v104, v93, v131
	v_and_b32_e32 v105, 0xffff0000, v68
	v_fmac_f32_e32 v97, v104, v105
	v_mul_f32_e32 v104, v93, v132
	v_lshlrev_b32_e32 v105, 16, v69
	v_fmac_f32_e32 v98, v104, v105
	v_mul_f32_e32 v104, v93, v133
	v_and_b32_e32 v105, 0xffff0000, v69
	v_fmac_f32_e32 v99, v104, v105
	v_mul_f32_e32 v104, v93, v134
	v_lshlrev_b32_e32 v105, 16, v70
	v_fmac_f32_e32 v100, v104, v105
	v_mul_f32_e32 v104, v93, v135
	v_and_b32_e32 v105, 0xffff0000, v70
	v_fmac_f32_e32 v101, v104, v105
	v_mul_f32_e32 v104, v93, v136
	v_lshlrev_b32_e32 v105, 16, v71
	v_fmac_f32_e32 v102, v104, v105
	v_mul_f32_e32 v104, v93, v137
	v_and_b32_e32 v105, 0xffff0000, v71
	v_fmac_f32_e32 v103, v104, v105
	v_mul_f32_e32 v104, v92, v138
	v_lshlrev_b32_e32 v105, 16, v64
	v_fmac_f32_e32 v96, v104, v105
	v_mul_f32_e32 v104, v92, v139
	v_and_b32_e32 v105, 0xffff0000, v64
	v_fmac_f32_e32 v97, v104, v105
	v_mul_f32_e32 v104, v92, v140
	v_lshlrev_b32_e32 v105, 16, v65
	v_fmac_f32_e32 v98, v104, v105
	v_mul_f32_e32 v104, v92, v141
	v_and_b32_e32 v105, 0xffff0000, v65
	v_fmac_f32_e32 v99, v104, v105
	v_mul_f32_e32 v104, v92, v142
	v_lshlrev_b32_e32 v105, 16, v66
	v_fmac_f32_e32 v100, v104, v105
	v_mul_f32_e32 v104, v92, v143
	v_and_b32_e32 v105, 0xffff0000, v66
	v_fmac_f32_e32 v101, v104, v105
	v_mul_f32_e32 v104, v92, v144
	v_lshlrev_b32_e32 v105, 16, v67
	v_fmac_f32_e32 v102, v104, v105
	v_mul_f32_e32 v104, v92, v145
	v_and_b32_e32 v105, 0xffff0000, v67
	v_fmac_f32_e32 v103, v104, v105
	v_mul_f32_e32 v184, 0xbfb8aa3b, v96
	v_mul_f32_e32 v185, 0xbfb8aa3b, v97
	v_mul_f32_e32 v186, 0xbfb8aa3b, v98
	v_mul_f32_e32 v187, 0xbfb8aa3b, v99
	v_mul_f32_e32 v188, 0xbfb8aa3b, v100
	v_mul_f32_e32 v189, 0xbfb8aa3b, v101
; __device__ __forceinline__ bf16_t f2bf(float f) { return (bf16_t)(pack2(f, 0.f) & 0xffffu); }
; __device__ __forceinline__ float siluf(float x) { return x * frcp(1.f + fexp(-x)); }
; __device__ __forceinline__ void ml_conv8_comp(const uint4* u, const float* wc, int ccol, int L, int pos, float* o) {
;     ...
;   for (int e = 0; e < 8; ++e) o[e] = siluf(o[e]);
; __device__ void ml_local_tile(unsigned char* lds, const Params& p, int l, int b, int h, int n) {
;     ...
; #pragma unroll
;       for (int e = 0; e < 8; ++e) {
;         KT[(ec * 8 + e) * 136 + s] = f2bf(k8[e] * 0.08838834764831845f);
;         VF[(ec * 8 + e) * 136 + s] = f2bf(v8[e] * wf);
;         VB[(ec * 8 + e) * 136 + s] = f2bf(v8[e] * wb);
;       }
	v_mul_f32_e32 v190, 0xbfb8aa3b, v102
	v_mul_f32_e32 v191, 0xbfb8aa3b, v103
	v_exp_f32_e32 v184, v184
	v_exp_f32_e32 v185, v185
	v_exp_f32_e32 v186, v186
	v_exp_f32_e32 v187, v187
	v_exp_f32_e32 v188, v188
	v_exp_f32_e32 v189, v189
	v_exp_f32_e32 v190, v190
	v_exp_f32_e32 v191, v191
	v_add_f32_e32 v184, 1.0, v184
	v_add_f32_e32 v185, 1.0, v185
	v_add_f32_e32 v186, 1.0, v186
	v_add_f32_e32 v187, 1.0, v187
	v_add_f32_e32 v188, 1.0, v188
	v_add_f32_e32 v189, 1.0, v189
	v_add_f32_e32 v190, 1.0, v190
	v_add_f32_e32 v191, 1.0, v191
	v_rcp_f32_e32 v184, v184
	v_rcp_f32_e32 v185, v185
	v_rcp_f32_e32 v186, v186
	v_rcp_f32_e32 v187, v187
	v_rcp_f32_e32 v188, v188
	v_rcp_f32_e32 v189, v189
	v_rcp_f32_e32 v190, v190
	v_rcp_f32_e32 v191, v191
	s_nop 0
	v_mul_f32_e32 v96, v96, v184
	v_mul_f32_e32 v97, v97, v185
	v_mul_f32_e32 v98, v98, v186
	v_mul_f32_e32 v99, v99, v187
	v_mul_f32_e32 v100, v100, v188
	v_mul_f32_e32 v101, v101, v189
	v_mul_f32_e32 v102, v102, v190
	v_mul_f32_e32 v103, v103, v191
	v_mul_f32_e32 v96, 0x3db504f3, v96
	v_mul_f32_e32 v97, 0x3db504f3, v97
	v_mul_f32_e32 v98, 0x3db504f3, v98
	v_mul_f32_e32 v99, 0x3db504f3, v99
	v_mul_f32_e32 v100, 0x3db504f3, v100
	v_mul_f32_e32 v101, 0x3db504f3, v101
	v_mul_f32_e32 v102, 0x3db504f3, v102
	v_mul_f32_e32 v103, 0x3db504f3, v103
	v_cvt_pk_bf16_f32 v184, v96, v96
	v_cvt_pk_bf16_f32 v185, v97, v97
	v_cvt_pk_bf16_f32 v186, v98, v98
	v_cvt_pk_bf16_f32 v187, v99, v99
	v_cvt_pk_bf16_f32 v188, v100, v100
	v_cvt_pk_bf16_f32 v189, v101, v101
	v_cvt_pk_bf16_f32 v190, v102, v102
	v_cvt_pk_bf16_f32 v191, v103, v103
	ds_write_b16 v106, v184
	ds_write_b16 v106, v185 offset:272
	ds_write_b16 v106, v186 offset:544
	ds_write_b16 v106, v187 offset:816
	ds_write_b16 v106, v188 offset:1088
	ds_write_b16 v106, v189 offset:1360
	ds_write_b16 v106, v190 offset:1632
	ds_write_b16 v106, v191 offset:1904
	v_lshlrev_b32_e32 v105, 16, v60
	v_mul_f32_e32 v104, v80, v105
	v_mul_f32_e32 v112, v81, v105
	v_cvt_pk_bf16_f32 v104, v104, v104
	v_cvt_pk_bf16_f32 v112, v112, v112
	ds_write_b16 v106, v104 offset:34816
	ds_write_b16 v107, v112
	v_and_b32_e32 v105, 0xffff0000, v60
	v_mul_f32_e32 v104, v80, v105
	v_mul_f32_e32 v112, v81, v105
	v_cvt_pk_bf16_f32 v104, v104, v104
	v_cvt_pk_bf16_f32 v112, v112, v112
	ds_write_b16 v106, v104 offset:35088
	ds_write_b16 v107, v112 offset:272
	v_lshlrev_b32_e32 v105, 16, v61
	v_mul_f32_e32 v104, v80, v105
	v_mul_f32_e32 v112, v81, v105
	v_cvt_pk_bf16_f32 v104, v104, v104
	v_cvt_pk_bf16_f32 v112, v112, v112
	ds_write_b16 v106, v104 offset:35360
	ds_write_b16 v107, v112 offset:544
	v_and_b32_e32 v105, 0xffff0000, v61
	v_mul_f32_e32 v104, v80, v105
	v_mul_f32_e32 v112, v81, v105
	v_cvt_pk_bf16_f32 v104, v104, v104
	v_cvt_pk_bf16_f32 v112, v112, v112
	ds_write_b16 v106, v104 offset:35632
	ds_write_b16 v107, v112 offset:816
	v_lshlrev_b32_e32 v105, 16, v62
	v_mul_f32_e32 v104, v80, v105
	v_mul_f32_e32 v112, v81, v105
	v_cvt_pk_bf16_f32 v104, v104, v104
	v_cvt_pk_bf16_f32 v112, v112, v112
	ds_write_b16 v106, v104 offset:35904
	ds_write_b16 v107, v112 offset:1088
	v_and_b32_e32 v105, 0xffff0000, v62
	v_mul_f32_e32 v104, v80, v105
	v_mul_f32_e32 v112, v81, v105
	v_cvt_pk_bf16_f32 v104, v104, v104
	v_cvt_pk_bf16_f32 v112, v112, v112
	ds_write_b16 v106, v104 offset:36176
	ds_write_b16 v107, v112 offset:1360
	v_lshlrev_b32_e32 v105, 16, v63
	v_mul_f32_e32 v104, v80, v105
	v_mul_f32_e32 v112, v81, v105
	v_cvt_pk_bf16_f32 v104, v104, v104
	v_cvt_pk_bf16_f32 v112, v112, v112
	ds_write_b16 v106, v104 offset:36448
	ds_write_b16 v107, v112 offset:1632
	v_and_b32_e32 v105, 0xffff0000, v63
	v_mul_f32_e32 v104, v80, v105
	v_mul_f32_e32 v112, v81, v105
	v_cvt_pk_bf16_f32 v104, v104, v104
	v_cvt_pk_bf16_f32 v112, v112, v112
	ds_write_b16 v106, v104 offset:36720
	ds_write_b16 v107, v112 offset:1904
	global_load_dwordx4 v[114:117], v[84:85], off offset:2304
	global_load_dwordx4 v[118:121], v[84:85], off offset:2320
	global_load_dwordx4 v[122:125], v[178:179], off offset:2304
	global_load_dwordx4 v[126:129], v[178:179], off offset:2320
	global_load_dwordx4 v[130:133], v[180:181], off offset:2304
	global_load_dwordx4 v[134:137], v[180:181], off offset:2320
	global_load_dwordx4 v[138:141], v[182:183], off offset:2304
	global_load_dwordx4 v[142:145], v[182:183], off offset:2320
	s_waitcnt vmcnt(8)
; __device__ __forceinline__ bf16_t f2bf(float f) { return (bf16_t)(pack2(f, 0.f) & 0xffffu); }
; __device__ __forceinline__ float siluf(float x) { return x * frcp(1.f + fexp(-x)); }
; __device__ __forceinline__ void ml_conv8_comp(const uint4* u, const float* wc, int ccol, int L, int pos, float* o) {
; #pragma unroll
;   for (int e = 0; e < 8; ++e) o[e] = 0.f;
; #pragma unroll
;   for (int j = 0; j < 4; ++j) {
;     const int pp = pos + j - 1;
;     const float mk = (pp >= 0 && pp < L) ? 1.f : 0.f;
;     float f[8];
;     unpack8(u[j], f);
;     const float4 w0 = *(const float4*)(wc + j * 1024 + ccol);
;     const float4 w1 = *(const float4*)(wc + j * 1024 + ccol + 4);
;     o[0] += f[0] * (w0.x * mk); o[1] += f[1] * (w0.y * mk); o[2] += f[2] * (w0.z * mk); o[3] += f[3] * (w0.w * mk);
;     o[4] += f[4] * (w1.x * mk); o[5] += f[5] * (w1.y * mk); o[6] += f[6] * (w1.z * mk); o[7] += f[7] * (w1.w * mk);
;   }
; #pragma unroll
;   for (int e = 0; e < 8; ++e) o[e] = siluf(o[e]);
; __device__ void ml_local_tile(unsigned char* lds, const Params& p, int l, int b, int h, int n) {
;     ...
;     for (int i = 0; i < 4; ++i) {
;       const int ec = ec0 + 4 * i;
;       float k8[8];
;       ml_conv8_comp(ku[i], wc, 512 + h * 128 + ec * 8, L, p0 + s, k8);
;       float v8[8];
;       unpack8(vu[i], v8);
; #pragma unroll
;       for (int e = 0; e < 8; ++e) {
;         KT[(ec * 8 + e) * 136 + s] = f2bf(k8[e] * 0.08838834764831845f);
;         VF[(ec * 8 + e) * 136 + s] = f2bf(v8[e] * wf);
;         VB[(ec * 8 + e) * 136 + s] = f2bf(v8[e] * wb);
;       }
	v_mul_f32_e32 v104, v95, v146
	v_lshlrev_b32_e32 v105, 16, v56
	v_fma_f32 v96, v104, v105, 0
	v_mul_f32_e32 v104, v95, v147
	v_and_b32_e32 v105, 0xffff0000, v56
	v_fma_f32 v97, v104, v105, 0
	v_mul_f32_e32 v104, v95, v148
	v_lshlrev_b32_e32 v105, 16, v57
	v_fma_f32 v98, v104, v105, 0
	v_mul_f32_e32 v104, v95, v149
	v_and_b32_e32 v105, 0xffff0000, v57
	v_fma_f32 v99, v104, v105, 0
	v_mul_f32_e32 v104, v95, v150
	v_lshlrev_b32_e32 v105, 16, v58
	v_fma_f32 v100, v104, v105, 0
	v_mul_f32_e32 v104, v95, v151
	v_and_b32_e32 v105, 0xffff0000, v58
	v_fma_f32 v101, v104, v105, 0
	v_mul_f32_e32 v104, v95, v152
	v_lshlrev_b32_e32 v105, 16, v59
	v_fma_f32 v102, v104, v105, 0
	v_mul_f32_e32 v104, v95, v153
	v_and_b32_e32 v105, 0xffff0000, v59
	v_fma_f32 v103, v104, v105, 0
	v_mul_f32_e32 v104, v94, v154
	v_lshlrev_b32_e32 v105, 16, v52
	v_fmac_f32_e32 v96, v104, v105
	v_mul_f32_e32 v104, v94, v155
	v_and_b32_e32 v105, 0xffff0000, v52
	v_fmac_f32_e32 v97, v104, v105
	v_mul_f32_e32 v104, v94, v156
	v_lshlrev_b32_e32 v105, 16, v53
	v_fmac_f32_e32 v98, v104, v105
	v_mul_f32_e32 v104, v94, v157
	v_and_b32_e32 v105, 0xffff0000, v53
	v_fmac_f32_e32 v99, v104, v105
	v_mul_f32_e32 v104, v94, v158
	v_lshlrev_b32_e32 v105, 16, v54
	v_fmac_f32_e32 v100, v104, v105
	v_mul_f32_e32 v104, v94, v159
	v_and_b32_e32 v105, 0xffff0000, v54
	v_fmac_f32_e32 v101, v104, v105
	v_mul_f32_e32 v104, v94, v160
	v_lshlrev_b32_e32 v105, 16, v55
	v_fmac_f32_e32 v102, v104, v105
	v_mul_f32_e32 v104, v94, v161
	v_and_b32_e32 v105, 0xffff0000, v55
	v_fmac_f32_e32 v103, v104, v105
	v_mul_f32_e32 v104, v93, v162
	v_lshlrev_b32_e32 v105, 16, v48
	v_fmac_f32_e32 v96, v104, v105
	v_mul_f32_e32 v104, v93, v163
	v_and_b32_e32 v105, 0xffff0000, v48
	v_fmac_f32_e32 v97, v104, v105
	v_mul_f32_e32 v104, v93, v164
	v_lshlrev_b32_e32 v105, 16, v49
	v_fmac_f32_e32 v98, v104, v105
	v_mul_f32_e32 v104, v93, v165
	v_and_b32_e32 v105, 0xffff0000, v49
	v_fmac_f32_e32 v99, v104, v105
	v_mul_f32_e32 v104, v93, v166
	v_lshlrev_b32_e32 v105, 16, v50
	v_fmac_f32_e32 v100, v104, v105
	v_mul_f32_e32 v104, v93, v167
	v_and_b32_e32 v105, 0xffff0000, v50
	v_fmac_f32_e32 v101, v104, v105
	v_mul_f32_e32 v104, v93, v168
	v_lshlrev_b32_e32 v105, 16, v51
	v_fmac_f32_e32 v102, v104, v105
	v_mul_f32_e32 v104, v93, v169
	v_and_b32_e32 v105, 0xffff0000, v51
	v_fmac_f32_e32 v103, v104, v105
	v_mul_f32_e32 v104, v92, v170
	v_lshlrev_b32_e32 v105, 16, v44
	v_fmac_f32_e32 v96, v104, v105
	v_mul_f32_e32 v104, v92, v171
	v_and_b32_e32 v105, 0xffff0000, v44
	v_fmac_f32_e32 v97, v104, v105
	v_mul_f32_e32 v104, v92, v172
	v_lshlrev_b32_e32 v105, 16, v45
	v_fmac_f32_e32 v98, v104, v105
	v_mul_f32_e32 v104, v92, v173
	v_and_b32_e32 v105, 0xffff0000, v45
	v_fmac_f32_e32 v99, v104, v105
	v_mul_f32_e32 v104, v92, v174
	v_lshlrev_b32_e32 v105, 16, v46
	v_fmac_f32_e32 v100, v104, v105
	v_mul_f32_e32 v104, v92, v175
	v_and_b32_e32 v105, 0xffff0000, v46
	v_fmac_f32_e32 v101, v104, v105
	v_mul_f32_e32 v104, v92, v176
	v_lshlrev_b32_e32 v105, 16, v47
	v_fmac_f32_e32 v102, v104, v105
	v_mul_f32_e32 v104, v92, v177
	v_and_b32_e32 v105, 0xffff0000, v47
	v_fmac_f32_e32 v103, v104, v105
	v_mul_f32_e32 v184, 0xbfb8aa3b, v96
	v_mul_f32_e32 v185, 0xbfb8aa3b, v97
	v_mul_f32_e32 v186, 0xbfb8aa3b, v98
	v_mul_f32_e32 v187, 0xbfb8aa3b, v99
	v_mul_f32_e32 v188, 0xbfb8aa3b, v100
	v_mul_f32_e32 v189, 0xbfb8aa3b, v101
	v_mul_f32_e32 v190, 0xbfb8aa3b, v102
	v_mul_f32_e32 v191, 0xbfb8aa3b, v103
	v_exp_f32_e32 v184, v184
	v_exp_f32_e32 v185, v185
	v_exp_f32_e32 v186, v186
	v_exp_f32_e32 v187, v187
	v_exp_f32_e32 v188, v188
	v_exp_f32_e32 v189, v189
	v_exp_f32_e32 v190, v190
	v_exp_f32_e32 v191, v191
	v_add_f32_e32 v184, 1.0, v184
	v_add_f32_e32 v185, 1.0, v185
	v_add_f32_e32 v186, 1.0, v186
	v_add_f32_e32 v187, 1.0, v187
	v_add_f32_e32 v188, 1.0, v188
	v_add_f32_e32 v189, 1.0, v189
	v_add_f32_e32 v190, 1.0, v190
	v_add_f32_e32 v191, 1.0, v191
	v_rcp_f32_e32 v184, v184
	v_rcp_f32_e32 v185, v185
	v_rcp_f32_e32 v186, v186
	v_rcp_f32_e32 v187, v187
	v_rcp_f32_e32 v188, v188
	v_rcp_f32_e32 v189, v189
	v_rcp_f32_e32 v190, v190
	v_rcp_f32_e32 v191, v191
	s_nop 0
	v_mul_f32_e32 v96, v96, v184
	v_mul_f32_e32 v97, v97, v185
	v_mul_f32_e32 v98, v98, v186
	v_mul_f32_e32 v99, v99, v187
	v_mul_f32_e32 v100, v100, v188
	v_mul_f32_e32 v101, v101, v189
	v_mul_f32_e32 v102, v102, v190
	v_mul_f32_e32 v103, v103, v191
	v_mul_f32_e32 v96, 0x3db504f3, v96
	v_mul_f32_e32 v97, 0x3db504f3, v97
	v_mul_f32_e32 v98, 0x3db504f3, v98
	v_mul_f32_e32 v99, 0x3db504f3, v99
	v_mul_f32_e32 v100, 0x3db504f3, v100
	v_mul_f32_e32 v101, 0x3db504f3, v101
	v_mul_f32_e32 v102, 0x3db504f3, v102
	v_mul_f32_e32 v103, 0x3db504f3, v103
	v_cvt_pk_bf16_f32 v184, v96, v96
	v_cvt_pk_bf16_f32 v185, v97, v97
	v_cvt_pk_bf16_f32 v186, v98, v98
	v_cvt_pk_bf16_f32 v187, v99, v99
	v_cvt_pk_bf16_f32 v188, v100, v100
	v_cvt_pk_bf16_f32 v189, v101, v101
	v_cvt_pk_bf16_f32 v190, v102, v102
	v_cvt_pk_bf16_f32 v191, v103, v103
	ds_write_b16 v106, v184 offset:8704
	ds_write_b16 v106, v185 offset:8976
	ds_write_b16 v106, v186 offset:9248
	ds_write_b16 v106, v187 offset:9520
	ds_write_b16 v106, v188 offset:9792
	ds_write_b16 v106, v189 offset:10064
	ds_write_b16 v106, v190 offset:10336
	ds_write_b16 v106, v191 offset:10608
	v_lshlrev_b32_e32 v105, 16, v40
	v_mul_f32_e32 v104, v80, v105
	v_mul_f32_e32 v112, v81, v105
	v_cvt_pk_bf16_f32 v104, v104, v104
	v_cvt_pk_bf16_f32 v112, v112, v112
	ds_write_b16 v106, v104 offset:43520
	ds_write_b16 v107, v112 offset:8704
	v_and_b32_e32 v105, 0xffff0000, v40
	v_mul_f32_e32 v104, v80, v105
	v_mul_f32_e32 v112, v81, v105
	v_cvt_pk_bf16_f32 v104, v104, v104
	v_cvt_pk_bf16_f32 v112, v112, v112
; __device__ __forceinline__ bf16_t f2bf(float f) { return (bf16_t)(pack2(f, 0.f) & 0xffffu); }
; __device__ __forceinline__ float siluf(float x) { return x * frcp(1.f + fexp(-x)); }
; __device__ __forceinline__ void ml_conv8_comp(const uint4* u, const float* wc, int ccol, int L, int pos, float* o) {
; #pragma unroll
;   for (int e = 0; e < 8; ++e) o[e] = 0.f;
; #pragma unroll
;   for (int j = 0; j < 4; ++j) {
;     const int pp = pos + j - 1;
;     const float mk = (pp >= 0 && pp < L) ? 1.f : 0.f;
;     float f[8];
;     unpack8(u[j], f);
;     const float4 w0 = *(const float4*)(wc + j * 1024 + ccol);
;     const float4 w1 = *(const float4*)(wc + j * 1024 + ccol + 4);
;     o[0] += f[0] * (w0.x * mk); o[1] += f[1] * (w0.y * mk); o[2] += f[2] * (w0.z * mk); o[3] += f[3] * (w0.w * mk);
;     o[4] += f[4] * (w1.x * mk); o[5] += f[5] * (w1.y * mk); o[6] += f[6] * (w1.z * mk); o[7] += f[7] * (w1.w * mk);
;   }
; #pragma unroll
;   for (int e = 0; e < 8; ++e) o[e] = siluf(o[e]);
; __device__ void ml_local_tile(unsigned char* lds, const Params& p, int l, int b, int h, int n) {
;     ...
;     for (int i = 0; i < 4; ++i) {
;       const int ec = ec0 + 4 * i;
;       float k8[8];
;       ml_conv8_comp(ku[i], wc, 512 + h * 128 + ec * 8, L, p0 + s, k8);
;       float v8[8];
;       unpack8(vu[i], v8);
; #pragma unroll
;       for (int e = 0; e < 8; ++e) {
;         KT[(ec * 8 + e) * 136 + s] = f2bf(k8[e] * 0.08838834764831845f);
;         VF[(ec * 8 + e) * 136 + s] = f2bf(v8[e] * wf);
;         VB[(ec * 8 + e) * 136 + s] = f2bf(v8[e] * wb);
;       }
	ds_write_b16 v106, v104 offset:43792
	ds_write_b16 v107, v112 offset:8976
	v_lshlrev_b32_e32 v105, 16, v41
	v_mul_f32_e32 v104, v80, v105
	v_mul_f32_e32 v112, v81, v105
	v_cvt_pk_bf16_f32 v104, v104, v104
	v_cvt_pk_bf16_f32 v112, v112, v112
	ds_write_b16 v106, v104 offset:44064
	ds_write_b16 v107, v112 offset:9248
	v_and_b32_e32 v105, 0xffff0000, v41
	v_mul_f32_e32 v104, v80, v105
	v_mul_f32_e32 v112, v81, v105
	v_cvt_pk_bf16_f32 v104, v104, v104
	v_cvt_pk_bf16_f32 v112, v112, v112
	ds_write_b16 v106, v104 offset:44336
	ds_write_b16 v107, v112 offset:9520
	v_lshlrev_b32_e32 v105, 16, v42
	v_mul_f32_e32 v104, v80, v105
	v_mul_f32_e32 v112, v81, v105
	v_cvt_pk_bf16_f32 v104, v104, v104
	v_cvt_pk_bf16_f32 v112, v112, v112
	ds_write_b16 v106, v104 offset:44608
	ds_write_b16 v107, v112 offset:9792
	v_and_b32_e32 v105, 0xffff0000, v42
	v_mul_f32_e32 v104, v80, v105
	v_mul_f32_e32 v112, v81, v105
	v_cvt_pk_bf16_f32 v104, v104, v104
	v_cvt_pk_bf16_f32 v112, v112, v112
	ds_write_b16 v106, v104 offset:44880
	ds_write_b16 v107, v112 offset:10064
	v_lshlrev_b32_e32 v105, 16, v43
	v_mul_f32_e32 v104, v80, v105
	v_mul_f32_e32 v112, v81, v105
	v_cvt_pk_bf16_f32 v104, v104, v104
	v_cvt_pk_bf16_f32 v112, v112, v112
	ds_write_b16 v106, v104 offset:45152
	ds_write_b16 v107, v112 offset:10336
	v_and_b32_e32 v105, 0xffff0000, v43
	v_mul_f32_e32 v104, v80, v105
	v_mul_f32_e32 v112, v81, v105
	v_cvt_pk_bf16_f32 v104, v104, v104
	v_cvt_pk_bf16_f32 v112, v112, v112
	ds_write_b16 v106, v104 offset:45424
	ds_write_b16 v107, v112 offset:10608
	global_load_dwordx4 v[146:149], v[84:85], off offset:2432
	global_load_dwordx4 v[150:153], v[84:85], off offset:2448
	global_load_dwordx4 v[154:157], v[178:179], off offset:2432
	global_load_dwordx4 v[158:161], v[178:179], off offset:2448
	global_load_dwordx4 v[162:165], v[180:181], off offset:2432
	global_load_dwordx4 v[166:169], v[180:181], off offset:2448
	global_load_dwordx4 v[170:173], v[182:183], off offset:2432
	global_load_dwordx4 v[174:177], v[182:183], off offset:2448
	s_waitcnt vmcnt(8)
	v_mul_f32_e32 v104, v95, v114
	v_lshlrev_b32_e32 v105, 16, v36
	v_fma_f32 v96, v104, v105, 0
	v_mul_f32_e32 v104, v95, v115
	v_and_b32_e32 v105, 0xffff0000, v36
	v_fma_f32 v97, v104, v105, 0
	v_mul_f32_e32 v104, v95, v116
	v_lshlrev_b32_e32 v105, 16, v37
	v_fma_f32 v98, v104, v105, 0
	v_mul_f32_e32 v104, v95, v117
	v_and_b32_e32 v105, 0xffff0000, v37
	v_fma_f32 v99, v104, v105, 0
	v_mul_f32_e32 v104, v95, v118
	v_lshlrev_b32_e32 v105, 16, v38
	v_fma_f32 v100, v104, v105, 0
	v_mul_f32_e32 v104, v95, v119
	v_and_b32_e32 v105, 0xffff0000, v38
	v_fma_f32 v101, v104, v105, 0
	v_mul_f32_e32 v104, v95, v120
	v_lshlrev_b32_e32 v105, 16, v39
	v_fma_f32 v102, v104, v105, 0
	v_mul_f32_e32 v104, v95, v121
	v_and_b32_e32 v105, 0xffff0000, v39
	v_fma_f32 v103, v104, v105, 0
	v_mul_f32_e32 v104, v94, v122
	v_lshlrev_b32_e32 v105, 16, v32
	v_fmac_f32_e32 v96, v104, v105
	v_mul_f32_e32 v104, v94, v123
	v_and_b32_e32 v105, 0xffff0000, v32
	v_fmac_f32_e32 v97, v104, v105
	v_mul_f32_e32 v104, v94, v124
	v_lshlrev_b32_e32 v105, 16, v33
	v_fmac_f32_e32 v98, v104, v105
	v_mul_f32_e32 v104, v94, v125
	v_and_b32_e32 v105, 0xffff0000, v33
	v_fmac_f32_e32 v99, v104, v105
	v_mul_f32_e32 v104, v94, v126
	v_lshlrev_b32_e32 v105, 16, v34
	v_fmac_f32_e32 v100, v104, v105
	v_mul_f32_e32 v104, v94, v127
	v_and_b32_e32 v105, 0xffff0000, v34
	v_fmac_f32_e32 v101, v104, v105
	v_mul_f32_e32 v104, v94, v128
	v_lshlrev_b32_e32 v105, 16, v35
	v_fmac_f32_e32 v102, v104, v105
	v_mul_f32_e32 v104, v94, v129
	v_and_b32_e32 v105, 0xffff0000, v35
	v_fmac_f32_e32 v103, v104, v105
	v_mul_f32_e32 v104, v93, v130
	v_lshlrev_b32_e32 v105, 16, v28
	v_fmac_f32_e32 v96, v104, v105
	v_mul_f32_e32 v104, v93, v131
	v_and_b32_e32 v105, 0xffff0000, v28
	v_fmac_f32_e32 v97, v104, v105
	v_mul_f32_e32 v104, v93, v132
	v_lshlrev_b32_e32 v105, 16, v29
	v_fmac_f32_e32 v98, v104, v105
	v_mul_f32_e32 v104, v93, v133
	v_and_b32_e32 v105, 0xffff0000, v29
	v_fmac_f32_e32 v99, v104, v105
	v_mul_f32_e32 v104, v93, v134
	v_lshlrev_b32_e32 v105, 16, v30
	v_fmac_f32_e32 v100, v104, v105
	v_mul_f32_e32 v104, v93, v135
	v_and_b32_e32 v105, 0xffff0000, v30
	v_fmac_f32_e32 v101, v104, v105
	v_mul_f32_e32 v104, v93, v136
	v_lshlrev_b32_e32 v105, 16, v31
	v_fmac_f32_e32 v102, v104, v105
	v_mul_f32_e32 v104, v93, v137
	v_and_b32_e32 v105, 0xffff0000, v31
	v_fmac_f32_e32 v103, v104, v105
	v_mul_f32_e32 v104, v92, v138
	v_lshlrev_b32_e32 v105, 16, v24
	v_fmac_f32_e32 v96, v104, v105
	v_mul_f32_e32 v104, v92, v139
	v_and_b32_e32 v105, 0xffff0000, v24
	v_fmac_f32_e32 v97, v104, v105
	v_mul_f32_e32 v104, v92, v140
	v_lshlrev_b32_e32 v105, 16, v25
	v_fmac_f32_e32 v98, v104, v105
	v_mul_f32_e32 v104, v92, v141
	v_and_b32_e32 v105, 0xffff0000, v25
	v_fmac_f32_e32 v99, v104, v105
	v_mul_f32_e32 v104, v92, v142
	v_lshlrev_b32_e32 v105, 16, v26
	v_fmac_f32_e32 v100, v104, v105
	v_mul_f32_e32 v104, v92, v143
	v_and_b32_e32 v105, 0xffff0000, v26
	v_fmac_f32_e32 v101, v104, v105
	v_mul_f32_e32 v104, v92, v144
	v_lshlrev_b32_e32 v105, 16, v27
	v_fmac_f32_e32 v102, v104, v105
	v_mul_f32_e32 v104, v92, v145
	v_and_b32_e32 v105, 0xffff0000, v27
	v_fmac_f32_e32 v103, v104, v105
	v_mul_f32_e32 v184, 0xbfb8aa3b, v96
	v_mul_f32_e32 v185, 0xbfb8aa3b, v97
	v_mul_f32_e32 v186, 0xbfb8aa3b, v98
	v_mul_f32_e32 v187, 0xbfb8aa3b, v99
	v_mul_f32_e32 v188, 0xbfb8aa3b, v100
	v_mul_f32_e32 v189, 0xbfb8aa3b, v101
	v_mul_f32_e32 v190, 0xbfb8aa3b, v102
	v_mul_f32_e32 v191, 0xbfb8aa3b, v103
	v_exp_f32_e32 v184, v184
	v_exp_f32_e32 v185, v185
	v_exp_f32_e32 v186, v186
	v_exp_f32_e32 v187, v187
	v_exp_f32_e32 v188, v188
	v_exp_f32_e32 v189, v189
; __device__ __forceinline__ bf16_t f2bf(float f) { return (bf16_t)(pack2(f, 0.f) & 0xffffu); }
; __device__ __forceinline__ float siluf(float x) { return x * frcp(1.f + fexp(-x)); }
; __device__ __forceinline__ void ml_conv8_comp(const uint4* u, const float* wc, int ccol, int L, int pos, float* o) {
; #pragma unroll
;   for (int e = 0; e < 8; ++e) o[e] = 0.f;
; #pragma unroll
;   for (int j = 0; j < 4; ++j) {
;     const int pp = pos + j - 1;
;     const float mk = (pp >= 0 && pp < L) ? 1.f : 0.f;
;     float f[8];
;     unpack8(u[j], f);
;     const float4 w0 = *(const float4*)(wc + j * 1024 + ccol);
;     const float4 w1 = *(const float4*)(wc + j * 1024 + ccol + 4);
;     o[0] += f[0] * (w0.x * mk); o[1] += f[1] * (w0.y * mk); o[2] += f[2] * (w0.z * mk); o[3] += f[3] * (w0.w * mk);
;     o[4] += f[4] * (w1.x * mk); o[5] += f[5] * (w1.y * mk); o[6] += f[6] * (w1.z * mk); o[7] += f[7] * (w1.w * mk);
;   }
; #pragma unroll
;   for (int e = 0; e < 8; ++e) o[e] = siluf(o[e]);
; __device__ void ml_local_tile(unsigned char* lds, const Params& p, int l, int b, int h, int n) {
;     ...
;     for (int i = 0; i < 4; ++i) {
;       const int ec = ec0 + 4 * i;
;       float k8[8];
;       ml_conv8_comp(ku[i], wc, 512 + h * 128 + ec * 8, L, p0 + s, k8);
;       float v8[8];
;       unpack8(vu[i], v8);
; #pragma unroll
;       for (int e = 0; e < 8; ++e) {
;         KT[(ec * 8 + e) * 136 + s] = f2bf(k8[e] * 0.08838834764831845f);
;         VF[(ec * 8 + e) * 136 + s] = f2bf(v8[e] * wf);
;         VB[(ec * 8 + e) * 136 + s] = f2bf(v8[e] * wb);
;       }
	v_exp_f32_e32 v190, v190
	v_exp_f32_e32 v191, v191
	v_add_f32_e32 v184, 1.0, v184
	v_add_f32_e32 v185, 1.0, v185
	v_add_f32_e32 v186, 1.0, v186
	v_add_f32_e32 v187, 1.0, v187
	v_add_f32_e32 v188, 1.0, v188
	v_add_f32_e32 v189, 1.0, v189
	v_add_f32_e32 v190, 1.0, v190
	v_add_f32_e32 v191, 1.0, v191
	v_rcp_f32_e32 v184, v184
	v_rcp_f32_e32 v185, v185
	v_rcp_f32_e32 v186, v186
	v_rcp_f32_e32 v187, v187
	v_rcp_f32_e32 v188, v188
	v_rcp_f32_e32 v189, v189
	v_rcp_f32_e32 v190, v190
	v_rcp_f32_e32 v191, v191
	s_nop 0
	v_mul_f32_e32 v96, v96, v184
	v_mul_f32_e32 v97, v97, v185
	v_mul_f32_e32 v98, v98, v186
	v_mul_f32_e32 v99, v99, v187
	v_mul_f32_e32 v100, v100, v188
	v_mul_f32_e32 v101, v101, v189
	v_mul_f32_e32 v102, v102, v190
	v_mul_f32_e32 v103, v103, v191
	v_mul_f32_e32 v96, 0x3db504f3, v96
	v_mul_f32_e32 v97, 0x3db504f3, v97
	v_mul_f32_e32 v98, 0x3db504f3, v98
	v_mul_f32_e32 v99, 0x3db504f3, v99
	v_mul_f32_e32 v100, 0x3db504f3, v100
	v_mul_f32_e32 v101, 0x3db504f3, v101
	v_mul_f32_e32 v102, 0x3db504f3, v102
	v_mul_f32_e32 v103, 0x3db504f3, v103
	v_cvt_pk_bf16_f32 v184, v96, v96
	v_cvt_pk_bf16_f32 v185, v97, v97
	v_cvt_pk_bf16_f32 v186, v98, v98
	v_cvt_pk_bf16_f32 v187, v99, v99
	v_cvt_pk_bf16_f32 v188, v100, v100
	v_cvt_pk_bf16_f32 v189, v101, v101
	v_cvt_pk_bf16_f32 v190, v102, v102
	v_cvt_pk_bf16_f32 v191, v103, v103
	ds_write_b16 v106, v184 offset:17408
	ds_write_b16 v106, v185 offset:17680
	ds_write_b16 v106, v186 offset:17952
	ds_write_b16 v106, v187 offset:18224
	ds_write_b16 v106, v188 offset:18496
	ds_write_b16 v106, v189 offset:18768
	ds_write_b16 v106, v190 offset:19040
	ds_write_b16 v106, v191 offset:19312
	v_lshlrev_b32_e32 v105, 16, v20
	v_mul_f32_e32 v104, v80, v105
	v_mul_f32_e32 v112, v81, v105
	v_cvt_pk_bf16_f32 v104, v104, v104
	v_cvt_pk_bf16_f32 v112, v112, v112
	ds_write_b16 v106, v104 offset:52224
	ds_write_b16 v107, v112 offset:17408
	v_and_b32_e32 v105, 0xffff0000, v20
	v_mul_f32_e32 v104, v80, v105
	v_mul_f32_e32 v112, v81, v105
	v_cvt_pk_bf16_f32 v104, v104, v104
	v_cvt_pk_bf16_f32 v112, v112, v112
	ds_write_b16 v106, v104 offset:52496
	ds_write_b16 v107, v112 offset:17680
	v_lshlrev_b32_e32 v105, 16, v21
	v_mul_f32_e32 v104, v80, v105
	v_mul_f32_e32 v112, v81, v105
	v_cvt_pk_bf16_f32 v104, v104, v104
	v_cvt_pk_bf16_f32 v112, v112, v112
	ds_write_b16 v106, v104 offset:52768
	ds_write_b16 v107, v112 offset:17952
	v_and_b32_e32 v105, 0xffff0000, v21
	v_mul_f32_e32 v104, v80, v105
	v_mul_f32_e32 v112, v81, v105
	v_cvt_pk_bf16_f32 v104, v104, v104
	v_cvt_pk_bf16_f32 v112, v112, v112
	ds_write_b16 v106, v104 offset:53040
	ds_write_b16 v107, v112 offset:18224
	v_lshlrev_b32_e32 v105, 16, v22
	v_mul_f32_e32 v104, v80, v105
	v_mul_f32_e32 v112, v81, v105
	v_cvt_pk_bf16_f32 v104, v104, v104
	v_cvt_pk_bf16_f32 v112, v112, v112
	ds_write_b16 v106, v104 offset:53312
	ds_write_b16 v107, v112 offset:18496
	v_and_b32_e32 v105, 0xffff0000, v22
	v_mul_f32_e32 v104, v80, v105
	v_mul_f32_e32 v112, v81, v105
	v_cvt_pk_bf16_f32 v104, v104, v104
	v_cvt_pk_bf16_f32 v112, v112, v112
	ds_write_b16 v106, v104 offset:53584
	ds_write_b16 v107, v112 offset:18768
	v_lshlrev_b32_e32 v105, 16, v23
	v_mul_f32_e32 v104, v80, v105
	v_mul_f32_e32 v112, v81, v105
	v_cvt_pk_bf16_f32 v104, v104, v104
	v_cvt_pk_bf16_f32 v112, v112, v112
	ds_write_b16 v106, v104 offset:53856
	ds_write_b16 v107, v112 offset:19040
	v_and_b32_e32 v105, 0xffff0000, v23
	v_mul_f32_e32 v104, v80, v105
	v_mul_f32_e32 v112, v81, v105
	v_cvt_pk_bf16_f32 v104, v104, v104
	v_cvt_pk_bf16_f32 v112, v112, v112
	ds_write_b16 v106, v104 offset:54128
	ds_write_b16 v107, v112 offset:19312
	s_waitcnt vmcnt(0)
	v_mul_f32_e32 v104, v95, v146
	v_lshlrev_b32_e32 v105, 16, v16
	v_fma_f32 v96, v104, v105, 0
	v_mul_f32_e32 v104, v95, v147
	v_and_b32_e32 v105, 0xffff0000, v16
	v_fma_f32 v97, v104, v105, 0
	v_mul_f32_e32 v104, v95, v148
	v_lshlrev_b32_e32 v105, 16, v17
	v_fma_f32 v98, v104, v105, 0
	v_mul_f32_e32 v104, v95, v149
	v_and_b32_e32 v105, 0xffff0000, v17
	v_fma_f32 v99, v104, v105, 0
	v_mul_f32_e32 v104, v95, v150
	v_lshlrev_b32_e32 v105, 16, v18
	v_fma_f32 v100, v104, v105, 0
	v_mul_f32_e32 v104, v95, v151
	v_and_b32_e32 v105, 0xffff0000, v18
	v_fma_f32 v101, v104, v105, 0
	v_mul_f32_e32 v104, v95, v152
	v_lshlrev_b32_e32 v105, 16, v19
	v_fma_f32 v102, v104, v105, 0
	v_mul_f32_e32 v104, v95, v153
	v_and_b32_e32 v105, 0xffff0000, v19
	v_fma_f32 v103, v104, v105, 0
	v_mul_f32_e32 v104, v94, v154
	v_lshlrev_b32_e32 v105, 16, v12
	v_fmac_f32_e32 v96, v104, v105
	v_mul_f32_e32 v104, v94, v155
	v_and_b32_e32 v105, 0xffff0000, v12
	v_fmac_f32_e32 v97, v104, v105
	v_mul_f32_e32 v104, v94, v156
	v_lshlrev_b32_e32 v105, 16, v13
	v_fmac_f32_e32 v98, v104, v105
	v_mul_f32_e32 v104, v94, v157
	v_and_b32_e32 v105, 0xffff0000, v13
	v_fmac_f32_e32 v99, v104, v105
	v_mul_f32_e32 v104, v94, v158
	v_lshlrev_b32_e32 v105, 16, v14
	v_fmac_f32_e32 v100, v104, v105
	v_mul_f32_e32 v104, v94, v159
	v_and_b32_e32 v105, 0xffff0000, v14
	v_fmac_f32_e32 v101, v104, v105
	v_mul_f32_e32 v104, v94, v160
	v_lshlrev_b32_e32 v105, 16, v15
	v_fmac_f32_e32 v102, v104, v105
	v_mul_f32_e32 v104, v94, v161
	v_and_b32_e32 v105, 0xffff0000, v15
	v_fmac_f32_e32 v103, v104, v105
	v_mul_f32_e32 v104, v93, v162
	v_lshlrev_b32_e32 v105, 16, v8
	v_fmac_f32_e32 v96, v104, v105
	v_mul_f32_e32 v104, v93, v163
	v_and_b32_e32 v105, 0xffff0000, v8
	v_fmac_f32_e32 v97, v104, v105
	v_mul_f32_e32 v104, v93, v164
	v_lshlrev_b32_e32 v105, 16, v9
	v_fmac_f32_e32 v98, v104, v105
	v_mul_f32_e32 v104, v93, v165
	v_and_b32_e32 v105, 0xffff0000, v9
	v_fmac_f32_e32 v99, v104, v105
	v_mul_f32_e32 v104, v93, v166
	v_lshlrev_b32_e32 v105, 16, v10
; __device__ __forceinline__ bf16_t f2bf(float f) { return (bf16_t)(pack2(f, 0.f) & 0xffffu); }
; __device__ void ml_local_tile(unsigned char* lds, const Params& p, int l, int b, int h, int n) {
;     ...
;       ml_conv8_comp(ku[i], wc, 512 + h * 128 + ec * 8, L, p0 + s, k8);
;       float v8[8];
;       unpack8(vu[i], v8);
; #pragma unroll
;       for (int e = 0; e < 8; ++e) {
;         KT[(ec * 8 + e) * 136 + s] = f2bf(k8[e] * 0.08838834764831845f);
;         VF[(ec * 8 + e) * 136 + s] = f2bf(v8[e] * wf);
;         VB[(ec * 8 + e) * 136 + s] = f2bf(v8[e] * wb);
;       }
;     }
;   }
;   __syncthreads();
	v_fmac_f32_e32 v100, v104, v105
	v_mul_f32_e32 v104, v93, v167
	v_and_b32_e32 v105, 0xffff0000, v10
	v_fmac_f32_e32 v101, v104, v105
	v_mul_f32_e32 v104, v93, v168
	v_lshlrev_b32_e32 v105, 16, v11
	v_fmac_f32_e32 v102, v104, v105
	v_mul_f32_e32 v104, v93, v169
	v_and_b32_e32 v105, 0xffff0000, v11
	v_fmac_f32_e32 v103, v104, v105
	v_mul_f32_e32 v104, v92, v170
	v_lshlrev_b32_e32 v105, 16, v4
	v_fmac_f32_e32 v96, v104, v105
	v_mul_f32_e32 v104, v92, v171
	v_and_b32_e32 v105, 0xffff0000, v4
	v_fmac_f32_e32 v97, v104, v105
	v_mul_f32_e32 v104, v92, v172
	v_lshlrev_b32_e32 v105, 16, v5
	v_fmac_f32_e32 v98, v104, v105
	v_mul_f32_e32 v104, v92, v173
	v_and_b32_e32 v105, 0xffff0000, v5
	v_fmac_f32_e32 v99, v104, v105
	v_mul_f32_e32 v104, v92, v174
	v_lshlrev_b32_e32 v105, 16, v6
	v_fmac_f32_e32 v100, v104, v105
	v_mul_f32_e32 v104, v92, v175
	v_and_b32_e32 v105, 0xffff0000, v6
	v_fmac_f32_e32 v101, v104, v105
	v_mul_f32_e32 v104, v92, v176
	v_lshlrev_b32_e32 v105, 16, v7
	v_fmac_f32_e32 v102, v104, v105
	v_mul_f32_e32 v104, v92, v177
	v_and_b32_e32 v105, 0xffff0000, v7
	v_fmac_f32_e32 v103, v104, v105
	v_mul_f32_e32 v184, 0xbfb8aa3b, v96
	v_mul_f32_e32 v185, 0xbfb8aa3b, v97
	v_mul_f32_e32 v186, 0xbfb8aa3b, v98
	v_mul_f32_e32 v187, 0xbfb8aa3b, v99
	v_mul_f32_e32 v188, 0xbfb8aa3b, v100
	v_mul_f32_e32 v189, 0xbfb8aa3b, v101
	v_mul_f32_e32 v190, 0xbfb8aa3b, v102
	v_mul_f32_e32 v191, 0xbfb8aa3b, v103
	v_exp_f32_e32 v184, v184
	v_exp_f32_e32 v185, v185
	v_exp_f32_e32 v186, v186
	v_exp_f32_e32 v187, v187
	v_exp_f32_e32 v188, v188
	v_exp_f32_e32 v189, v189
	v_exp_f32_e32 v190, v190
	v_exp_f32_e32 v191, v191
	v_add_f32_e32 v184, 1.0, v184
	v_add_f32_e32 v185, 1.0, v185
	v_add_f32_e32 v186, 1.0, v186
	v_add_f32_e32 v187, 1.0, v187
	v_add_f32_e32 v188, 1.0, v188
	v_add_f32_e32 v189, 1.0, v189
	v_add_f32_e32 v190, 1.0, v190
	v_add_f32_e32 v191, 1.0, v191
	v_rcp_f32_e32 v184, v184
	v_rcp_f32_e32 v185, v185
	v_rcp_f32_e32 v186, v186
	v_rcp_f32_e32 v187, v187
	v_rcp_f32_e32 v188, v188
	v_rcp_f32_e32 v189, v189
	v_rcp_f32_e32 v190, v190
	v_rcp_f32_e32 v191, v191
	s_nop 0
	v_mul_f32_e32 v96, v96, v184
	v_mul_f32_e32 v97, v97, v185
	v_mul_f32_e32 v98, v98, v186
	v_mul_f32_e32 v99, v99, v187
	v_mul_f32_e32 v100, v100, v188
	v_mul_f32_e32 v101, v101, v189
	v_mul_f32_e32 v102, v102, v190
	v_mul_f32_e32 v103, v103, v191
	v_mul_f32_e32 v96, 0x3db504f3, v96
	v_mul_f32_e32 v97, 0x3db504f3, v97
	v_mul_f32_e32 v98, 0x3db504f3, v98
	v_mul_f32_e32 v99, 0x3db504f3, v99
	v_mul_f32_e32 v100, 0x3db504f3, v100
	v_mul_f32_e32 v101, 0x3db504f3, v101
	v_mul_f32_e32 v102, 0x3db504f3, v102
	v_mul_f32_e32 v103, 0x3db504f3, v103
	v_cvt_pk_bf16_f32 v184, v96, v96
	v_cvt_pk_bf16_f32 v185, v97, v97
	v_cvt_pk_bf16_f32 v186, v98, v98
	v_cvt_pk_bf16_f32 v187, v99, v99
	v_cvt_pk_bf16_f32 v188, v100, v100
	v_cvt_pk_bf16_f32 v189, v101, v101
	v_cvt_pk_bf16_f32 v190, v102, v102
	v_cvt_pk_bf16_f32 v191, v103, v103
	ds_write_b16 v106, v184 offset:26112
	ds_write_b16 v106, v185 offset:26384
	ds_write_b16 v106, v186 offset:26656
	ds_write_b16 v106, v187 offset:26928
	ds_write_b16 v106, v188 offset:27200
	ds_write_b16 v106, v189 offset:27472
	ds_write_b16 v106, v190 offset:27744
	ds_write_b16 v106, v191 offset:28016
	v_lshlrev_b32_e32 v105, 16, v0
	v_mul_f32_e32 v104, v80, v105
	v_mul_f32_e32 v112, v81, v105
	v_cvt_pk_bf16_f32 v104, v104, v104
	v_cvt_pk_bf16_f32 v112, v112, v112
	ds_write_b16 v106, v104 offset:60928
	ds_write_b16 v107, v112 offset:26112
	v_and_b32_e32 v105, 0xffff0000, v0
	v_mul_f32_e32 v104, v80, v105
	v_mul_f32_e32 v112, v81, v105
	v_cvt_pk_bf16_f32 v104, v104, v104
	v_cvt_pk_bf16_f32 v112, v112, v112
	ds_write_b16 v106, v104 offset:61200
	ds_write_b16 v107, v112 offset:26384
	v_lshlrev_b32_e32 v105, 16, v1
	v_mul_f32_e32 v104, v80, v105
	v_mul_f32_e32 v112, v81, v105
	v_cvt_pk_bf16_f32 v104, v104, v104
	v_cvt_pk_bf16_f32 v112, v112, v112
	ds_write_b16 v106, v104 offset:61472
	ds_write_b16 v107, v112 offset:26656
	v_and_b32_e32 v105, 0xffff0000, v1
	v_mul_f32_e32 v104, v80, v105
	v_mul_f32_e32 v112, v81, v105
	v_cvt_pk_bf16_f32 v104, v104, v104
	v_cvt_pk_bf16_f32 v112, v112, v112
	ds_write_b16 v106, v104 offset:61744
	ds_write_b16 v107, v112 offset:26928
	v_lshlrev_b32_e32 v105, 16, v2
	v_mul_f32_e32 v104, v80, v105
	v_mul_f32_e32 v112, v81, v105
	v_cvt_pk_bf16_f32 v104, v104, v104
	v_cvt_pk_bf16_f32 v112, v112, v112
	ds_write_b16 v106, v104 offset:62016
	ds_write_b16 v107, v112 offset:27200
	v_and_b32_e32 v105, 0xffff0000, v2
	v_mul_f32_e32 v104, v80, v105
	v_mul_f32_e32 v112, v81, v105
	v_cvt_pk_bf16_f32 v104, v104, v104
	v_cvt_pk_bf16_f32 v112, v112, v112
	ds_write_b16 v106, v104 offset:62288
	ds_write_b16 v107, v112 offset:27472
	v_lshlrev_b32_e32 v105, 16, v3
	v_mul_f32_e32 v104, v80, v105
	v_mul_f32_e32 v112, v81, v105
	v_cvt_pk_bf16_f32 v104, v104, v104
	v_cvt_pk_bf16_f32 v112, v112, v112
	ds_write_b16 v106, v104 offset:62560
	ds_write_b16 v107, v112 offset:27744
	v_and_b32_e32 v105, 0xffff0000, v3
	v_mul_f32_e32 v104, v80, v105
	v_mul_f32_e32 v112, v81, v105
	v_cvt_pk_bf16_f32 v104, v104, v104
	v_cvt_pk_bf16_f32 v112, v112, v112
	ds_write_b16 v106, v104 offset:62832
	ds_write_b16 v107, v112 offset:28016
	v_lshl_or_b32 v0, v89, 4, v90
	v_lshlrev_b32_e32 v1, 4, v91
	v_mul_lo_u32 v0, v0, s93
	v_add_u32_e32 v8, 0, v1
	v_add_u32_e32 v9, v8, v0
	v_mad_u32_u24 v8, v90, s93, v8
	s_and_b32 s2, s21, -4
	s_ashr_i32 s21, s20, 31
	s_waitcnt lgkmcnt(0)
	s_barrier
; __device__ void ml_local_tile(unsigned char* lds, const Params& p, int l, int b, int h, int n) {
;     ...
;   {
;     f32x4 accf[8], accb[8];
; #pragma unroll
;     for (int i = 0; i < 8; ++i) { accf[i] = (f32x4){0.f, 0.f, 0.f, 0.f}; accb[i] = (f32x4){0.f, 0.f, 0.f, 0.f}; }
; #pragma unroll
;     for (int ks = 0; ks < 4; ++ks) {
;       const bf16x8 bfv = ldfrag(VF + (16 * w + lr) * 136 + ks * 32 + lg * 8);
;       const bf16x8 bbv = ldfrag(VB + (16 * w + lr) * 136 + ks * 32 + lg * 8);
; #pragma unroll
;       for (int ef = 0; ef < 8; ++ef) {
;         const bf16x8 a = ldfrag(KT + (ef * 16 + lr) * 136 + ks * 32 + lg * 8);
;         accf[ef] = mfma16(a, bfv, accf[ef]);
;         accb[ef] = mfma16(a, bbv, accb[ef]);
;       }
;     }
	v_add3_u32 v78, s0, v0, v1
	ds_read_b128 v[0:3], v9 offset:34816
	ds_read_b128 v[4:7], v78
	ds_read_b128 v[10:13], v8
	ds_read_b128 v[18:21], v8 offset:4352
	ds_read_b128 v[26:29], v8 offset:8704
	ds_read_b128 v[34:37], v8 offset:13056
	ds_read_b128 v[42:45], v8 offset:17408
	ds_read_b128 v[50:53], v8 offset:21760
	ds_read_b128 v[58:61], v8 offset:26112
	ds_read_b128 v[66:69], v8 offset:30464
	s_waitcnt lgkmcnt(7)
	v_mfma_f32_16x16x32_bf16 v[14:17], v[10:13], v[0:3], 0
	s_lshl_b64 s[0:1], s[20:21], 15
	s_add_u32 s0, s82, s0
	s_addc_u32 s1, s83, s1
	v_mfma_f32_16x16x32_bf16 v[10:13], v[10:13], v[4:7], 0
	s_waitcnt lgkmcnt(6)
	v_mfma_f32_16x16x32_bf16 v[22:25], v[18:21], v[0:3], 0
	v_mfma_f32_16x16x32_bf16 v[18:21], v[18:21], v[4:7], 0
	s_waitcnt lgkmcnt(5)
	v_mfma_f32_16x16x32_bf16 v[30:33], v[26:29], v[0:3], 0
	v_mfma_f32_16x16x32_bf16 v[26:29], v[26:29], v[4:7], 0
	s_waitcnt lgkmcnt(4)
	v_mfma_f32_16x16x32_bf16 v[38:41], v[34:37], v[0:3], 0
	v_mfma_f32_16x16x32_bf16 v[34:37], v[34:37], v[4:7], 0
	s_waitcnt lgkmcnt(3)
	v_mfma_f32_16x16x32_bf16 v[46:49], v[42:45], v[0:3], 0
	v_mfma_f32_16x16x32_bf16 v[42:45], v[42:45], v[4:7], 0
	s_waitcnt lgkmcnt(2)
	v_mfma_f32_16x16x32_bf16 v[54:57], v[50:53], v[0:3], 0
	v_mfma_f32_16x16x32_bf16 v[50:53], v[50:53], v[4:7], 0
	s_waitcnt lgkmcnt(1)
	v_mfma_f32_16x16x32_bf16 v[62:65], v[58:61], v[0:3], 0
	v_mfma_f32_16x16x32_bf16 v[58:61], v[58:61], v[4:7], 0
	s_waitcnt lgkmcnt(0)
	v_mfma_f32_16x16x32_bf16 v[0:3], v[66:69], v[0:3], 0
	v_mfma_f32_16x16x32_bf16 v[4:7], v[66:69], v[4:7], 0
	ds_read_b128 v[66:69], v9 offset:34880
	ds_read_b128 v[70:73], v78 offset:64
	ds_read_b128 v[74:77], v8 offset:64
	s_waitcnt lgkmcnt(0)
	v_mfma_f32_16x16x32_bf16 v[14:17], v[74:77], v[66:69], v[14:17]
	v_mfma_f32_16x16x32_bf16 v[10:13], v[74:77], v[70:73], v[10:13]
	ds_read_b128 v[74:77], v8 offset:4416
	s_waitcnt lgkmcnt(0)
	v_mfma_f32_16x16x32_bf16 v[22:25], v[74:77], v[66:69], v[22:25]
	v_mfma_f32_16x16x32_bf16 v[18:21], v[74:77], v[70:73], v[18:21]
	ds_read_b128 v[74:77], v8 offset:8768
	s_waitcnt lgkmcnt(0)
	v_mfma_f32_16x16x32_bf16 v[30:33], v[74:77], v[66:69], v[30:33]
	v_mfma_f32_16x16x32_bf16 v[26:29], v[74:77], v[70:73], v[26:29]
	ds_read_b128 v[74:77], v8 offset:13120
	s_waitcnt lgkmcnt(0)
	v_mfma_f32_16x16x32_bf16 v[38:41], v[74:77], v[66:69], v[38:41]
	v_mfma_f32_16x16x32_bf16 v[34:37], v[74:77], v[70:73], v[34:37]
	ds_read_b128 v[74:77], v8 offset:17472
	s_waitcnt lgkmcnt(0)
	v_mfma_f32_16x16x32_bf16 v[46:49], v[74:77], v[66:69], v[46:49]
	v_mfma_f32_16x16x32_bf16 v[42:45], v[74:77], v[70:73], v[42:45]
	ds_read_b128 v[74:77], v8 offset:21824
	s_waitcnt lgkmcnt(0)
	v_mfma_f32_16x16x32_bf16 v[54:57], v[74:77], v[66:69], v[54:57]
	v_mfma_f32_16x16x32_bf16 v[50:53], v[74:77], v[70:73], v[50:53]
	ds_read_b128 v[74:77], v8 offset:26176
	s_waitcnt lgkmcnt(0)
	v_mfma_f32_16x16x32_bf16 v[62:65], v[74:77], v[66:69], v[62:65]
	v_mfma_f32_16x16x32_bf16 v[58:61], v[74:77], v[70:73], v[58:61]
	ds_read_b128 v[74:77], v8 offset:30528
	s_waitcnt lgkmcnt(0)
	v_mfma_f32_16x16x32_bf16 v[0:3], v[74:77], v[66:69], v[0:3]
	v_mfma_f32_16x16x32_bf16 v[66:69], v[74:77], v[70:73], v[4:7]
	s_nop 2
	ds_read_b128 v[4:7], v9 offset:34944
	ds_read_b128 v[70:73], v78 offset:128
	ds_read_b128 v[74:77], v8 offset:128
	s_waitcnt lgkmcnt(0)
	v_mfma_f32_16x16x32_bf16 v[14:17], v[74:77], v[4:7], v[14:17]
	v_mfma_f32_16x16x32_bf16 v[10:13], v[74:77], v[70:73], v[10:13]
	ds_read_b128 v[74:77], v8 offset:4480
	s_waitcnt lgkmcnt(0)
	v_mfma_f32_16x16x32_bf16 v[22:25], v[74:77], v[4:7], v[22:25]
	v_mfma_f32_16x16x32_bf16 v[18:21], v[74:77], v[70:73], v[18:21]
	ds_read_b128 v[74:77], v8 offset:8832
	s_waitcnt lgkmcnt(0)
	v_mfma_f32_16x16x32_bf16 v[30:33], v[74:77], v[4:7], v[30:33]
	v_mfma_f32_16x16x32_bf16 v[26:29], v[74:77], v[70:73], v[26:29]
	ds_read_b128 v[74:77], v8 offset:13184
	s_waitcnt lgkmcnt(0)
	v_mfma_f32_16x16x32_bf16 v[38:41], v[74:77], v[4:7], v[38:41]
	v_mfma_f32_16x16x32_bf16 v[34:37], v[74:77], v[70:73], v[34:37]
	ds_read_b128 v[74:77], v8 offset:17536
	s_waitcnt lgkmcnt(0)
	v_mfma_f32_16x16x32_bf16 v[46:49], v[74:77], v[4:7], v[46:49]
	v_mfma_f32_16x16x32_bf16 v[42:45], v[74:77], v[70:73], v[42:45]
	ds_read_b128 v[74:77], v8 offset:21888
	s_waitcnt lgkmcnt(0)
	v_mfma_f32_16x16x32_bf16 v[54:57], v[74:77], v[4:7], v[54:57]
	v_mfma_f32_16x16x32_bf16 v[50:53], v[74:77], v[70:73], v[50:53]
	ds_read_b128 v[74:77], v8 offset:26240
	s_waitcnt lgkmcnt(0)
	v_mfma_f32_16x16x32_bf16 v[62:65], v[74:77], v[4:7], v[62:65]
	v_mfma_f32_16x16x32_bf16 v[58:61], v[74:77], v[70:73], v[58:61]
	ds_read_b128 v[74:77], v8 offset:30592
	s_waitcnt lgkmcnt(0)
	v_mfma_f32_16x16x32_bf16 v[4:7], v[74:77], v[4:7], v[0:3]
	v_mfma_f32_16x16x32_bf16 v[0:3], v[74:77], v[70:73], v[66:69]
	s_nop 2
	ds_read_b128 v[66:69], v9 offset:35008
	ds_read_b128 v[70:73], v78 offset:192
	ds_read_b128 v[74:77], v8 offset:192
	s_waitcnt lgkmcnt(0)
	v_mfma_f32_16x16x32_bf16 v[14:17], v[74:77], v[66:69], v[14:17]
	v_mfma_f32_16x16x32_bf16 v[10:13], v[74:77], v[70:73], v[10:13]
	ds_read_b128 v[74:77], v8 offset:4544
	s_nop 5
	v_cvt_pk_bf16_f32 v14, v14, v15
	v_cvt_pk_bf16_f32 v15, v16, v17
	s_waitcnt lgkmcnt(0)
	v_mfma_f32_16x16x32_bf16 v[22:25], v[74:77], v[66:69], v[22:25]
	v_cvt_pk_bf16_f32 v10, v10, v11
	v_cvt_pk_bf16_f32 v11, v12, v13
	v_mfma_f32_16x16x32_bf16 v[18:21], v[74:77], v[70:73], v[18:21]
	ds_read_b128 v[74:77], v8 offset:8896
	s_waitcnt lgkmcnt(0)
	v_mfma_f32_16x16x32_bf16 v[30:33], v[74:77], v[66:69], v[30:33]
	v_mfma_f32_16x16x32_bf16 v[26:29], v[74:77], v[70:73], v[26:29]
	ds_read_b128 v[74:77], v8 offset:13248
	s_waitcnt lgkmcnt(0)
; __device__ __forceinline__ float bf2f(bf16_t h) { return __uint_as_float(((unsigned)h) << 16); }
; __device__ __forceinline__ int sidx(int dir, int b, int h, int n) { return ((dir * 8 + b) * 4 + h) * 18 + n; }
; __device__ void ml_local_tile(unsigned char* lds, const Params& p, int l, int b, int h, int n) {
;     ...
;     bf16_t* cf = Cst + (size_t)sidx(0, b, h, n) * 16384 + (16 * w + lr) * 128;
;     bf16_t* cb = Cst + (size_t)sidx(1, b, h, n) * 16384 + (16 * w + lr) * 128;
; #pragma unroll
;     for (int ef = 0; ef < 8; ++ef) {
;       uint2 u; u.x = pack2(accf[ef][0], accf[ef][1]); u.y = pack2(accf[ef][2], accf[ef][3]);
;       *(uint2*)(cf + ef * 16 + lg * 4) = u;
;       uint2 u2; u2.x = pack2(accb[ef][0], accb[ef][1]); u2.y = pack2(accb[ef][2], accb[ef][3]);
;       *(uint2*)(cb + ef * 16 + lg * 4) = u2;
;     }
;   }
;   if (tid < 256) {
;     const int e = tid & 127, dir = tid >> 7;
;     const float* wv = vec + (6 + dir) * 128;
;     float s = 0.f;
;     for (int q = 0; q < 128; ++q) s += wv[q] * bf2f(KT[e * 136 + q]);
;     nst[(size_t)sidx(dir, b, h, n) * 128 + e] = s;
	v_mfma_f32_16x16x32_bf16 v[38:41], v[74:77], v[66:69], v[38:41]
	v_mfma_f32_16x16x32_bf16 v[34:37], v[74:77], v[70:73], v[34:37]
	ds_read_b128 v[74:77], v8 offset:17600
	s_waitcnt lgkmcnt(0)
	v_mfma_f32_16x16x32_bf16 v[46:49], v[74:77], v[66:69], v[46:49]
	v_mfma_f32_16x16x32_bf16 v[42:45], v[74:77], v[70:73], v[42:45]
	ds_read_b128 v[74:77], v8 offset:21952
	s_waitcnt lgkmcnt(0)
	v_mfma_f32_16x16x32_bf16 v[54:57], v[74:77], v[66:69], v[54:57]
	v_mfma_f32_16x16x32_bf16 v[50:53], v[74:77], v[70:73], v[50:53]
	ds_read_b128 v[74:77], v8 offset:26304
	s_waitcnt lgkmcnt(0)
	v_mfma_f32_16x16x32_bf16 v[62:65], v[74:77], v[66:69], v[62:65]
	v_mfma_f32_16x16x32_bf16 v[58:61], v[74:77], v[70:73], v[58:61]
	ds_read_b128 v[74:77], v8 offset:30656
	v_lshlrev_b32_e32 v8, 7, v90
	v_lshl_or_b32 v8, v89, 11, v8
	v_ashrrev_i32_e32 v9, 31, v8
	v_lshlrev_b64 v[8:9], 1, v[8:9]
	s_waitcnt lgkmcnt(0)
	v_mfma_f32_16x16x32_bf16 v[4:7], v[74:77], v[66:69], v[4:7]
	v_lshl_add_u64 v[66:67], s[0:1], 0, v[8:9]
	s_or_b32 s0, s2, s25
	s_mul_i32 s0, s0, 18
	s_add_i32 s0, s0, s24
	s_addk_i32 s0, 0x240
	s_ashr_i32 s1, s0, 31
	s_lshl_b64 s[0:1], s[0:1], 15
	s_add_u32 s0, s82, s0
	s_addc_u32 s1, s83, s1
	v_lshl_add_u64 v[8:9], s[0:1], 0, v[8:9]
	v_lshl_add_u64 v[66:67], v[66:67], 0, v[192:193]
	v_lshl_add_u64 v[8:9], v[8:9], 0, v[192:193]
	global_store_dwordx2 v[66:67], v[14:15], off
	global_store_dwordx2 v[8:9], v[10:11], off
	v_cvt_pk_bf16_f32 v10, v22, v23
	v_cvt_pk_bf16_f32 v11, v24, v25
	global_store_dwordx2 v[66:67], v[10:11], off offset:32
	v_cvt_pk_bf16_f32 v10, v18, v19
	v_cvt_pk_bf16_f32 v11, v20, v21
	global_store_dwordx2 v[8:9], v[10:11], off offset:32
	v_cvt_pk_bf16_f32 v10, v30, v31
	v_cvt_pk_bf16_f32 v11, v32, v33
	global_store_dwordx2 v[66:67], v[10:11], off offset:64
	v_cvt_pk_bf16_f32 v10, v26, v27
	v_cvt_pk_bf16_f32 v11, v28, v29
	global_store_dwordx2 v[8:9], v[10:11], off offset:64
	v_cvt_pk_bf16_f32 v10, v38, v39
	v_cvt_pk_bf16_f32 v11, v40, v41
	global_store_dwordx2 v[66:67], v[10:11], off offset:96
	v_cvt_pk_bf16_f32 v10, v34, v35
	v_cvt_pk_bf16_f32 v11, v36, v37
	global_store_dwordx2 v[8:9], v[10:11], off offset:96
	v_cvt_pk_bf16_f32 v10, v46, v47
	v_cvt_pk_bf16_f32 v11, v48, v49
	v_mfma_f32_16x16x32_bf16 v[0:3], v[74:77], v[70:73], v[0:3]
	global_store_dwordx2 v[66:67], v[10:11], off offset:128
	v_cvt_pk_bf16_f32 v10, v42, v43
	v_cvt_pk_bf16_f32 v11, v44, v45
	global_store_dwordx2 v[8:9], v[10:11], off offset:128
	v_cvt_pk_bf16_f32 v10, v54, v55
	v_cvt_pk_bf16_f32 v11, v56, v57
	global_store_dwordx2 v[66:67], v[10:11], off offset:160
	v_cvt_pk_bf16_f32 v10, v50, v51
	v_cvt_pk_bf16_f32 v11, v52, v53
	global_store_dwordx2 v[8:9], v[10:11], off offset:160
	v_cvt_pk_bf16_f32 v10, v62, v63
	v_cvt_pk_bf16_f32 v11, v64, v65
	s_movk_i32 s0, 0x100
	global_store_dwordx2 v[66:67], v[10:11], off offset:192
	v_cvt_pk_bf16_f32 v10, v58, v59
	v_cvt_pk_bf16_f32 v11, v60, v61
	v_cvt_pk_bf16_f32 v4, v4, v5
	v_cvt_pk_bf16_f32 v5, v6, v7
	v_cvt_pk_bf16_f32 v0, v0, v1
	v_cvt_pk_bf16_f32 v1, v2, v3
	v_cmp_gt_i32_e32 vcc, s0, v88
	global_store_dwordx2 v[8:9], v[10:11], off offset:192
	global_store_dwordx2 v[66:67], v[4:5], off offset:224
	global_store_dwordx2 v[8:9], v[0:1], off offset:224
	s_and_saveexec_b64 s[0:1], vcc
	s_cbranch_execz .LBB0_321
	v_lshlrev_b32_e32 v0, 2, v88
	v_and_b32_e32 v0, 0xfffffe00, v0
	v_mad_u32_u24 v1, v86, s93, 0
	s_movk_i32 s3, 0xfe00
	v_add_u32_e32 v2, 0, v0
	v_mov_b32_e32 v0, 0
	v_add_u32_e32 v3, 0x1a400, v2
	v_mov_b32_e32 v52, 0
	v_mov_b32_e32 v53, 0
	v_mov_b32_e32 v54, 0
	v_mov_b32_e32 v55, 0
	ds_read_b128 v[4:7], v1 offset:0
	ds_read_b128 v[8:11], v1 offset:16
	ds_read_b128 v[12:15], v3 offset:0
	ds_read_b128 v[16:19], v3 offset:16
	ds_read_b128 v[20:23], v3 offset:32
	ds_read_b128 v[24:27], v3 offset:48
	ds_read_b128 v[28:31], v1 offset:32
	ds_read_b128 v[32:35], v1 offset:48
	ds_read_b128 v[36:39], v3 offset:64
	ds_read_b128 v[40:43], v3 offset:80
	ds_read_b128 v[44:47], v3 offset:96
	ds_read_b128 v[48:51], v3 offset:112
	s_waitcnt lgkmcnt(6)
	v_lshlrev_b32_e32 v56, 16, v4
	v_fmac_f32_e32 v52, v12, v56
	v_and_b32_e32 v56, 0xffff0000, v4
	v_fmac_f32_e32 v53, v13, v56
	v_lshlrev_b32_e32 v56, 16, v5
	v_fmac_f32_e32 v54, v14, v56
	v_and_b32_e32 v56, 0xffff0000, v5
	v_fmac_f32_e32 v55, v15, v56
	v_lshlrev_b32_e32 v56, 16, v6
	v_fmac_f32_e32 v52, v16, v56
	v_and_b32_e32 v56, 0xffff0000, v6
	v_fmac_f32_e32 v53, v17, v56
	v_lshlrev_b32_e32 v56, 16, v7
	v_fmac_f32_e32 v54, v18, v56
	v_and_b32_e32 v56, 0xffff0000, v7
	v_fmac_f32_e32 v55, v19, v56
	v_lshlrev_b32_e32 v56, 16, v8
	v_fmac_f32_e32 v52, v20, v56
	v_and_b32_e32 v56, 0xffff0000, v8
	v_fmac_f32_e32 v53, v21, v56
	v_lshlrev_b32_e32 v56, 16, v9
	v_fmac_f32_e32 v54, v22, v56
	v_and_b32_e32 v56, 0xffff0000, v9
	v_fmac_f32_e32 v55, v23, v56
	v_lshlrev_b32_e32 v56, 16, v10
	v_fmac_f32_e32 v52, v24, v56
	v_and_b32_e32 v56, 0xffff0000, v10
	v_fmac_f32_e32 v53, v25, v56
	v_lshlrev_b32_e32 v56, 16, v11
	v_fmac_f32_e32 v54, v26, v56
	v_and_b32_e32 v56, 0xffff0000, v11
	v_fmac_f32_e32 v55, v27, v56
	ds_read_b128 v[4:7], v1 offset:64
	ds_read_b128 v[8:11], v1 offset:80
	ds_read_b128 v[12:15], v3 offset:128
	ds_read_b128 v[16:19], v3 offset:144
	ds_read_b128 v[20:23], v3 offset:160
	ds_read_b128 v[24:27], v3 offset:176
	s_waitcnt lgkmcnt(6)
; __device__ __forceinline__ float bf2f(bf16_t h) { return __uint_as_float(((unsigned)h) << 16); }
; __device__ __forceinline__ int sidx(int dir, int b, int h, int n) { return ((dir * 8 + b) * 4 + h) * 18 + n; }
; __device__ void ml_local_tile(unsigned char* lds, const Params& p, int l, int b, int h, int n) {
;     ...
;   if (tid < 256) {
;     const int e = tid & 127, dir = tid >> 7;
;     const float* wv = vec + (6 + dir) * 128;
;     float s = 0.f;
;     for (int q = 0; q < 128; ++q) s += wv[q] * bf2f(KT[e * 136 + q]);
;     nst[(size_t)sidx(dir, b, h, n) * 128 + e] = s;
	v_lshlrev_b32_e32 v56, 16, v28
	v_fmac_f32_e32 v52, v36, v56
	v_and_b32_e32 v56, 0xffff0000, v28
	v_fmac_f32_e32 v53, v37, v56
	v_lshlrev_b32_e32 v56, 16, v29
	v_fmac_f32_e32 v54, v38, v56
	v_and_b32_e32 v56, 0xffff0000, v29
	v_fmac_f32_e32 v55, v39, v56
	v_lshlrev_b32_e32 v56, 16, v30
	v_fmac_f32_e32 v52, v40, v56
	v_and_b32_e32 v56, 0xffff0000, v30
	v_fmac_f32_e32 v53, v41, v56
	v_lshlrev_b32_e32 v56, 16, v31
	v_fmac_f32_e32 v54, v42, v56
	v_and_b32_e32 v56, 0xffff0000, v31
	v_fmac_f32_e32 v55, v43, v56
	v_lshlrev_b32_e32 v56, 16, v32
	v_fmac_f32_e32 v52, v44, v56
	v_and_b32_e32 v56, 0xffff0000, v32
	v_fmac_f32_e32 v53, v45, v56
	v_lshlrev_b32_e32 v56, 16, v33
	v_fmac_f32_e32 v54, v46, v56
	v_and_b32_e32 v56, 0xffff0000, v33
	v_fmac_f32_e32 v55, v47, v56
	v_lshlrev_b32_e32 v56, 16, v34
	v_fmac_f32_e32 v52, v48, v56
	v_and_b32_e32 v56, 0xffff0000, v34
	v_fmac_f32_e32 v53, v49, v56
	v_lshlrev_b32_e32 v56, 16, v35
	v_fmac_f32_e32 v54, v50, v56
	v_and_b32_e32 v56, 0xffff0000, v35
	v_fmac_f32_e32 v55, v51, v56
	ds_read_b128 v[28:31], v1 offset:96
	ds_read_b128 v[32:35], v1 offset:112
	ds_read_b128 v[36:39], v3 offset:192
	ds_read_b128 v[40:43], v3 offset:208
	ds_read_b128 v[44:47], v3 offset:224
	ds_read_b128 v[48:51], v3 offset:240
	s_waitcnt lgkmcnt(6)
	v_lshlrev_b32_e32 v56, 16, v4
	v_fmac_f32_e32 v52, v12, v56
	v_and_b32_e32 v56, 0xffff0000, v4
	v_fmac_f32_e32 v53, v13, v56
	v_lshlrev_b32_e32 v56, 16, v5
	v_fmac_f32_e32 v54, v14, v56
	v_and_b32_e32 v56, 0xffff0000, v5
	v_fmac_f32_e32 v55, v15, v56
	v_lshlrev_b32_e32 v56, 16, v6
	v_fmac_f32_e32 v52, v16, v56
	v_and_b32_e32 v56, 0xffff0000, v6
	v_fmac_f32_e32 v53, v17, v56
	v_lshlrev_b32_e32 v56, 16, v7
	v_fmac_f32_e32 v54, v18, v56
	v_and_b32_e32 v56, 0xffff0000, v7
	v_fmac_f32_e32 v55, v19, v56
	v_lshlrev_b32_e32 v56, 16, v8
	v_fmac_f32_e32 v52, v20, v56
	v_and_b32_e32 v56, 0xffff0000, v8
	v_fmac_f32_e32 v53, v21, v56
	v_lshlrev_b32_e32 v56, 16, v9
	v_fmac_f32_e32 v54, v22, v56
	v_and_b32_e32 v56, 0xffff0000, v9
	v_fmac_f32_e32 v55, v23, v56
	v_lshlrev_b32_e32 v56, 16, v10
	v_fmac_f32_e32 v52, v24, v56
	v_and_b32_e32 v56, 0xffff0000, v10
	v_fmac_f32_e32 v53, v25, v56
	v_lshlrev_b32_e32 v56, 16, v11
	v_fmac_f32_e32 v54, v26, v56
	v_and_b32_e32 v56, 0xffff0000, v11
	v_fmac_f32_e32 v55, v27, v56
	ds_read_b128 v[4:7], v1 offset:128
	ds_read_b128 v[8:11], v1 offset:144
	ds_read_b128 v[12:15], v3 offset:256
	ds_read_b128 v[16:19], v3 offset:272
	ds_read_b128 v[20:23], v3 offset:288
	ds_read_b128 v[24:27], v3 offset:304
	s_waitcnt lgkmcnt(6)
	v_lshlrev_b32_e32 v56, 16, v28
	v_fmac_f32_e32 v52, v36, v56
	v_and_b32_e32 v56, 0xffff0000, v28
	v_fmac_f32_e32 v53, v37, v56
	v_lshlrev_b32_e32 v56, 16, v29
	v_fmac_f32_e32 v54, v38, v56
	v_and_b32_e32 v56, 0xffff0000, v29
	v_fmac_f32_e32 v55, v39, v56
	v_lshlrev_b32_e32 v56, 16, v30
	v_fmac_f32_e32 v52, v40, v56
	v_and_b32_e32 v56, 0xffff0000, v30
	v_fmac_f32_e32 v53, v41, v56
	v_lshlrev_b32_e32 v56, 16, v31
	v_fmac_f32_e32 v54, v42, v56
	v_and_b32_e32 v56, 0xffff0000, v31
	v_fmac_f32_e32 v55, v43, v56
	v_lshlrev_b32_e32 v56, 16, v32
	v_fmac_f32_e32 v52, v44, v56
	v_and_b32_e32 v56, 0xffff0000, v32
	v_fmac_f32_e32 v53, v45, v56
	v_lshlrev_b32_e32 v56, 16, v33
	v_fmac_f32_e32 v54, v46, v56
	v_and_b32_e32 v56, 0xffff0000, v33
	v_fmac_f32_e32 v55, v47, v56
	v_lshlrev_b32_e32 v56, 16, v34
	v_fmac_f32_e32 v52, v48, v56
	v_and_b32_e32 v56, 0xffff0000, v34
	v_fmac_f32_e32 v53, v49, v56
	v_lshlrev_b32_e32 v56, 16, v35
	v_fmac_f32_e32 v54, v50, v56
	v_and_b32_e32 v56, 0xffff0000, v35
	v_fmac_f32_e32 v55, v51, v56
	ds_read_b128 v[28:31], v1 offset:160
	ds_read_b128 v[32:35], v1 offset:176
	ds_read_b128 v[36:39], v3 offset:320
	ds_read_b128 v[40:43], v3 offset:336
	ds_read_b128 v[44:47], v3 offset:352
	ds_read_b128 v[48:51], v3 offset:368
	s_waitcnt lgkmcnt(6)
	v_lshlrev_b32_e32 v56, 16, v4
	v_fmac_f32_e32 v52, v12, v56
	v_and_b32_e32 v56, 0xffff0000, v4
	v_fmac_f32_e32 v53, v13, v56
	v_lshlrev_b32_e32 v56, 16, v5
	v_fmac_f32_e32 v54, v14, v56
	v_and_b32_e32 v56, 0xffff0000, v5
	v_fmac_f32_e32 v55, v15, v56
	v_lshlrev_b32_e32 v56, 16, v6
	v_fmac_f32_e32 v52, v16, v56
	v_and_b32_e32 v56, 0xffff0000, v6
	v_fmac_f32_e32 v53, v17, v56
	v_lshlrev_b32_e32 v56, 16, v7
	v_fmac_f32_e32 v54, v18, v56
	v_and_b32_e32 v56, 0xffff0000, v7
	v_fmac_f32_e32 v55, v19, v56
	v_lshlrev_b32_e32 v56, 16, v8
	v_fmac_f32_e32 v52, v20, v56
	v_and_b32_e32 v56, 0xffff0000, v8
	v_fmac_f32_e32 v53, v21, v56
	v_lshlrev_b32_e32 v56, 16, v9
	v_fmac_f32_e32 v54, v22, v56
	v_and_b32_e32 v56, 0xffff0000, v9
	v_fmac_f32_e32 v55, v23, v56
	v_lshlrev_b32_e32 v56, 16, v10
	v_fmac_f32_e32 v52, v24, v56
	v_and_b32_e32 v56, 0xffff0000, v10
	v_fmac_f32_e32 v53, v25, v56
	v_lshlrev_b32_e32 v56, 16, v11
	v_fmac_f32_e32 v54, v26, v56
	v_and_b32_e32 v56, 0xffff0000, v11
	v_fmac_f32_e32 v55, v27, v56
	ds_read_b128 v[4:7], v1 offset:192
	ds_read_b128 v[8:11], v1 offset:208
	ds_read_b128 v[12:15], v3 offset:384
	ds_read_b128 v[16:19], v3 offset:400
	ds_read_b128 v[20:23], v3 offset:416
	ds_read_b128 v[24:27], v3 offset:432
	s_waitcnt lgkmcnt(6)
; __device__ __forceinline__ float bf2f(bf16_t h) { return __uint_as_float(((unsigned)h) << 16); }
; __device__ __forceinline__ int sidx(int dir, int b, int h, int n) { return ((dir * 8 + b) * 4 + h) * 18 + n; }
; __device__ void ml_local_tile(unsigned char* lds, const Params& p, int l, int b, int h, int n) {
;     ...
;   if (tid < 256) {
;     const int e = tid & 127, dir = tid >> 7;
;     const float* wv = vec + (6 + dir) * 128;
;     float s = 0.f;
;     for (int q = 0; q < 128; ++q) s += wv[q] * bf2f(KT[e * 136 + q]);
;     nst[(size_t)sidx(dir, b, h, n) * 128 + e] = s;
;   }
;   __syncthreads();
	v_lshlrev_b32_e32 v56, 16, v28
	v_fmac_f32_e32 v52, v36, v56
	v_and_b32_e32 v56, 0xffff0000, v28
	v_fmac_f32_e32 v53, v37, v56
	v_lshlrev_b32_e32 v56, 16, v29
	v_fmac_f32_e32 v54, v38, v56
	v_and_b32_e32 v56, 0xffff0000, v29
	v_fmac_f32_e32 v55, v39, v56
	v_lshlrev_b32_e32 v56, 16, v30
	v_fmac_f32_e32 v52, v40, v56
	v_and_b32_e32 v56, 0xffff0000, v30
	v_fmac_f32_e32 v53, v41, v56
	v_lshlrev_b32_e32 v56, 16, v31
	v_fmac_f32_e32 v54, v42, v56
	v_and_b32_e32 v56, 0xffff0000, v31
	v_fmac_f32_e32 v55, v43, v56
	v_lshlrev_b32_e32 v56, 16, v32
	v_fmac_f32_e32 v52, v44, v56
	v_and_b32_e32 v56, 0xffff0000, v32
	v_fmac_f32_e32 v53, v45, v56
	v_lshlrev_b32_e32 v56, 16, v33
	v_fmac_f32_e32 v54, v46, v56
	v_and_b32_e32 v56, 0xffff0000, v33
	v_fmac_f32_e32 v55, v47, v56
	v_lshlrev_b32_e32 v56, 16, v34
	v_fmac_f32_e32 v52, v48, v56
	v_and_b32_e32 v56, 0xffff0000, v34
	v_fmac_f32_e32 v53, v49, v56
	v_lshlrev_b32_e32 v56, 16, v35
	v_fmac_f32_e32 v54, v50, v56
	v_and_b32_e32 v56, 0xffff0000, v35
	v_fmac_f32_e32 v55, v51, v56
	ds_read_b128 v[28:31], v1 offset:224
	ds_read_b128 v[32:35], v1 offset:240
	ds_read_b128 v[36:39], v3 offset:448
	ds_read_b128 v[40:43], v3 offset:464
	ds_read_b128 v[44:47], v3 offset:480
	ds_read_b128 v[48:51], v3 offset:496
	s_waitcnt lgkmcnt(6)
	v_lshlrev_b32_e32 v56, 16, v4
	v_fmac_f32_e32 v52, v12, v56
	v_and_b32_e32 v56, 0xffff0000, v4
	v_fmac_f32_e32 v53, v13, v56
	v_lshlrev_b32_e32 v56, 16, v5
	v_fmac_f32_e32 v54, v14, v56
	v_and_b32_e32 v56, 0xffff0000, v5
	v_fmac_f32_e32 v55, v15, v56
	v_lshlrev_b32_e32 v56, 16, v6
	v_fmac_f32_e32 v52, v16, v56
	v_and_b32_e32 v56, 0xffff0000, v6
	v_fmac_f32_e32 v53, v17, v56
	v_lshlrev_b32_e32 v56, 16, v7
	v_fmac_f32_e32 v54, v18, v56
	v_and_b32_e32 v56, 0xffff0000, v7
	v_fmac_f32_e32 v55, v19, v56
	v_lshlrev_b32_e32 v56, 16, v8
	v_fmac_f32_e32 v52, v20, v56
	v_and_b32_e32 v56, 0xffff0000, v8
	v_fmac_f32_e32 v53, v21, v56
	v_lshlrev_b32_e32 v56, 16, v9
	v_fmac_f32_e32 v54, v22, v56
	v_and_b32_e32 v56, 0xffff0000, v9
	v_fmac_f32_e32 v55, v23, v56
	v_lshlrev_b32_e32 v56, 16, v10
	v_fmac_f32_e32 v52, v24, v56
	v_and_b32_e32 v56, 0xffff0000, v10
	v_fmac_f32_e32 v53, v25, v56
	v_lshlrev_b32_e32 v56, 16, v11
	v_fmac_f32_e32 v54, v26, v56
	v_and_b32_e32 v56, 0xffff0000, v11
	v_fmac_f32_e32 v55, v27, v56
	s_waitcnt lgkmcnt(0)
	v_lshlrev_b32_e32 v56, 16, v28
	v_fmac_f32_e32 v52, v36, v56
	v_and_b32_e32 v56, 0xffff0000, v28
	v_fmac_f32_e32 v53, v37, v56
	v_lshlrev_b32_e32 v56, 16, v29
	v_fmac_f32_e32 v54, v38, v56
	v_and_b32_e32 v56, 0xffff0000, v29
	v_fmac_f32_e32 v55, v39, v56
	v_lshlrev_b32_e32 v56, 16, v30
	v_fmac_f32_e32 v52, v40, v56
	v_and_b32_e32 v56, 0xffff0000, v30
	v_fmac_f32_e32 v53, v41, v56
	v_lshlrev_b32_e32 v56, 16, v31
	v_fmac_f32_e32 v54, v42, v56
	v_and_b32_e32 v56, 0xffff0000, v31
	v_fmac_f32_e32 v55, v43, v56
	v_lshlrev_b32_e32 v56, 16, v32
	v_fmac_f32_e32 v52, v44, v56
	v_and_b32_e32 v56, 0xffff0000, v32
	v_fmac_f32_e32 v53, v45, v56
	v_lshlrev_b32_e32 v56, 16, v33
	v_fmac_f32_e32 v54, v46, v56
	v_and_b32_e32 v56, 0xffff0000, v33
	v_fmac_f32_e32 v55, v47, v56
	v_lshlrev_b32_e32 v56, 16, v34
	v_fmac_f32_e32 v52, v48, v56
	v_and_b32_e32 v56, 0xffff0000, v34
	v_fmac_f32_e32 v53, v49, v56
	v_lshlrev_b32_e32 v56, 16, v35
	v_fmac_f32_e32 v54, v50, v56
	v_and_b32_e32 v56, 0xffff0000, v35
	v_fmac_f32_e32 v55, v51, v56
	v_add_f32_e32 v52, v52, v53
	v_add_f32_e32 v54, v54, v55
	v_add_f32_e32 v0, v52, v54
	v_lshl_add_u32 v1, v87, 5, s2
	v_or_b32_e32 v1, s25, v1
	v_mov_b32_e32 v2, s24
	v_mad_u64_u32 v[2:3], s[2:3], v1, 18, v[2:3]
	v_ashrrev_i32_e32 v3, 31, v2
	v_readlane_b32 s2, v251, 58
	v_lshlrev_b64 v[2:3], 9, v[2:3]
	v_readlane_b32 s3, v251, 59
	v_lshlrev_b32_e32 v192, 2, v86
	s_nop 0
	v_lshl_add_u64 v[2:3], s[2:3], 0, v[2:3]
	v_lshl_add_u64 v[2:3], v[2:3], 0, v[192:193]
	global_store_dword v[2:3], v0, off
	s_branch .LBB0_321

; __device__ __forceinline__ float bf2f(bf16_t h) { return __uint_as_float(((unsigned)h) << 16); }
; __device__ void rg_tile(unsigned char* lds, const Params& p, int l, int b, int ck, int hh, bool outmode) {
;     ...
;   const bool isctx = ck < 4;
;   const int L = isctx ? 256 : 2048;
;   const int t0 = isctx ? ck * 64 : (ck - 4) * 64;
;   const int rowbase = isctx ? (NLAT + b * 256) : (b * 2048);
;   float car_pre = 0.f, gp_pre[8];
;   {
;     const int d_ = (tid >> 6) & 1, j_ = tid & 63;
;     if (outmode) {
;       car_pre = car[((size_t)(b * 36 + ck) * 2 + d_) * 256 + hh * 64 + j_];
; #pragma unroll
;       for (int q = 0; q < 8; ++q) gp_pre[q] = bf2f(z[(size_t)(rowbase + t0 + w * 8 + q) * ZS + 2816 + 256 + hh * 64 + lane]);
;     } else {
; #pragma unroll
;       for (int q = 0; q < 8; ++q) gp_pre[q] = 0.f;
;     }
;   }
;   const int chm_ = hh * 64 + (w & 3) * 16 + lr, dm_ = w >> 2;
;   const float br = p.in[22][(size_t)l * 1024 + (dm_ * 2 + 0) * 256 + chm_];
;   const float bi = p.in[22][(size_t)l * 1024 + (dm_ * 2 + 1) * 256 + chm_];
;   const float lam_ = p.in[23][(size_t)l * 512 + dm_ * 256 + chm_];
;   {
;     const int i = tid & 63, tq = tid >> 6;
;     const int ch = hh * 64 + i;
;     const float* wc = p.in[20] + (size_t)l * 4 * 256 + ch;
;     const float w0 = wc[0], w1 = wc[256], w2 = wc[512], w3 = wc[768];
; #pragma unroll
;     for (int ii = 0; ii < 8; ++ii) {
;       const int tt = tq * 8 + ii;
;       const int tp = t0 + tt;
;       const int tm1 = tp - 1 >= 0 ? tp - 1 : 0, tp1 = tp + 1 < L ? tp + 1 : L - 1, tp2 = tp + 2 < L ? tp + 2 : L - 1;
;       const float z0 = bf2f(z[(size_t)(rowbase + tm1) * ZS + 2816 + ch]);
;       const float z1 = bf2f(z[(size_t)(rowbase + tp) * ZS + 2816 + ch]);
;       const float z2 = bf2f(z[(size_t)(rowbase + tp1) * ZS + 2816 + ch]);
;       const float z3 = bf2f(z[(size_t)(rowbase + tp2) * ZS + 2816 + ch]);
.LBB0_708:
	s_and_b64 vcc, exec, s[0:1]
	s_cbranch_vccz .LBB0_812
	s_sub_i32 s0, s13, s30
	s_ashr_i32 s2, s0, 2
	s_abs_i32 s2, s2
	v_readlane_b32 s3, v254, 14
	s_mul_hi_u32 s3, s2, s3
	v_readlane_b32 s4, v254, 11
	s_mul_i32 s3, s3, s4
	s_sub_i32 s2, s2, s3
	s_and_b32 s1, s13, 3
	s_sub_i32 s3, s2, s4
	s_cmp_ge_u32 s2, s4
	s_cselect_b32 s2, s3, s2
	s_sub_i32 s3, s2, s4
	s_cmp_ge_u32 s2, s4
	s_cselect_b32 s2, s3, s2
	s_ashr_i32 s3, s0, 31
	s_xor_b32 s2, s2, s3
	s_sub_i32 s2, s2, s3
	v_readlane_b32 s4, v254, 22
	s_add_i32 s4, s2, s4
	s_abs_i32 s0, s0
	v_readlane_b32 s2, v254, 16
	s_mul_hi_u32 s2, s0, s2
	v_readlane_b32 s7, v254, 15
	s_mul_i32 s5, s2, s7
	s_sub_i32 s0, s0, s5
	s_add_i32 s5, s2, 1
	s_sub_i32 s6, s0, s7
	s_cmp_ge_u32 s0, s7
	s_cselect_b32 s2, s5, s2
	s_cselect_b32 s0, s6, s0
	s_add_i32 s5, s2, 1
	s_cmp_ge_u32 s0, s7
	s_cselect_b32 s0, s5, s2
	s_xor_b32 s0, s0, s3
	s_sub_i32 s5, s0, s3
	s_lshl_b32 s2, s4, 6
	s_lshl_b32 s0, s5, 8
	s_add_i32 s3, s2, 0xffffff00
	s_add_i32 s6, s0, 0x4000
	s_lshl_b32 s7, s5, 11
	s_cmp_lt_i32 s4, 4
	s_movk_i32 s0, 0x800
	s_mul_i32 s5, s5, 36
	s_cselect_b32 s0, 0x100, s0
	s_cselect_b32 s3, s2, s3
	s_cselect_b32 s2, s6, s7
	s_add_i32 s4, s5, s4
	v_mov_b32_e32 v52, v195
	v_readfirstlane_b32 s44, v195
	s_mov_b32 s47, s0
	s_mov_b32 s48, s2
	s_mov_b32 s49, s3
	s_lshl_b32 s50, s1, 7
	s_lshr_b32 s44, s44, 6
	s_lshl_b32 s45, s44, 3
	s_add_i32 s45, s45, s49
	s_add_i32 s46, s47, -1
	s_addk_i32 s50, 0x1600
	v_and_b32_e32 v185, 63, v195
	v_lshl_add_u32 v180, v185, 1, s50
	v_readlane_b32 s52, v254, 3
	v_readlane_b32 s53, v254, 4
	s_lshl_b32 s51, s1, 8
	v_lshl_add_u32 v181, v185, 2, s51
	s_nop 4
	global_load_dword v165, v181, s[52:53]
	global_load_dword v166, v181, s[52:53] offset:1024
	global_load_dword v167, v181, s[52:53] offset:2048
	global_load_dword v168, v181, s[52:53] offset:3072
	s_add_i32 s54, s45, s48
	s_mul_i32 s54, s54, 0x1a00
	s_and_b32 s56, s13, 3
	v_bfe_u32 v208, v195, 4, 2
	v_and_b32_e32 v209, 15, v195
	v_mul_u32_u24_e32 v210, 0x1a00, v208
	v_lshl_add_u32 v210, v209, 3, v210
	s_add_i32 s57, s54, s50
	s_addk_i32 s57, 0x200
	v_add_u32_e32 v210, s57, v210
	v_readlane_b32 s58, v254, 9
	v_readlane_b32 s59, v254, 10
	global_load_dwordx2 v[204:205], v210, s[88:89]
	v_add_u32_e32 v210, 0x6800, v210
	global_load_dwordx2 v[206:207], v210, s[88:89]
	s_lshl_b32 s57, s56, 8
	s_addk_i32 s57, 0xc00
	v_lshl_add_u32 v211, v209, 4, s57
	s_nop 1
	global_load_dwordx4 v[200:203], v211, s[58:59]
	v_add_u32_e32 v181, s54, v180
	s_add_i32 s55, s45, -1
	s_max_i32 s55, s55, 0
	s_add_i32 s55, s55, s48
	s_mul_i32 s55, s55, 0x1a00
	v_add_u32_e32 v184, s55, v180
	global_load_ushort v154, v184, s[88:89]
	global_load_ushort v155, v181, s[88:89]
	v_add_u32_e32 v181, 0x1a00, v181
	global_load_ushort v156, v181, s[88:89]
	v_add_u32_e32 v181, 0x1a00, v181
	global_load_ushort v157, v181, s[88:89]
	v_add_u32_e32 v181, 0x1a00, v181
	global_load_ushort v158, v181, s[88:89]
	v_add_u32_e32 v181, 0x1a00, v181
	global_load_ushort v159, v181, s[88:89]
	v_add_u32_e32 v181, 0x1a00, v181
	global_load_ushort v160, v181, s[88:89]
	v_add_u32_e32 v181, 0x1a00, v181
	global_load_ushort v161, v181, s[88:89]
	v_add_u32_e32 v181, 0x1a00, v181
	global_load_ushort v162, v181, s[88:89]
	s_add_i32 s55, s45, 8
	s_min_i32 s55, s55, s46
	s_add_i32 s55, s55, s48
	s_mul_i32 s55, s55, 0x1a00
	v_add_u32_e32 v184, s55, v180
	global_load_ushort v163, v184, s[88:89]
	s_add_i32 s55, s45, 9
	s_min_i32 s55, s55, s46
	s_add_i32 s55, s55, s48
	s_mul_i32 s55, s55, 0x1a00
	v_add_u32_e32 v184, s55, v180
	global_load_ushort v164, v184, s[88:89]
	s_mul_i32 s55, s44, 0x820
	v_lshl_add_u32 v182, v185, 2, s55
	s_mul_i32 s55, s44, 0x480
	v_lshl_add_u32 v183, v185, 1, s55
	s_ashr_i32 s5, s4, 31
	s_lshl_b32 s7, s1, 6
	v_ashrrev_i32_e32 v47, 6, v52
	s_lshl_b64 s[4:5], s[4:5], 11
	v_readlane_b32 s8, v252, 11
	v_and_b32_e32 v48, 1, v47
	v_readlane_b32 s9, v252, 12
	s_add_u32 s4, s8, s4
	s_addc_u32 s5, s9, s5
	v_lshlrev_b32_e32 v192, 10, v48
	v_and_b32_e32 v29, 63, v52
	v_lshl_add_u64 v[0:1], s[4:5], 0, v[192:193]
	s_lshl_b32 s96, s1, 8
	v_lshl_add_u64 v[0:1], v[0:1], 0, s[96:97]
	v_lshlrev_b32_e32 v192, 2, v29
	s_add_i32 s4, s3, s2
	v_lshlrev_b32_e32 v12, 3, v47
	v_lshl_add_u64 v[2:3], v[0:1], 0, v[192:193]
	v_add_u32_e32 v28, s4, v12
	v_mov_b64_e32 v[0:1], s[88:89]
	s_lshl_b32 s96, s1, 7
	s_movk_i32 s10, 0x1000
	s_nop 0
	s_nop 0
	global_load_dword v51, v[2:3], off
	s_add_i32 s6, s2, -1
	v_or_b32_e32 v7, s7, v29
	v_lshlrev_b32_e32 v32, 1, v7
	v_mov_b32_e32 v33, v193
	v_lshlrev_b32_e32 v39, 2, v7
	s_add_i32 s5, s0, -1
	s_nop 0
	s_nop 0
	s_nop 0
	s_nop 0
	v_and_b32_e32 v6, 15, v52
	s_nop 0
	v_lshlrev_b32_e32 v2, 4, v47
	v_ashrrev_i32_e32 v56, 8, v52
	v_and_or_b32 v55, v2, 48, v6
	v_lshlrev_b32_e32 v2, 9, v56
	v_readlane_b32 s8, v254, 12
	v_lshl_or_b32 v7, v56, 1, 1
	v_or_b32_e32 v4, s7, v55
	v_ashrrev_i32_e32 v3, 31, v2
	v_readlane_b32 s9, v254, 13
	v_lshlrev_b32_e32 v16, 8, v7
	v_lshlrev_b32_e32 v4, 2, v4
	v_lshl_add_u64 v[2:3], v[2:3], 2, s[8:9]
	v_mov_b32_e32 v5, v193
	v_ashrrev_i32_e32 v17, 31, v16
	v_lshl_add_u64 v[2:3], v[2:3], 0, v[4:5]
	v_lshl_add_u64 v[16:17], v[16:17], 2, s[8:9]
	v_lshl_add_u64 v[16:17], v[16:17], 0, v[4:5]
	global_load_dword v54, v[2:3], off
	global_load_dword v53, v[16:17], off
	v_and_b32_e32 v2, 0xffffff00, v52
	v_readlane_b32 s8, v254, 1
	v_ashrrev_i32_e32 v3, 31, v2
	v_readlane_b32 s9, v254, 2
	v_or_b32_e32 v37, 1, v12
	v_add_u32_e32 v30, 0, v192
	v_lshl_add_u64 v[2:3], v[2:3], 2, s[8:9]
	v_lshl_add_u64 v[2:3], v[2:3], 0, v[4:5]
	global_load_dword v16, v[2:3], off
	s_nop 0
	s_nop 0
	v_or_b32_e32 v38, 2, v12
	s_nop 0
	v_or_b32_e32 v40, 3, v12
	s_nop 0
; __device__ __forceinline__ bf16_t f2bf(float f) { return (bf16_t)(pack2(f, 0.f) & 0xffffu); }
; __device__ __forceinline__ float bf2f(bf16_t h) { return __uint_as_float(((unsigned)h) << 16); }
; __device__ void rg_tile(unsigned char* lds, const Params& p, int l, int b, int ck, int hh, bool outmode) {
;     ...
;     const int i = tid & 63, tq = tid >> 6;
;     const int ch = hh * 64 + i;
;     const float* wc = p.in[20] + (size_t)l * 4 * 256 + ch;
;     const float w0 = wc[0], w1 = wc[256], w2 = wc[512], w3 = wc[768];
; #pragma unroll
;     for (int ii = 0; ii < 8; ++ii) {
;       const int tt = tq * 8 + ii;
;       const int tp = t0 + tt;
;       const int tm1 = tp - 1 >= 0 ? tp - 1 : 0, tp1 = tp + 1 < L ? tp + 1 : L - 1, tp2 = tp + 2 < L ? tp + 2 : L - 1;
;       const float z0 = bf2f(z[(size_t)(rowbase + tm1) * ZS + 2816 + ch]);
;       const float z1 = bf2f(z[(size_t)(rowbase + tp) * ZS + 2816 + ch]);
;       const float z2 = bf2f(z[(size_t)(rowbase + tp1) * ZS + 2816 + ch]);
;       const float z3 = bf2f(z[(size_t)(rowbase + tp2) * ZS + 2816 + ch]);
;       float xr = w1 * z1;
;       xr += (tp - 1 >= 0 ? w0 : 0.f) * z0;
;       xr += (tp + 1 < L ? w2 : 0.f) * z2;
;       xr += (tp + 2 < L ? w3 : 0.f) * z3;
;       XR[tt * 65 + i] = xr;
;       XB[tt * 72 + i] = f2bf(xr);
;     }
;     const bf16_t* rgw = (const bf16_t*)(p.ws + OFF_RGW);
; #pragma unroll
;     for (int q = 0; q < 4; ++q) {
;       const int id = tid + 512 * q;
;       const int row = id >> 3, kc = id & 7;
;       *(uint4*)(WT + row * 72 + kc * 8) = *(const uint4*)(rgw + ((size_t)((l * 4 + (row >> 6)) * 4 + hh)) * 4096 + (row & 63) * 64 + kc * 8);
;     }
;   }
	s_nop 0
	s_nop 0
	s_nop 0
	s_nop 0
	s_nop 0
	v_or_b32_e32 v43, 4, v12
	s_nop 0
	s_movk_i32 s12, 0x104
	s_movk_i32 s11, 0x90
	s_nop 0
	v_or_b32_e32 v44, 5, v12
	v_or_b32_e32 v45, 6, v12
	v_add_u32_e32 v68, s3, v45
	s_nop 0
	v_add_u32_e32 v69, 2, v68
	v_min_i32_e32 v26, s5, v69
	v_or_b32_e32 v46, 7, v12
	v_add_u32_e32 v13, s2, v26
	v_add_u32_e32 v70, s3, v46
	v_mad_i64_i32 v[26:27], s[8:9], v13, s92, v[0:1]
	v_max_i32_e32 v12, 1, v70
	v_add_u32_e32 v12, s6, v12
	v_mad_u64_u32 v[12:13], s[6:7], v12, s92, v[0:1]
	v_lshl_add_u64 v[12:13], v[12:13], 0, v[32:33]
	v_add_u32_e32 v58, s2, v70
	v_add_co_u32_e32 v12, vcc, s10, v12
	v_mad_i64_i32 v[58:59], s[6:7], v58, s92, v[0:1]
	s_nop 0
	v_addc_co_u32_e32 v13, vcc, 0, v13, vcc
	v_ashrrev_i32_e32 v80, 3, v52
	s_nop 0
	global_load_ushort v78, v[12:13], off offset:1536
	v_readlane_b32 s2, v254, 5
	v_lshlrev_b32_e32 v12, 4, v52
	v_ashrrev_i32_e32 v33, 7, v52
	s_or_b32 s1, s1, s2
	v_and_b32_e32 v26, 0x70, v12
	v_and_b32_e32 v12, -4, v33
	v_add_u32_e32 v12, s1, v12
	v_ashrrev_i32_e32 v13, 31, v12
	v_readlane_b32 s2, v251, 22
	v_lshlrev_b64 v[12:13], 13, v[12:13]
	v_readlane_b32 s3, v251, 23
	v_lshlrev_b32_e32 v14, 7, v80
	v_and_b32_e32 v14, 0x1f80, v14
	v_lshl_add_u64 v[12:13], s[2:3], 0, v[12:13]
	v_mov_b32_e32 v15, v193
	v_lshl_add_u64 v[12:13], v[12:13], 0, v[14:15]
	v_mov_b32_e32 v27, v193
	v_lshl_add_u64 v[12:13], v[12:13], 0, v[26:27]
	s_nop 0
	global_load_dwordx4 v[12:15], v[12:13], off
	v_add_u32_e32 v0, 0x200, v52
	v_ashrrev_i32_e32 v82, 3, v0
	v_ashrrev_i32_e32 v0, 7, v0
	v_and_b32_e32 v0, -4, v0
	v_add_u32_e32 v0, s1, v0
	v_ashrrev_i32_e32 v1, 31, v0
	v_lshlrev_b64 v[0:1], 13, v[0:1]
	v_lshlrev_b32_e32 v18, 7, v82
	v_lshl_add_u64 v[0:1], s[2:3], 0, v[0:1]
	v_and_b32_e32 v18, 0x1f80, v18
	v_mov_b32_e32 v19, v193
	v_lshl_add_u64 v[0:1], v[0:1], 0, v[18:19]
	v_add_u32_e32 v18, 0x400, v52
	v_ashrrev_i32_e32 v83, 3, v18
	v_ashrrev_i32_e32 v18, 7, v18
	v_and_b32_e32 v18, -4, v18
	v_add_u32_e32 v18, s1, v18
	v_ashrrev_i32_e32 v19, 31, v18
	v_lshlrev_b64 v[18:19], 13, v[18:19]
	v_lshlrev_b32_e32 v20, 7, v83
	v_lshl_add_u64 v[18:19], s[2:3], 0, v[18:19]
	v_and_b32_e32 v20, 0x1f80, v20
	v_mov_b32_e32 v21, v193
	v_lshl_add_u64 v[18:19], v[18:19], 0, v[20:21]
	v_lshl_add_u64 v[0:1], v[0:1], 0, v[26:27]
	v_lshl_add_u64 v[22:23], v[18:19], 0, v[26:27]
	global_load_dwordx4 v[18:21], v[0:1], off
	s_nop 0
	global_load_dwordx4 v[22:25], v[22:23], off
	v_add_u32_e32 v0, 0x600, v52
	v_ashrrev_i32_e32 v84, 3, v0
	v_ashrrev_i32_e32 v0, 7, v0
	v_and_b32_e32 v0, -4, v0
	v_add_u32_e32 v0, s1, v0
	v_ashrrev_i32_e32 v1, 31, v0
	v_lshlrev_b64 v[0:1], 13, v[0:1]
	v_lshlrev_b32_e32 v58, 7, v84
	v_lshl_add_u64 v[0:1], s[2:3], 0, v[0:1]
	v_and_b32_e32 v58, 0x1f80, v58
	v_mov_b32_e32 v59, v193
	v_lshl_add_u64 v[0:1], v[0:1], 0, v[58:59]
	v_lshl_add_u64 v[0:1], v[0:1], 0, v[26:27]
	global_load_dwordx4 v[58:61], v[0:1], off
	s_waitcnt vmcnt(0)
	v_lshlrev_b32_e32 v1, 16, v78
	s_nop 0
	s_nop 0
	v_add_u32_e32 v0, 0, v26
	v_mad_u64_u32 v[2:3], s[0:1], v80, s11, v[0:1]
	ds_write_b128 v2, v[12:15] offset:25856
	v_mad_u64_u32 v[2:3], s[0:1], v82, s11, v[0:1]
	ds_write_b128 v2, v[18:21] offset:25856
	v_mad_u64_u32 v[2:3], s[0:1], v83, s11, v[0:1]
	v_mad_u64_u32 v[0:1], s[0:1], v84, s11, v[0:1]
	ds_write_b128 v2, v[22:25] offset:25856
	ds_write_b128 v0, v[58:61] offset:25856
	v_and_b32_e32 v0, 48, v52
	v_add_u32_e32 v0, 0, v0
	v_mad_u32_u24 v17, v6, s11, v0
	s_waitcnt vmcnt(0)
	v_lshlrev_b32_e32 v154, 16, v154
	v_lshlrev_b32_e32 v155, 16, v155
	v_lshlrev_b32_e32 v156, 16, v156
	v_lshlrev_b32_e32 v157, 16, v157
	v_lshlrev_b32_e32 v158, 16, v158
	v_lshlrev_b32_e32 v159, 16, v159
	v_lshlrev_b32_e32 v160, 16, v160
	v_lshlrev_b32_e32 v161, 16, v161
	v_lshlrev_b32_e32 v162, 16, v162
	v_lshlrev_b32_e32 v163, 16, v163
	v_lshlrev_b32_e32 v164, 16, v164
	s_cmp_ge_i32 s45, 1
	s_cselect_b64 s[56:57], -1, 0
	s_add_i32 s55, s45, 8
	s_cmp_lt_i32 s55, s47
	s_cselect_b64 s[58:59], -1, 0
	v_cndmask_b32_e64 v169, 0, v165, s[56:57]
	v_cndmask_b32_e64 v170, 0, v167, s[58:59]
	v_cndmask_b32_e64 v171, 0, v168, s[58:59]
	v_mul_f32_e32 v172, v166, v155
	v_fmac_f32_e32 v172, v169, v154
	v_fmac_f32_e32 v172, v167, v156
	v_fmac_f32_e32 v172, v168, v157
	v_mul_f32_e32 v173, v166, v156
	v_fmac_f32_e32 v173, v165, v155
	v_fmac_f32_e32 v173, v167, v157
	v_fmac_f32_e32 v173, v168, v158
	v_mul_f32_e32 v174, v166, v157
	v_fmac_f32_e32 v174, v165, v156
	v_fmac_f32_e32 v174, v167, v158
	v_fmac_f32_e32 v174, v168, v159
	v_mul_f32_e32 v175, v166, v158
	v_fmac_f32_e32 v175, v165, v157
	v_fmac_f32_e32 v175, v167, v159
	v_fmac_f32_e32 v175, v168, v160
	v_mul_f32_e32 v176, v166, v159
	v_fmac_f32_e32 v176, v165, v158
	v_fmac_f32_e32 v176, v167, v160
	v_fmac_f32_e32 v176, v168, v161
	v_mul_f32_e32 v177, v166, v160
	v_fmac_f32_e32 v177, v165, v159
	v_fmac_f32_e32 v177, v167, v161
	v_fmac_f32_e32 v177, v168, v162
	v_mul_f32_e32 v178, v166, v161
	v_fmac_f32_e32 v178, v165, v160
	v_fmac_f32_e32 v178, v167, v162
	v_fmac_f32_e32 v178, v171, v163
	v_mul_f32_e32 v179, v166, v162
	v_fmac_f32_e32 v179, v165, v161
	v_fmac_f32_e32 v179, v170, v163
	v_fmac_f32_e32 v179, v171, v164
	v_cvt_pk_bf16_f32 v184, v172, v172
	ds_write_b32 v182, v172
	ds_write_b16 v183, v184 offset:16640
	v_cvt_pk_bf16_f32 v184, v173, v173
	ds_write_b32 v182, v173 offset:260
	ds_write_b16 v183, v184 offset:16784
	v_cvt_pk_bf16_f32 v184, v174, v174
	ds_write_b32 v182, v174 offset:520
	ds_write_b16 v183, v184 offset:16928
	v_cvt_pk_bf16_f32 v184, v175, v175
	ds_write_b32 v182, v175 offset:780
	ds_write_b16 v183, v184 offset:17072
	v_cvt_pk_bf16_f32 v184, v176, v176
	ds_write_b32 v182, v176 offset:1040
	ds_write_b16 v183, v184 offset:17216
	v_cvt_pk_bf16_f32 v184, v177, v177
	ds_write_b32 v182, v177 offset:1300
	ds_write_b16 v183, v184 offset:17360
	v_cvt_pk_bf16_f32 v184, v178, v178
	ds_write_b32 v182, v178 offset:1560
	ds_write_b16 v183, v184 offset:17504
	v_cvt_pk_bf16_f32 v184, v179, v179
	ds_write_b32 v182, v179 offset:1820
	ds_write_b16 v183, v184 offset:17648
	s_waitcnt lgkmcnt(0)
	s_barrier
; __device__ __forceinline__ float fexp(float x) { return __expf(x); }
; __device__ __forceinline__ float sigm(float x) { return frcp(1.f + fexp(-x)); }
; __device__ __forceinline__ float softplusf(float x) { return fmaxf(x, 0.f) + __logf(1.f + fexp(-fabsf(x))); }
; __device__ void rg_tile(unsigned char* lds, const Params& p, int l, int b, int ck, int hh, bool outmode) {
;     ...
;   {
;     const int d = w >> 2, jf = w & 3;
;     f32x4 ar[4], ai[4];
; #pragma unroll
;     for (int i = 0; i < 4; ++i) { ar[i] = (f32x4){0.f, 0.f, 0.f, 0.f}; ai[i] = (f32x4){0.f, 0.f, 0.f, 0.f}; }
; #pragma unroll
;     for (int ks = 0; ks < 2; ++ks) {
;       const bf16x8 wr = ldfrag(WT + ((d * 2 + 0) * 64 + jf * 16 + lr) * 72 + ks * 32 + lg * 8);
;       const bf16x8 wi = ldfrag(WT + ((d * 2 + 1) * 64 + jf * 16 + lr) * 72 + ks * 32 + lg * 8);
; #pragma unroll
;       for (int tf = 0; tf < 4; ++tf) {
;         const bf16x8 xf = ldfrag(XB + (tf * 16 + lr) * 72 + ks * 32 + lg * 8);
;         ar[tf] = mfma16(xf, wr, ar[tf]);
;         ai[tf] = mfma16(xf, wi, ai[tf]);
;       }
;     }
;     const int j = jf * 16 + lr;
;     const int ch = hh * 64 + j;
;     const float sp = softplusf(-lam_);
; #pragma unroll
;     for (int tf = 0; tf < 4; ++tf)
; #pragma unroll
;       for (int jj = 0; jj < 4; ++jj) {
;         const int tt = tf * 16 + lg * 4 + jj;
;         const float r = sigm(ar[tf][jj] + br);
;         const float ig = sigm(ai[tf][jj] + bi);
;         const float la = -8.0f * r * sp;
;         const float a = fexp(la);
;         const float bq = __builtin_amdgcn_sqrtf(fmaxf(1.f - a * a, 0.f)) * ig * XR[tt * 65 + j];
;         AA[(d * 64 + tt) * 64 + j] = a;
;         BQ[(d * 64 + tt) * 64 + j] = bq;
;       }
;   }
	ds_read_b128 v[18:21], v17 offset:16640
	v_lshl_or_b32 v1, v56, 7, v55
	v_mad_u64_u32 v[2:3], s[0:1], v1, s11, v[0:1]
	v_lshl_or_b32 v1, v7, 6, v55
	ds_read_b128 v[12:15], v2 offset:25856
	v_mad_u64_u32 v[0:1], s[0:1], v1, s11, v[0:1]
	ds_read_b128 v[4:7], v2 offset:25920
	ds_read_b128 v[22:25], v17 offset:16704
	ds_read_b128 v[8:11], v0 offset:25856
	ds_read_b128 v[0:3], v0 offset:25920
	s_mov_b32 s0, 0xbfb8aa3b
	v_mul_f32_e64 v26, |v16|, s0
	s_waitcnt lgkmcnt(4)
	v_mfma_f32_16x16x32_bf16 v[58:61], v[18:21], v[12:15], 0
	v_exp_f32_e32 v26, v26
	s_mov_b32 s0, 0x800000
	v_max_f32_e64 v16, -v16, -v16
	s_waitcnt lgkmcnt(1)
	v_mfma_f32_16x16x32_bf16 v[18:21], v[18:21], v[8:11], 0
	v_max_f32_e32 v16, 0, v16
	v_bfe_u32 v82, v52, 4, 2
	ds_read_b128 v[62:65], v17 offset:18944
	ds_read_b128 v[66:69], v17 offset:19008
	s_waitcnt lgkmcnt(2)
	v_mfma_f32_16x16x32_bf16 v[74:77], v[22:25], v[0:3], v[18:21]
	v_lshlrev_b32_e32 v56, 12, v56
	v_and_b32_e32 v52, 0x1fffff80, v52
	s_nop 0
	v_add_f32_e32 v18, 1.0, v26
	v_cmp_gt_f32_e32 vcc, s0, v18
	v_mfma_f32_16x16x32_bf16 v[58:61], v[22:25], v[4:7], v[58:61]
	s_mov_b32 s0, 0x3f317217
	v_cndmask_b32_e64 v19, 0, 32, vcc
	v_ldexp_f32 v18, v18, v19
	v_log_f32_e32 v18, v18
	v_mov_b32_e32 v20, 0x41b17218
	v_cndmask_b32_e32 v20, 0, v20, vcc
	s_nop 1
	v_add_f32_e32 v59, v54, v59
	v_mul_f32_e32 v19, 0x3f317217, v18
	v_fma_f32 v19, v18, s0, -v19
	v_fmac_f32_e32 v19, 0x3377d1cf, v18
	s_mov_b32 s0, 0x7f800000
	v_fmac_f32_e32 v19, 0x3f317217, v18
	v_cmp_lt_f32_e64 s[0:1], |v18|, s0
	ds_read_b128 v[78:81], v17 offset:21248
	ds_read_b128 v[24:27], v17 offset:21312
	v_cndmask_b32_e64 v18, v18, v19, s[0:1]
	v_add_f32_e32 v19, v54, v58
	v_mul_f32_e32 v19, 0xbfb8aa3b, v19
	v_exp_f32_e32 v19, v19
	v_sub_f32_e32 v18, v18, v20
	v_add_f32_e32 v57, v16, v18
	v_add_f32_e32 v18, v53, v74
	v_add_f32_e32 v16, 1.0, v19
	v_rcp_f32_e32 v16, v16
	v_mul_f32_e32 v18, 0xbfb8aa3b, v18
	v_exp_f32_e32 v18, v18
	v_lshl_add_u32 v74, v55, 2, 0
	v_mul_f32_e32 v16, 0xc1000000, v16
	v_mul_f32_e32 v16, v57, v16
	v_mul_f32_e32 v16, 0x3fb8aa3b, v16
	v_exp_f32_e32 v58, v16
	v_add_f32_e32 v16, 1.0, v18
	v_rcp_f32_e32 v83, v16
	s_movk_i32 s0, 0x410
	v_fma_f32 v16, -v58, v58, 1.0
	v_max_f32_e32 v16, 0, v16
	v_sqrt_f32_e32 v84, v16
	v_mad_u32_u24 v16, v82, s0, v74
	ds_read_b32 v85, v16
	ds_read_b128 v[20:23], v17 offset:23552
	ds_read_b128 v[16:19], v17 offset:23616
	v_mul_f32_e32 v59, 0xbfb8aa3b, v59
	v_mul_f32_e32 v83, v83, v84
	v_lshlrev_b32_e32 v84, 8, v82
	v_or3_b32 v84, v84, v56, v55
	v_exp_f32_e32 v59, v59
	v_lshlrev_b32_e32 v84, 2, v84
	s_waitcnt lgkmcnt(2)
	v_mul_f32_e32 v83, v85, v83
	v_add_u32_e32 v85, 0, v84
	v_readlane_b32 s0, v253, 37
	ds_write_b32 v85, v58 offset:62720
	v_mfma_f32_16x16x32_bf16 v[70:73], v[62:65], v[12:15], 0
	v_add_u32_e32 v58, s0, v84
	ds_write_b32 v58, v83
	v_add_f32_e32 v58, 1.0, v59
	v_add_f32_e32 v59, v53, v75
	v_lshl_or_b32 v75, v82, 2, 1
	v_rcp_f32_e32 v58, v58
	v_mad_u32_u24 v74, v75, s12, v74
	v_lshlrev_b32_e32 v75, 6, v75
	v_or3_b32 v55, v75, v56, v55
	v_add_f32_e32 v56, v54, v60
	v_mul_f32_e32 v56, 0xbfb8aa3b, v56
	v_exp_f32_e32 v56, v56
	v_mul_f32_e32 v58, 0xc1000000, v58
	v_mul_f32_e32 v58, v57, v58
	v_mul_f32_e32 v58, 0x3fb8aa3b, v58
	v_mul_f32_e32 v59, 0xbfb8aa3b, v59
	v_exp_f32_e32 v58, v58
	v_add_f32_e32 v56, 1.0, v56
	v_exp_f32_e32 v59, v59
	v_rcp_f32_e32 v56, v56
	v_fma_f32 v82, -v58, v58, 1.0
	v_lshlrev_b32_e32 v55, 2, v55
	v_add_f32_e32 v59, 1.0, v59
	v_max_f32_e32 v82, 0, v82
	v_add_u32_e32 v60, 0, v55
	v_mul_f32_e32 v56, 0xc1000000, v56
	v_rcp_f32_e32 v59, v59
	v_sqrt_f32_e32 v82, v82
	ds_read_b32 v83, v74
	ds_write_b32 v60, v58 offset:62720
	v_add_f32_e32 v58, v53, v76
	v_mul_f32_e32 v56, v57, v56
	v_mul_f32_e32 v58, 0xbfb8aa3b, v58
	v_mul_f32_e32 v56, 0x3fb8aa3b, v56
	v_exp_f32_e32 v58, v58
	v_exp_f32_e32 v56, v56
	v_mul_f32_e32 v59, v59, v82
	s_waitcnt lgkmcnt(1)
	v_mul_f32_e32 v59, v83, v59
	v_add_u32_e32 v55, s0, v55
	ds_write_b32 v55, v59
	v_add_f32_e32 v55, 1.0, v58
	v_fma_f32 v58, -v56, v56, 1.0
	v_max_f32_e32 v58, 0, v58
	v_rcp_f32_e32 v55, v55
	v_sqrt_f32_e32 v58, v58
	ds_read_b32 v59, v74 offset:260
	v_mfma_f32_16x16x32_bf16 v[62:65], v[62:65], v[8:11], 0
	v_cmp_eq_u32_e32 vcc, 0, v48
	v_mul_f32_e32 v55, v55, v58
	v_or_b32_e32 v58, 0x200, v84
	s_waitcnt lgkmcnt(0)
	v_mul_f32_e32 v55, v55, v59
	v_add_f32_e32 v59, v54, v61
	v_mul_f32_e32 v59, 0xbfb8aa3b, v59
	v_exp_f32_e32 v59, v59
	v_add_u32_e32 v60, 0, v58
	ds_write_b32 v60, v56 offset:62720
	v_add_u32_e32 v56, s0, v58
	v_add_f32_e32 v58, 1.0, v59
	v_rcp_f32_e32 v58, v58
	v_add_f32_e32 v59, v53, v77
	v_mul_f32_e32 v59, 0xbfb8aa3b, v59
	v_mfma_f32_16x16x32_bf16 v[70:73], v[66:69], v[4:7], v[70:73]
	v_exp_f32_e32 v59, v59
	v_mul_f32_e32 v58, 0xc1000000, v58
	v_mul_f32_e32 v58, v57, v58
	v_mul_f32_e32 v58, 0x3fb8aa3b, v58
	v_exp_f32_e32 v75, v58
	ds_write_b32 v56, v55
	v_add_f32_e32 v55, 1.0, v59
	v_mfma_f32_16x16x32_bf16 v[58:61], v[66:69], v[0:3], v[62:65]
	v_fma_f32 v56, -v75, v75, 1.0
	v_max_f32_e32 v56, 0, v56
	v_rcp_f32_e32 v55, v55
	v_add_f32_e32 v62, v54, v70
	v_mul_f32_e32 v62, 0xbfb8aa3b, v62
	v_exp_f32_e32 v62, v62
	v_sqrt_f32_e32 v56, v56
	ds_read_b32 v76, v74 offset:520
	v_add_f32_e32 v58, v53, v58
	v_add_f32_e32 v62, 1.0, v62
	v_rcp_f32_e32 v62, v62
	v_mul_f32_e32 v58, 0xbfb8aa3b, v58
	v_exp_f32_e32 v58, v58
	v_mul_f32_e32 v55, v55, v56
	v_mul_f32_e32 v62, 0xc1000000, v62
	v_mul_f32_e32 v62, v57, v62
	v_mul_f32_e32 v62, 0x3fb8aa3b, v62
	v_exp_f32_e32 v66, v62
	v_or_b32_e32 v56, 0x300, v84
	s_waitcnt lgkmcnt(0)
; __device__ __forceinline__ float fexp(float x) { return __expf(x); }
; __device__ __forceinline__ float sigm(float x) { return frcp(1.f + fexp(-x)); }
; __device__ __forceinline__ float softplusf(float x) { return fmaxf(x, 0.f) + __logf(1.f + fexp(-fabsf(x))); }
; __device__ void rg_tile(unsigned char* lds, const Params& p, int l, int b, int ck, int hh, bool outmode) {
;     ...
;     const int j = jf * 16 + lr;
;     const int ch = hh * 64 + j;
;     const float sp = softplusf(-lam_);
; #pragma unroll
;     for (int tf = 0; tf < 4; ++tf)
; #pragma unroll
;       for (int jj = 0; jj < 4; ++jj) {
;         const int tt = tf * 16 + lg * 4 + jj;
;         const float r = sigm(ar[tf][jj] + br);
;         const float ig = sigm(ai[tf][jj] + bi);
;         const float la = -8.0f * r * sp;
;         const float a = fexp(la);
;         const float bq = __builtin_amdgcn_sqrtf(fmaxf(1.f - a * a, 0.f)) * ig * XR[tt * 65 + j];
;         AA[(d * 64 + tt) * 64 + j] = a;
;         BQ[(d * 64 + tt) * 64 + j] = bq;
;       }
	v_mul_f32_e32 v55, v55, v76
	v_add_u32_e32 v63, 0, v56
	v_add_u32_e32 v56, s0, v56
	ds_write_b32 v56, v55
	v_fma_f32 v56, -v66, v66, 1.0
	ds_write_b32 v63, v75 offset:62720
	v_add_f32_e32 v55, 1.0, v58
	v_max_f32_e32 v56, 0, v56
	v_rcp_f32_e32 v55, v55
	v_sqrt_f32_e32 v56, v56
	ds_read_b32 v58, v74 offset:3900
	v_add_f32_e32 v59, v53, v59
	v_mul_f32_e32 v59, 0xbfb8aa3b, v59
	v_mul_f32_e32 v55, v55, v56
	v_exp_f32_e32 v59, v59
	s_waitcnt lgkmcnt(0)
	v_mul_f32_e32 v55, v55, v58
	v_add_f32_e32 v58, v54, v71
	v_mul_f32_e32 v58, 0xbfb8aa3b, v58
	v_exp_f32_e32 v58, v58
	v_or_b32_e32 v56, 0x1000, v84
	v_add_u32_e32 v67, 0, v56
	v_add_u32_e32 v56, s0, v56
	v_add_f32_e32 v58, 1.0, v58
	v_rcp_f32_e32 v58, v58
	ds_write_b32 v56, v55
	ds_write_b32 v67, v66 offset:62720
	v_add_f32_e32 v55, 1.0, v59
	v_mul_f32_e32 v58, 0xc1000000, v58
	v_mul_f32_e32 v58, v57, v58
	v_mul_f32_e32 v58, 0x3fb8aa3b, v58
	v_exp_f32_e32 v58, v58
	v_rcp_f32_e32 v55, v55
	ds_read_b32 v59, v74 offset:4160
	v_mfma_f32_16x16x32_bf16 v[62:65], v[78:81], v[12:15], 0
	v_fma_f32 v56, -v58, v58, 1.0
	v_max_f32_e32 v56, 0, v56
	v_sqrt_f32_e32 v56, v56
	v_mfma_f32_16x16x32_bf16 v[62:65], v[24:27], v[4:7], v[62:65]
	v_mul_f32_e32 v55, v55, v56
	s_waitcnt lgkmcnt(0)
	v_mul_f32_e32 v55, v55, v59
	v_add_f32_e32 v59, v54, v72
	v_mul_f32_e32 v59, 0xbfb8aa3b, v59
	v_exp_f32_e32 v59, v59
	v_or_b32_e32 v56, 0x1100, v84
	v_add_u32_e32 v70, 0, v56
	ds_write_b32 v70, v58 offset:62720
	v_add_f32_e32 v58, 1.0, v59
	v_rcp_f32_e32 v58, v58
	v_add_f32_e32 v59, v53, v60
	v_mul_f32_e32 v59, 0xbfb8aa3b, v59
	v_exp_f32_e32 v59, v59
	v_mul_f32_e32 v58, 0xc1000000, v58
	v_mul_f32_e32 v58, v57, v58
	v_mul_f32_e32 v58, 0x3fb8aa3b, v58
	v_exp_f32_e32 v58, v58
	v_add_u32_e32 v56, s0, v56
	ds_write_b32 v56, v55
	v_add_f32_e32 v55, 1.0, v59
	v_fma_f32 v56, -v58, v58, 1.0
	v_max_f32_e32 v56, 0, v56
	v_rcp_f32_e32 v55, v55
	v_sqrt_f32_e32 v56, v56
	ds_read_b32 v59, v74 offset:4420
	v_mfma_f32_16x16x32_bf16 v[66:69], v[78:81], v[8:11], 0
	v_mul_f32_e32 v55, v55, v56
	v_or_b32_e32 v56, 0x1200, v84
	s_waitcnt lgkmcnt(0)
	v_mul_f32_e32 v55, v55, v59
	v_add_f32_e32 v59, v54, v73
	v_mul_f32_e32 v59, 0xbfb8aa3b, v59
	v_exp_f32_e32 v59, v59
	v_add_u32_e32 v60, 0, v56
	ds_write_b32 v60, v58 offset:62720
	v_add_u32_e32 v56, s0, v56
	v_add_f32_e32 v58, 1.0, v59
	v_rcp_f32_e32 v58, v58
	v_add_f32_e32 v59, v53, v61
	v_mul_f32_e32 v59, 0xbfb8aa3b, v59
	v_exp_f32_e32 v59, v59
	v_mul_f32_e32 v58, 0xc1000000, v58
	v_mul_f32_e32 v58, v57, v58
	v_mul_f32_e32 v58, 0x3fb8aa3b, v58
	v_exp_f32_e32 v58, v58
	ds_write_b32 v56, v55
	v_add_f32_e32 v55, 1.0, v59
	v_rcp_f32_e32 v55, v55
	v_fma_f32 v56, -v58, v58, 1.0
	v_max_f32_e32 v56, 0, v56
	v_sqrt_f32_e32 v56, v56
	ds_read_b32 v59, v74 offset:4680
	v_mfma_f32_16x16x32_bf16 v[24:27], v[24:27], v[0:3], v[66:69]
	v_mul_f32_e32 v55, v55, v56
	v_or_b32_e32 v56, 0x1300, v84
	s_waitcnt lgkmcnt(0)
	v_mul_f32_e32 v55, v55, v59
	v_add_f32_e32 v59, v54, v62
	v_mul_f32_e32 v59, 0xbfb8aa3b, v59
	v_exp_f32_e32 v59, v59
	v_add_u32_e32 v60, 0, v56
	ds_write_b32 v60, v58 offset:62720
	v_add_f32_e32 v24, v53, v24
	v_add_f32_e32 v58, 1.0, v59
	v_rcp_f32_e32 v58, v58
	v_mul_f32_e32 v24, 0xbfb8aa3b, v24
	v_exp_f32_e32 v24, v24
	v_add_u32_e32 v56, s0, v56
	v_mul_f32_e32 v58, 0xc1000000, v58
	v_mul_f32_e32 v58, v57, v58
	v_mul_f32_e32 v58, 0x3fb8aa3b, v58
	v_exp_f32_e32 v58, v58
	ds_write_b32 v56, v55
	v_add_f32_e32 v24, 1.0, v24
	v_rcp_f32_e32 v24, v24
	v_fma_f32 v55, -v58, v58, 1.0
	v_max_f32_e32 v55, 0, v55
	v_sqrt_f32_e32 v55, v55
	ds_read_b32 v56, v74 offset:8060
	v_mfma_f32_16x16x32_bf16 v[12:15], v[20:23], v[12:15], 0
	v_add_f32_e32 v25, v53, v25
	v_mul_f32_e32 v24, v24, v55
	v_mul_f32_e32 v25, 0xbfb8aa3b, v25
	s_waitcnt lgkmcnt(0)
	v_mul_f32_e32 v24, v24, v56
	v_add_f32_e32 v56, v54, v63
	v_mul_f32_e32 v56, 0xbfb8aa3b, v56
	v_exp_f32_e32 v56, v56
	v_mfma_f32_16x16x32_bf16 v[8:11], v[20:23], v[8:11], 0
	v_add_f32_e32 v22, v54, v64
	v_mul_f32_e32 v22, 0xbfb8aa3b, v22
	v_add_f32_e32 v56, 1.0, v56
	v_rcp_f32_e32 v56, v56
	v_exp_f32_e32 v22, v22
	v_exp_f32_e32 v25, v25
	v_or_b32_e32 v55, 0x2000, v84
	v_mul_f32_e32 v56, 0xc1000000, v56
	v_mul_f32_e32 v56, v57, v56
	v_mul_f32_e32 v56, 0x3fb8aa3b, v56
	v_exp_f32_e32 v56, v56
	v_add_f32_e32 v22, 1.0, v22
	v_rcp_f32_e32 v22, v22
	v_mfma_f32_16x16x32_bf16 v[4:7], v[16:19], v[4:7], v[12:15]
	v_add_u32_e32 v59, 0, v55
	v_add_u32_e32 v55, s0, v55
	ds_write_b32 v55, v24
	v_add_f32_e32 v14, v54, v65
	v_mul_f32_e32 v14, 0xbfb8aa3b, v14
	v_add_f32_e32 v24, 1.0, v25
	v_fma_f32 v25, -v56, v56, 1.0
	v_exp_f32_e32 v14, v14
	ds_write_b32 v59, v58 offset:62720
	v_max_f32_e32 v25, 0, v25
	v_or_b32_e32 v21, 0x2100, v84
	v_mul_f32_e32 v22, 0xc1000000, v22
	v_rcp_f32_e32 v24, v24
	v_sqrt_f32_e32 v25, v25
	ds_read_b32 v55, v74 offset:8320
	v_add_u32_e32 v23, 0, v21
	v_mul_f32_e32 v22, v57, v22
	ds_write_b32 v23, v56 offset:62720
	v_add_f32_e32 v23, v53, v26
	v_mul_f32_e32 v22, 0x3fb8aa3b, v22
	v_mul_f32_e32 v23, 0xbfb8aa3b, v23
	v_exp_f32_e32 v22, v22
	v_add_f32_e32 v14, 1.0, v14
	v_exp_f32_e32 v23, v23
	v_rcp_f32_e32 v14, v14
	v_mul_f32_e32 v20, v24, v25
	v_add_f32_e32 v4, v54, v4
	s_waitcnt lgkmcnt(1)
	v_mul_f32_e32 v20, v20, v55
	v_add_u32_e32 v21, s0, v21
	v_mul_f32_e32 v4, 0xbfb8aa3b, v4
	ds_write_b32 v21, v20
	v_fma_f32 v21, -v22, v22, 1.0
	v_exp_f32_e32 v4, v4
	v_add_f32_e32 v20, 1.0, v23
	v_max_f32_e32 v21, 0, v21
	v_or_b32_e32 v13, 0x2200, v84
	v_mul_f32_e32 v14, 0xc1000000, v14
	v_rcp_f32_e32 v20, v20
	v_sqrt_f32_e32 v21, v21
	ds_read_b32 v23, v74 offset:8580
	v_add_u32_e32 v15, 0, v13
	v_mul_f32_e32 v14, v57, v14
	ds_write_b32 v15, v22 offset:62720
	v_add_f32_e32 v15, v53, v27
	v_mul_f32_e32 v14, 0x3fb8aa3b, v14
	v_mul_f32_e32 v15, 0xbfb8aa3b, v15
	v_exp_f32_e32 v14, v14
	v_add_f32_e32 v4, 1.0, v4
	v_exp_f32_e32 v15, v15
	v_rcp_f32_e32 v4, v4
	v_mul_f32_e32 v12, v20, v21
	s_waitcnt lgkmcnt(1)
; __device__ __forceinline__ float fexp(float x) { return __expf(x); }
; __device__ __forceinline__ float sigm(float x) { return frcp(1.f + fexp(-x)); }
; __device__ void rg_tile(unsigned char* lds, const Params& p, int l, int b, int ck, int hh, bool outmode) {
;     ...
;       for (int jj = 0; jj < 4; ++jj) {
;         const int tt = tf * 16 + lg * 4 + jj;
;         const float r = sigm(ar[tf][jj] + br);
;         const float ig = sigm(ai[tf][jj] + bi);
;         const float la = -8.0f * r * sp;
;         const float a = fexp(la);
;         const float bq = __builtin_amdgcn_sqrtf(fmaxf(1.f - a * a, 0.f)) * ig * XR[tt * 65 + j];
;         AA[(d * 64 + tt) * 64 + j] = a;
;         BQ[(d * 64 + tt) * 64 + j] = bq;
;       }
;   }
;   __syncthreads();
;   {
;     float* SEG = XR;
;     const int seg = tid >> 7, d = (tid >> 6) & 1, j = tid & 63;
;     const int ch = hh * 64 + j;
;     const size_t ci = ((size_t)(b * 36 + ck) * 2 + d) * 256 + ch;
;     float H = 0.f, Ap = 1.f;
; #pragma unroll
;     for (int q = 0; q < 16; ++q) {
;       const int pos = seg * 16 + q;
;       const int tt = d == 0 ? pos : 63 - pos;
;       const float a = AA[(d * 64 + tt) * 64 + j];
;       H = a * H + BQ[(d * 64 + tt) * 64 + j];
;       Ap *= a;
;     }
;     SEG[((seg * 2 + d) * 64 + j) * 2 + 0] = Ap;
;     SEG[((seg * 2 + d) * 64 + j) * 2 + 1] = H;
;     __syncthreads();
	v_mul_f32_e32 v12, v12, v23
	v_add_u32_e32 v13, s0, v13
	v_mfma_f32_16x16x32_bf16 v[0:3], v[16:19], v[0:3], v[8:11]
	v_add_f32_e32 v5, v54, v5
	ds_write_b32 v13, v12
	v_fma_f32 v13, -v14, v14, 1.0
	v_mul_f32_e32 v5, 0xbfb8aa3b, v5
	v_add_f32_e32 v12, 1.0, v15
	v_max_f32_e32 v13, 0, v13
	v_mul_f32_e32 v4, 0xc1000000, v4
	v_exp_f32_e32 v5, v5
	v_rcp_f32_e32 v12, v12
	v_sqrt_f32_e32 v13, v13
	ds_read_b32 v15, v74 offset:8840
	v_mul_f32_e32 v4, v57, v4
	v_add_f32_e32 v0, v53, v0
	v_mul_f32_e32 v4, 0x3fb8aa3b, v4
	v_mul_f32_e32 v0, 0xbfb8aa3b, v0
	v_exp_f32_e32 v4, v4
	v_exp_f32_e32 v0, v0
	v_add_f32_e32 v5, 1.0, v5
	v_mul_f32_e32 v8, v12, v13
	v_or_b32_e32 v9, 0x2300, v84
	v_rcp_f32_e32 v5, v5
	s_waitcnt lgkmcnt(0)
	v_mul_f32_e32 v8, v8, v15
	v_add_u32_e32 v10, 0, v9
	v_add_u32_e32 v9, s0, v9
	ds_write_b32 v9, v8
	v_fma_f32 v8, -v4, v4, 1.0
	ds_write_b32 v10, v14 offset:62720
	v_add_f32_e32 v0, 1.0, v0
	v_max_f32_e32 v8, 0, v8
	v_rcp_f32_e32 v0, v0
	v_sqrt_f32_e32 v8, v8
	ds_read_b32 v9, v74 offset:12220
	v_mul_f32_e32 v5, 0xc1000000, v5
	v_add_f32_e32 v1, v53, v1
	v_mul_f32_e32 v5, v57, v5
	v_mul_f32_e32 v1, 0xbfb8aa3b, v1
	v_mul_f32_e32 v5, 0x3fb8aa3b, v5
	v_exp_f32_e32 v1, v1
	v_exp_f32_e32 v5, v5
	v_mul_f32_e32 v0, v0, v8
	v_or_b32_e32 v8, 0x3000, v84
	s_waitcnt lgkmcnt(0)
	v_mul_f32_e32 v0, v0, v9
	v_add_u32_e32 v9, 0, v8
	ds_write_b32 v9, v4 offset:62720
	v_add_u32_e32 v4, s0, v8
	ds_write_b32 v4, v0
	v_add_f32_e32 v0, 1.0, v1
	v_fma_f32 v1, -v5, v5, 1.0
	v_max_f32_e32 v1, 0, v1
	v_rcp_f32_e32 v0, v0
	v_sqrt_f32_e32 v1, v1
	ds_read_b32 v4, v74 offset:12480
	v_add_f32_e32 v2, v53, v2
	v_mul_f32_e32 v2, 0xbfb8aa3b, v2
	v_mul_f32_e32 v0, v0, v1
	v_exp_f32_e32 v2, v2
	s_waitcnt lgkmcnt(0)
	v_mul_f32_e32 v0, v0, v4
	v_add_f32_e32 v4, v54, v6
	v_mul_f32_e32 v4, 0xbfb8aa3b, v4
	v_exp_f32_e32 v4, v4
	v_or_b32_e32 v1, 0x3100, v84
	v_add_u32_e32 v6, 0, v1
	v_add_u32_e32 v1, s0, v1
	v_add_f32_e32 v4, 1.0, v4
	v_rcp_f32_e32 v4, v4
	ds_write_b32 v1, v0
	ds_write_b32 v6, v5 offset:62720
	v_add_f32_e32 v0, 1.0, v2
	v_mul_f32_e32 v4, 0xc1000000, v4
	v_mul_f32_e32 v4, v57, v4
	v_mul_f32_e32 v4, 0x3fb8aa3b, v4
	v_exp_f32_e32 v4, v4
	v_rcp_f32_e32 v0, v0
	ds_read_b32 v2, v74 offset:12740
	v_add_f32_e32 v3, v53, v3
	v_fma_f32 v1, -v4, v4, 1.0
	v_max_f32_e32 v1, 0, v1
	v_sqrt_f32_e32 v1, v1
	v_mul_f32_e32 v3, 0xbfb8aa3b, v3
	v_exp_f32_e32 v3, v3
	v_lshlrev_b32_e32 v20, 4, v33
	v_mul_f32_e32 v0, v0, v1
	s_waitcnt lgkmcnt(0)
	v_mul_f32_e32 v0, v0, v2
	v_add_f32_e32 v2, v54, v7
	v_mul_f32_e32 v2, 0xbfb8aa3b, v2
	v_exp_f32_e32 v2, v2
	v_or_b32_e32 v1, 0x3200, v84
	v_add_u32_e32 v5, 0, v1
	v_add_u32_e32 v1, s0, v1
	v_add_f32_e32 v2, 1.0, v2
	v_rcp_f32_e32 v2, v2
	ds_write_b32 v1, v0
	ds_write_b32 v5, v4 offset:62720
	v_add_f32_e32 v0, 1.0, v3
	v_mul_f32_e32 v2, 0xc1000000, v2
	v_mul_f32_e32 v2, v57, v2
	v_mul_f32_e32 v2, 0x3fb8aa3b, v2
	v_exp_f32_e32 v2, v2
	v_rcp_f32_e32 v0, v0
	ds_read_b32 v3, v74 offset:13000
	v_lshl_or_b32 v57, v48, 12, v29
	v_fma_f32 v1, -v2, v2, 1.0
	v_max_f32_e32 v1, 0, v1
	v_sqrt_f32_e32 v1, v1
	v_or_b32_e32 v8, 11, v20
	v_sub_u32_e32 v9, 63, v8
	v_cndmask_b32_e32 v8, v9, v8, vcc
	v_mul_f32_e32 v0, v0, v1
	v_or_b32_e32 v1, 0x3300, v84
	s_waitcnt lgkmcnt(0)
	v_mul_f32_e32 v0, v0, v3
	v_add_u32_e32 v3, 0, v1
	ds_write_b32 v3, v2 offset:62720
	v_or_b32_e32 v2, 1, v20
	v_sub_u32_e32 v3, 63, v2
	v_cndmask_b32_e32 v2, v3, v2, vcc
	v_lshlrev_b32_e32 v2, 6, v2
	v_add_lshl_u32 v2, v2, v57, 2
	v_add_u32_e32 v16, 0, v2
	v_add_u32_e32 v22, s0, v2
	v_or_b32_e32 v2, 2, v20
	v_sub_u32_e32 v3, 63, v2
	v_cndmask_b32_e32 v2, v3, v2, vcc
	v_lshlrev_b32_e32 v2, 6, v2
	v_add_u32_e32 v1, s0, v1
	v_add_lshl_u32 v2, v2, v57, 2
	ds_write_b32 v1, v0
	v_sub_u32_e32 v0, 63, v20
	v_add_u32_e32 v23, 0, v2
	v_add_u32_e32 v24, s0, v2
	v_or_b32_e32 v2, 3, v20
	v_cndmask_b32_e32 v0, v0, v20, vcc
	v_sub_u32_e32 v3, 63, v2
	v_lshlrev_b32_e32 v0, 6, v0
	v_cndmask_b32_e32 v2, v3, v2, vcc
	v_add_lshl_u32 v1, v0, v57, 2
	v_lshlrev_b32_e32 v2, 6, v2
	v_add_u32_e32 v0, 0, v1
	v_add_lshl_u32 v2, v2, v57, 2
	s_waitcnt lgkmcnt(0)
	s_barrier
	s_and_b32 s0, s44, 1
	s_lshr_b32 s1, s44, 1
	v_and_b32_e32 v190, 63, v195
	v_lshlrev_b32_e32 v189, 3, v195
	s_cmp_eq_u32 s0, 0
	s_cbranch_scc0 .Lrgs_p5_b1
	s_lshl_b32 s2, s1, 12
	s_add_i32 s2, s2, 0xf500
	v_lshl_add_u32 v188, v190, 2, s2
	ds_read_b32 v154, v188 offset:0
	ds_read_b32 v170, v188 offset:32768
	ds_read_b32 v155, v188 offset:256
	ds_read_b32 v171, v188 offset:33024
	ds_read_b32 v156, v188 offset:512
	ds_read_b32 v172, v188 offset:33280
	ds_read_b32 v157, v188 offset:768
	ds_read_b32 v173, v188 offset:33536
	ds_read_b32 v158, v188 offset:1024
	ds_read_b32 v174, v188 offset:33792
	ds_read_b32 v159, v188 offset:1280
	ds_read_b32 v175, v188 offset:34048
	ds_read_b32 v160, v188 offset:1536
	ds_read_b32 v176, v188 offset:34304
	s_waitcnt lgkmcnt(12)
	v_mov_b32_e32 v186, v170
	v_mov_b32_e32 v187, v154
	ds_read_b32 v161, v188 offset:1792
	ds_read_b32 v177, v188 offset:34560
	s_waitcnt lgkmcnt(12)
	v_fma_f32 v186, v155, v186, v171
	v_mul_f32_e32 v187, v187, v155
	ds_read_b32 v162, v188 offset:2048
	ds_read_b32 v178, v188 offset:34816
	s_waitcnt lgkmcnt(12)
	v_fma_f32 v186, v156, v186, v172
	v_mul_f32_e32 v187, v187, v156
	ds_read_b32 v163, v188 offset:2304
	ds_read_b32 v179, v188 offset:35072
	s_waitcnt lgkmcnt(12)
	v_fma_f32 v186, v157, v186, v173
	v_mul_f32_e32 v187, v187, v157
	ds_read_b32 v164, v188 offset:2560
	ds_read_b32 v180, v188 offset:35328
	s_waitcnt lgkmcnt(12)
	v_fma_f32 v186, v158, v186, v174
	v_mul_f32_e32 v187, v187, v158
	ds_read_b32 v165, v188 offset:2816
	ds_read_b32 v181, v188 offset:35584
	s_waitcnt lgkmcnt(12)
	v_fma_f32 v186, v159, v186, v175
	v_mul_f32_e32 v187, v187, v159
	ds_read_b32 v166, v188 offset:3072
	ds_read_b32 v182, v188 offset:35840
	s_waitcnt lgkmcnt(12)
	v_fma_f32 v186, v160, v186, v176
	v_mul_f32_e32 v187, v187, v160
	ds_read_b32 v167, v188 offset:3328
	ds_read_b32 v183, v188 offset:36096
	s_waitcnt lgkmcnt(12)
	v_fma_f32 v186, v161, v186, v177
	v_mul_f32_e32 v187, v187, v161
	ds_read_b32 v168, v188 offset:3584
	ds_read_b32 v184, v188 offset:36352
	s_waitcnt lgkmcnt(12)
	v_fma_f32 v186, v162, v186, v178
	v_mul_f32_e32 v187, v187, v162
	ds_read_b32 v169, v188 offset:3840
	ds_read_b32 v185, v188 offset:36608
	s_waitcnt lgkmcnt(12)
	v_fma_f32 v186, v163, v186, v179
	v_mul_f32_e32 v187, v187, v163
	s_waitcnt lgkmcnt(10)
	v_fma_f32 v186, v164, v186, v180
	v_mul_f32_e32 v187, v187, v164
	s_waitcnt lgkmcnt(8)
	v_fma_f32 v186, v165, v186, v181
	v_mul_f32_e32 v187, v187, v165
	s_waitcnt lgkmcnt(6)
	v_fma_f32 v186, v166, v186, v182
	v_mul_f32_e32 v187, v187, v166
	s_waitcnt lgkmcnt(4)
	v_fma_f32 v186, v167, v186, v183
	v_mul_f32_e32 v187, v187, v167
	s_waitcnt lgkmcnt(2)
	v_fma_f32 v186, v168, v186, v184
	v_mul_f32_e32 v187, v187, v168
	s_waitcnt lgkmcnt(0)
	v_fma_f32 v186, v169, v186, v185
	v_mul_f32_e32 v187, v187, v169
	v_mov_b32_e32 v190, v187
	v_mov_b32_e32 v191, v186
	ds_write_b64 v189, v[190:191]
	s_branch .Lrgs_p5_j1

; __device__ __forceinline__ float lo16(unsigned u) { return __uint_as_float(u << 16); }
; __device__ __forceinline__ float hi16(unsigned u) { return __uint_as_float(u & 0xffff0000u); }
; __device__ __forceinline__ float sigm(float x) { return frcp(1.f + fexp(-x)); }
; __device__ void ml_out_tile(unsigned char* lds, const Params& p, int l, int b, int h, int n) {
;     ...
;   {
;     float ss = 0.f;
; #pragma unroll
;     for (int df = 0; df < 8; ++df)
; #pragma unroll
;       for (int j = 0; j < 4; ++j) ss += hsum[df][j] * hsum[df][j];
;     ss += shfl_idx(ss, lane ^ 16);
;     ss += shfl_idx(ss, lane ^ 32);
;     const float rn = rsqrtf(ss * (1.f / 128.f) + EPSF);
;     const float* gm = p.in[24] + (size_t)l * 1024 + 256 + h * 128;
; #pragma unroll
;     for (int df = 0; df < 8; ++df) {
;       const int d = df * 16 + lg * 4;
;       const float4 gg = *(const float4*)(gm + d);
;       float o0 = hsum[df][0] * rn * gg.x * sigm(lo16(ou[df].x));
;       float o1 = hsum[df][1] * rn * gg.y * sigm(hi16(ou[df].x));
;       float o2 = hsum[df][2] * rn * gg.z * sigm(lo16(ou[df].y));
;       float o3 = hsum[df][3] * rn * gg.w * sigm(hi16(ou[df].y));
;       uint2 u; u.x = pack2(o0, o1); u.y = pack2(o2, o3);
;       *(uint2*)(y + (size_t)orow * 1024 + 256 + h * 128 + d) = u;
;     }
.LBB0_810:
	s_mov_b32 s33, 1
	s_andn2_b64 vcc, exec, s[70:71]
	s_mov_b64 s[72:73], 0
	s_cbranch_vccnz .LBB0_738
	v_readlane_b32 s46, v254, 28
	v_readlane_b32 s44, v254, 9
	v_readlane_b32 s45, v254, 10
	v_lshlrev_b32_e32 v100, 2, v68
	s_lshl_b32 s46, s46, 2
	s_add_u32 s44, s44, s46
	s_addc_u32 s45, s45, 0
	s_nop 0
	global_load_dwordx4 v[126:129], v100, s[44:45] offset:1024
	global_load_dwordx4 v[130:133], v100, s[44:45] offset:1088
	global_load_dwordx4 v[134:137], v100, s[44:45] offset:1152
	global_load_dwordx4 v[138:141], v100, s[44:45] offset:1216
	global_load_dwordx4 v[142:145], v100, s[44:45] offset:1280
	global_load_dwordx4 v[146:149], v100, s[44:45] offset:1344
	global_load_dwordx4 v[150:153], v100, s[44:45] offset:1408
	global_load_dwordx4 v[154:157], v100, s[44:45] offset:1472
	v_pk_mul_f32 v[0:1], v[84:85], v[84:85]
	v_pk_mul_f32 v[2:3], v[82:83], v[82:83]
	v_add_f32_e32 v0, v0, v1
	v_add_f32_e32 v0, v2, v0
	v_pk_mul_f32 v[4:5], v[78:79], v[78:79]
	v_add_f32_e32 v0, v3, v0
	v_add_f32_e32 v0, v0, v4
	v_pk_mul_f32 v[6:7], v[76:77], v[76:77]
	v_add_f32_e32 v0, v5, v0
	v_add_f32_e32 v0, v6, v0
	v_pk_mul_f32 v[8:9], v[72:73], v[72:73]
	v_add_f32_e32 v0, v7, v0
	v_add_f32_e32 v0, v0, v8
	v_pk_mul_f32 v[10:11], v[70:71], v[70:71]
	v_add_f32_e32 v0, v9, v0
	v_add_f32_e32 v0, v10, v0
	v_pk_mul_f32 v[12:13], v[64:65], v[64:65]
	v_add_f32_e32 v0, v11, v0
	v_add_f32_e32 v0, v0, v12
	v_pk_mul_f32 v[14:15], v[62:63], v[62:63]
	v_add_f32_e32 v0, v13, v0
	v_add_f32_e32 v0, v14, v0
	s_waitcnt vmcnt(0)
	v_pk_mul_f32 v[16:17], v[58:59], v[58:59]
	v_add_f32_e32 v0, v15, v0
	v_add_f32_e32 v0, v0, v16
	v_pk_mul_f32 v[18:19], v[56:57], v[56:57]
	v_add_f32_e32 v0, v17, v0
	v_add_f32_e32 v0, v18, v0
	v_pk_mul_f32 v[20:21], v[52:53], v[52:53]
	v_add_f32_e32 v0, v19, v0
	v_add_f32_e32 v0, v0, v20
	v_pk_mul_f32 v[22:23], v[50:51], v[50:51]
	v_add_f32_e32 v0, v21, v0
	v_add_f32_e32 v0, v22, v0
	v_pk_mul_f32 v[24:25], v[46:47], v[46:47]
	v_add_f32_e32 v0, v23, v0
	v_add_f32_e32 v0, v0, v24
	v_pk_mul_f32 v[26:27], v[44:45], v[44:45]
	v_add_f32_e32 v0, v25, v0
	v_add_f32_e32 v0, v26, v0
	v_pk_mul_f32 v[28:29], v[42:43], v[42:43]
	v_add_f32_e32 v0, v27, v0
	v_add_f32_e32 v0, v0, v28
	v_pk_mul_f32 v[30:31], v[40:41], v[40:41]
	v_add_f32_e32 v0, v29, v0
	v_add_f32_e32 v0, v30, v0
	v_add_f32_e32 v0, v31, v0
	ds_bpermute_b32 v1, v69, v0
	s_mov_b32 s0, 0x800000
	v_readlane_b32 s96, v254, 28
	v_readlane_b32 s2, v254, 9
	v_readlane_b32 s3, v254, 10
	s_waitcnt lgkmcnt(0)
	v_add_f32_e32 v0, v0, v1
	ds_bpermute_b32 v1, v108, v0
	v_readlane_b32 s84, v253, 41
	v_readlane_b32 s97, v254, 29
	v_readlane_b32 s88, v253, 45
	v_readlane_b32 s89, v253, 46
	s_waitcnt lgkmcnt(0)
	v_add_f32_e32 v0, v0, v1
	v_fmamk_f32 v0, v0, 0x3c000000, v194
	v_cmp_gt_f32_e32 vcc, s0, v0
	v_mul_f32_e32 v1, 0x4b800000, v0
	s_lshl_b32 s0, s96, 2
	v_cndmask_b32_e32 v0, v0, v1, vcc
	v_rsq_f32_e32 v0, v0
	s_add_u32 s0, s2, s0
	s_addc_u32 s1, s3, 0
	v_readlane_b32 s2, v254, 30
	v_mul_f32_e32 v1, 0x45800000, v0
	v_cndmask_b32_e32 v4, v0, v1, vcc
	v_lshlrev_b64 v[0:1], 11, v[198:199]
	v_readlane_b32 s3, v254, 31
	v_lshl_add_u64 v[0:1], s[88:89], 0, v[0:1]
	s_mov_b32 s3, s97
	v_lshl_add_u64 v[6:7], v[0:1], 0, s[2:3]
	v_lshlrev_b32_e32 v0, 16, v88
	v_mul_f32_e32 v0, 0xbfb8aa3b, v0
	v_exp_f32_e32 v0, v0
	v_lshlrev_b32_e32 v5, 2, v68
	v_pk_mul_f32 v[10:11], v[84:85], v[4:5] op_sel_hi:[1,0]
	v_lshlrev_b32_e32 v192, 1, v68
	v_add_f32_e32 v0, 1.0, v0
	v_rcp_f32_e32 v8, v0
	v_and_b32_e32 v0, 0xffff0000, v88
	v_mul_f32_e32 v0, 0xbfb8aa3b, v0
	v_exp_f32_e32 v0, v0
	s_mov_b64 s[2:3], 0x8000200
	v_readlane_b32 s91, v253, 48
	v_readlane_b32 s82, v253, 49
	v_add_f32_e32 v0, 1.0, v0
	v_rcp_f32_e32 v9, v0
	v_mov_b64_e32 v[0:1], v[126:127]
	v_mov_b64_e32 v[2:3], v[128:129]
	v_readlane_b32 s85, v253, 42
	v_readlane_b32 s86, v253, 43
	v_readlane_b32 s87, v253, 44
	v_readlane_b32 s90, v253, 47
	v_readlane_b32 s83, v253, 50
	s_movk_i32 s91, 0x80
	s_movk_i32 s92, 0x1a00
	s_movk_i32 s93, 0x110
	v_readlane_b32 s94, v253, 52
	v_readlane_b32 s29, v254, 24
	v_readlane_b32 s30, v254, 18
	v_readlane_b32 s14, v254, 19
	v_readlane_b32 s13, v254, 25
	v_readlane_b32 s15, v254, 20
	v_pk_mul_f32 v[0:1], v[0:1], v[10:11]
	s_nop 0
	v_pk_mul_f32 v[0:1], v[8:9], v[0:1]
	v_lshlrev_b32_e32 v8, 16, v89
	v_and_b32_e32 v9, 0xffff0000, v89
	v_mul_f32_e32 v8, 0xbfb8aa3b, v8
	v_mul_f32_e32 v9, 0xbfb8aa3b, v9
	v_exp_f32_e32 v8, v8
	v_exp_f32_e32 v9, v9
	v_pk_mul_f32 v[10:11], v[82:83], v[4:5] op_sel_hi:[1,0]
	v_add_f32_e32 v8, 1.0, v8
	v_add_f32_e32 v9, 1.0, v9
	v_rcp_f32_e32 v8, v8
	v_rcp_f32_e32 v9, v9
	v_pk_mul_f32 v[2:3], v[2:3], v[10:11]
	v_pk_mul_f32 v[10:11], v[78:79], v[4:5] op_sel_hi:[1,0]
	v_pk_mul_f32 v[2:3], v[8:9], v[2:3]
	s_nop 0
	v_cvt_pk_bf16_f32 v9, v2, v3
	v_lshl_add_u64 v[2:3], v[6:7], 0, v[192:193]
	v_cvt_pk_bf16_f32 v8, v0, v1
	v_lshl_add_u64 v[0:1], v[2:3], 0, s[2:3]
	s_brev_b32 s2, 16
	v_add_co_u32_e32 v2, vcc, s2, v2
	s_nop 1
	v_addc_co_u32_e32 v3, vcc, 0, v3, vcc
	global_store_dwordx2 v[2:3], v[8:9], off offset:512
	v_mov_b64_e32 v[6:7], v[130:131]
	v_mov_b64_e32 v[8:9], v[132:133]
	v_lshlrev_b32_e32 v2, 16, v86
	v_and_b32_e32 v3, 0xffff0000, v86
	v_mul_f32_e32 v2, 0xbfb8aa3b, v2
	v_mul_f32_e32 v3, 0xbfb8aa3b, v3
	v_exp_f32_e32 v2, v2
	v_exp_f32_e32 v3, v3
	v_add_f32_e32 v2, 1.0, v2
	v_add_f32_e32 v3, 1.0, v3
	v_rcp_f32_e32 v2, v2
	v_rcp_f32_e32 v3, v3
	v_pk_mul_f32 v[6:7], v[6:7], v[10:11]
	s_nop 0
	v_pk_mul_f32 v[2:3], v[2:3], v[6:7]
	v_lshlrev_b32_e32 v6, 16, v87
	v_and_b32_e32 v7, 0xffff0000, v87
	v_mul_f32_e32 v6, 0xbfb8aa3b, v6
	v_mul_f32_e32 v7, 0xbfb8aa3b, v7
	v_exp_f32_e32 v6, v6
	v_exp_f32_e32 v7, v7
; __device__ __forceinline__ float lo16(unsigned u) { return __uint_as_float(u << 16); }
; __device__ __forceinline__ float hi16(unsigned u) { return __uint_as_float(u & 0xffff0000u); }
; __device__ __forceinline__ float sigm(float x) { return frcp(1.f + fexp(-x)); }
; __device__ void ml_out_tile(unsigned char* lds, const Params& p, int l, int b, int h, int n) {
;     ...
;     for (int df = 0; df < 8; ++df) {
;       const int d = df * 16 + lg * 4;
;       const float4 gg = *(const float4*)(gm + d);
;       float o0 = hsum[df][0] * rn * gg.x * sigm(lo16(ou[df].x));
;       float o1 = hsum[df][1] * rn * gg.y * sigm(hi16(ou[df].x));
;       float o2 = hsum[df][2] * rn * gg.z * sigm(lo16(ou[df].y));
;       float o3 = hsum[df][3] * rn * gg.w * sigm(hi16(ou[df].y));
;       uint2 u; u.x = pack2(o0, o1); u.y = pack2(o2, o3);
;       *(uint2*)(y + (size_t)orow * 1024 + 256 + h * 128 + d) = u;
;     }
;   }
;   __syncthreads();
	v_pk_mul_f32 v[10:11], v[76:77], v[4:5] op_sel_hi:[1,0]
	v_cvt_pk_bf16_f32 v2, v2, v3
	v_add_f32_e32 v6, 1.0, v6
	v_add_f32_e32 v7, 1.0, v7
	v_rcp_f32_e32 v6, v6
	v_rcp_f32_e32 v7, v7
	v_pk_mul_f32 v[8:9], v[8:9], v[10:11]
	v_pk_mul_f32 v[10:11], v[72:73], v[4:5] op_sel_hi:[1,0]
	v_pk_mul_f32 v[6:7], v[6:7], v[8:9]
	s_nop 0
	v_cvt_pk_bf16_f32 v3, v6, v7
	global_store_dwordx2 v[0:1], v[2:3], off offset:32
	v_mov_b64_e32 v[6:7], v[134:135]
	v_mov_b64_e32 v[8:9], v[136:137]
	v_lshlrev_b32_e32 v2, 16, v80
	v_and_b32_e32 v3, 0xffff0000, v80
	v_mul_f32_e32 v2, 0xbfb8aa3b, v2
	v_mul_f32_e32 v3, 0xbfb8aa3b, v3
	v_exp_f32_e32 v2, v2
	v_exp_f32_e32 v3, v3
	v_add_f32_e32 v2, 1.0, v2
	v_add_f32_e32 v3, 1.0, v3
	v_rcp_f32_e32 v2, v2
	v_rcp_f32_e32 v3, v3
	v_pk_mul_f32 v[6:7], v[10:11], v[6:7]
	s_nop 0
	v_pk_mul_f32 v[2:3], v[2:3], v[6:7]
	v_lshlrev_b32_e32 v6, 16, v81
	v_and_b32_e32 v7, 0xffff0000, v81
	v_mul_f32_e32 v6, 0xbfb8aa3b, v6
	v_mul_f32_e32 v7, 0xbfb8aa3b, v7
	v_exp_f32_e32 v6, v6
	v_exp_f32_e32 v7, v7
	v_pk_mul_f32 v[10:11], v[70:71], v[4:5] op_sel_hi:[1,0]
	v_cvt_pk_bf16_f32 v2, v2, v3
	v_add_f32_e32 v6, 1.0, v6
	v_add_f32_e32 v7, 1.0, v7
	v_rcp_f32_e32 v6, v6
	v_rcp_f32_e32 v7, v7
	v_pk_mul_f32 v[8:9], v[10:11], v[8:9]
	v_pk_mul_f32 v[10:11], v[64:65], v[4:5] op_sel_hi:[1,0]
	v_pk_mul_f32 v[6:7], v[6:7], v[8:9]
	s_nop 0
	v_cvt_pk_bf16_f32 v3, v6, v7
	global_store_dwordx2 v[0:1], v[2:3], off offset:64
	v_mov_b64_e32 v[6:7], v[138:139]
	v_mov_b64_e32 v[8:9], v[140:141]
	v_lshlrev_b32_e32 v2, 16, v74
	v_and_b32_e32 v3, 0xffff0000, v74
	v_mul_f32_e32 v2, 0xbfb8aa3b, v2
	v_mul_f32_e32 v3, 0xbfb8aa3b, v3
	v_exp_f32_e32 v2, v2
	v_exp_f32_e32 v3, v3
	v_add_f32_e32 v2, 1.0, v2
	v_add_f32_e32 v3, 1.0, v3
	v_rcp_f32_e32 v2, v2
	v_rcp_f32_e32 v3, v3
	v_pk_mul_f32 v[6:7], v[10:11], v[6:7]
	s_nop 0
	v_pk_mul_f32 v[2:3], v[2:3], v[6:7]
	v_lshlrev_b32_e32 v6, 16, v75
	v_and_b32_e32 v7, 0xffff0000, v75
	v_mul_f32_e32 v6, 0xbfb8aa3b, v6
	v_mul_f32_e32 v7, 0xbfb8aa3b, v7
	v_exp_f32_e32 v6, v6
	v_exp_f32_e32 v7, v7
	v_pk_mul_f32 v[10:11], v[62:63], v[4:5] op_sel_hi:[1,0]
	v_cvt_pk_bf16_f32 v2, v2, v3
	v_add_f32_e32 v6, 1.0, v6
	v_add_f32_e32 v7, 1.0, v7
	v_rcp_f32_e32 v6, v6
	v_rcp_f32_e32 v7, v7
	v_pk_mul_f32 v[8:9], v[10:11], v[8:9]
	v_pk_mul_f32 v[10:11], v[58:59], v[4:5] op_sel_hi:[1,0]
	v_pk_mul_f32 v[6:7], v[6:7], v[8:9]
	s_nop 0
	v_cvt_pk_bf16_f32 v3, v6, v7
	global_store_dwordx2 v[0:1], v[2:3], off offset:96
	v_mov_b64_e32 v[6:7], v[142:143]
	v_mov_b64_e32 v[8:9], v[144:145]
	v_lshlrev_b32_e32 v2, 16, v66
	v_and_b32_e32 v3, 0xffff0000, v66
	v_mul_f32_e32 v2, 0xbfb8aa3b, v2
	v_mul_f32_e32 v3, 0xbfb8aa3b, v3
	v_exp_f32_e32 v2, v2
	v_exp_f32_e32 v3, v3
	v_add_f32_e32 v2, 1.0, v2
	v_add_f32_e32 v3, 1.0, v3
	v_rcp_f32_e32 v2, v2
	v_rcp_f32_e32 v3, v3
	v_pk_mul_f32 v[6:7], v[10:11], v[6:7]
	s_nop 0
	v_pk_mul_f32 v[2:3], v[2:3], v[6:7]
	v_lshlrev_b32_e32 v6, 16, v67
	v_and_b32_e32 v7, 0xffff0000, v67
	v_mul_f32_e32 v6, 0xbfb8aa3b, v6
	v_mul_f32_e32 v7, 0xbfb8aa3b, v7
	v_exp_f32_e32 v6, v6
	v_exp_f32_e32 v7, v7
	v_pk_mul_f32 v[10:11], v[56:57], v[4:5] op_sel_hi:[1,0]
	v_cvt_pk_bf16_f32 v2, v2, v3
	v_add_f32_e32 v6, 1.0, v6
	v_add_f32_e32 v7, 1.0, v7
	v_rcp_f32_e32 v6, v6
	v_rcp_f32_e32 v7, v7
	v_pk_mul_f32 v[8:9], v[10:11], v[8:9]
	v_pk_mul_f32 v[10:11], v[52:53], v[4:5] op_sel_hi:[1,0]
	v_pk_mul_f32 v[6:7], v[6:7], v[8:9]
	s_nop 0
	v_cvt_pk_bf16_f32 v3, v6, v7
	global_store_dwordx2 v[0:1], v[2:3], off offset:128
	v_mov_b64_e32 v[6:7], v[146:147]
	v_mov_b64_e32 v[8:9], v[148:149]
	v_lshlrev_b32_e32 v2, 16, v60
	v_and_b32_e32 v3, 0xffff0000, v60
	v_mul_f32_e32 v2, 0xbfb8aa3b, v2
	v_mul_f32_e32 v3, 0xbfb8aa3b, v3
	v_exp_f32_e32 v2, v2
	v_exp_f32_e32 v3, v3
	v_add_f32_e32 v2, 1.0, v2
	v_add_f32_e32 v3, 1.0, v3
	v_rcp_f32_e32 v2, v2
	v_rcp_f32_e32 v3, v3
	v_pk_mul_f32 v[6:7], v[10:11], v[6:7]
	s_nop 0
	v_pk_mul_f32 v[2:3], v[2:3], v[6:7]
	v_lshlrev_b32_e32 v6, 16, v61
	v_and_b32_e32 v7, 0xffff0000, v61
	v_mul_f32_e32 v6, 0xbfb8aa3b, v6
	v_mul_f32_e32 v7, 0xbfb8aa3b, v7
	v_exp_f32_e32 v6, v6
	v_exp_f32_e32 v7, v7
	v_pk_mul_f32 v[10:11], v[50:51], v[4:5] op_sel_hi:[1,0]
	v_cvt_pk_bf16_f32 v2, v2, v3
	v_add_f32_e32 v6, 1.0, v6
	v_add_f32_e32 v7, 1.0, v7
	v_rcp_f32_e32 v6, v6
	v_rcp_f32_e32 v7, v7
	v_pk_mul_f32 v[8:9], v[10:11], v[8:9]
	v_pk_mul_f32 v[10:11], v[46:47], v[4:5] op_sel_hi:[1,0]
	v_pk_mul_f32 v[6:7], v[6:7], v[8:9]
	s_nop 0
	v_cvt_pk_bf16_f32 v3, v6, v7
	global_store_dwordx2 v[0:1], v[2:3], off offset:160
	v_mov_b64_e32 v[6:7], v[150:151]
	v_mov_b64_e32 v[8:9], v[152:153]
	v_lshlrev_b32_e32 v2, 16, v54
	v_and_b32_e32 v3, 0xffff0000, v54
	v_mul_f32_e32 v2, 0xbfb8aa3b, v2
	v_mul_f32_e32 v3, 0xbfb8aa3b, v3
	v_exp_f32_e32 v2, v2
	v_exp_f32_e32 v3, v3
	v_add_f32_e32 v2, 1.0, v2
	v_add_f32_e32 v3, 1.0, v3
	v_rcp_f32_e32 v2, v2
	v_rcp_f32_e32 v3, v3
	v_pk_mul_f32 v[6:7], v[10:11], v[6:7]
	s_nop 0
	v_pk_mul_f32 v[2:3], v[2:3], v[6:7]
	v_lshlrev_b32_e32 v6, 16, v55
	v_and_b32_e32 v7, 0xffff0000, v55
	v_mul_f32_e32 v6, 0xbfb8aa3b, v6
	v_mul_f32_e32 v7, 0xbfb8aa3b, v7
	v_exp_f32_e32 v6, v6
	v_exp_f32_e32 v7, v7
	v_pk_mul_f32 v[10:11], v[44:45], v[4:5] op_sel_hi:[1,0]
	v_cvt_pk_bf16_f32 v2, v2, v3
	v_add_f32_e32 v6, 1.0, v6
	v_add_f32_e32 v7, 1.0, v7
	v_rcp_f32_e32 v6, v6
	v_rcp_f32_e32 v7, v7
	v_pk_mul_f32 v[8:9], v[10:11], v[8:9]
	v_pk_mul_f32 v[10:11], v[42:43], v[4:5] op_sel_hi:[1,0]
	v_pk_mul_f32 v[6:7], v[6:7], v[8:9]
	s_nop 0
	v_cvt_pk_bf16_f32 v3, v6, v7
	global_store_dwordx2 v[0:1], v[2:3], off offset:192
	v_mov_b64_e32 v[6:7], v[154:155]
	v_mov_b64_e32 v[8:9], v[156:157]
	v_lshlrev_b32_e32 v2, 16, v48
	v_and_b32_e32 v3, 0xffff0000, v48
	v_mul_f32_e32 v2, 0xbfb8aa3b, v2
	v_mul_f32_e32 v3, 0xbfb8aa3b, v3
	v_exp_f32_e32 v2, v2
	v_exp_f32_e32 v3, v3
	v_lshlrev_b32_e32 v5, 16, v49
	v_mul_f32_e32 v5, 0xbfb8aa3b, v5
	v_add_f32_e32 v2, 1.0, v2
	v_add_f32_e32 v3, 1.0, v3
	v_exp_f32_e32 v5, v5
	v_rcp_f32_e32 v2, v2
	v_rcp_f32_e32 v3, v3
	v_add_f32_e32 v5, 1.0, v5
	v_pk_mul_f32 v[6:7], v[10:11], v[6:7]
	s_nop 0
	v_pk_mul_f32 v[2:3], v[2:3], v[6:7]
	v_rcp_f32_e32 v6, v5
	v_and_b32_e32 v5, 0xffff0000, v49
	v_mul_f32_e32 v5, 0xbfb8aa3b, v5
	v_exp_f32_e32 v5, v5
	v_cvt_pk_bf16_f32 v2, v2, v3
	v_add_f32_e32 v5, 1.0, v5
	v_rcp_f32_e32 v7, v5
	v_pk_mul_f32 v[4:5], v[40:41], v[4:5] op_sel_hi:[1,0]
	s_nop 0
	v_pk_mul_f32 v[4:5], v[4:5], v[8:9]
	s_nop 0
	v_pk_mul_f32 v[4:5], v[6:7], v[4:5]
	s_nop 0
	v_cvt_pk_bf16_f32 v3, v4, v5
	global_store_dwordx2 v[0:1], v[2:3], off offset:224
	s_barrier
	s_branch .LBB0_638
